# trimmed 246 s_nop and 216 dead lgkmcnt waits around the DPP cumsum in the HGRN input-GEMM epilogue (bit-identical)
# speedup vs baseline: 1.0013x; 1.0013x over previous
; #define PG8_STAGE(bufoff, gbase, voff) do { _Pragma("unroll") for (int _i = 0; _i < 2; ++_i) \
;         __builtin_amdgcn_global_load_lds((const unsigned*)((const char*)(gbase) + (voff)[_i]), (PG8_LAS unsigned*)(lds + (bufoff) + ldsw + _i * 8192), 16, 0, 0); } while (0)
; #define PG8_LDA(dst, b, h) do { _Pragma("unroll") for (int m = 0; m < 4; ++m) _Pragma("unroll") for (int k = 0; k < 2; ++k) dst[m][k] = *(const PG8_LAS bf16x8*)(lds + PG8_SA(b, h) + aoff + m * 2048 + k * 1024); } while (0)
; #define PG8_LDB(dst, b, h) do { _Pragma("unroll") for (int n = 0; n < 2; ++n) _Pragma("unroll") for (int k = 0; k < 2; ++k) dst[n][k] = *(const PG8_LAS bf16x8*)(lds + PG8_SB(b, h) + boff + n * 2048 + k * 1024); } while (0)
; #define PG8_MMA(ai, bj, At, Bt) do { __builtin_amdgcn_s_setprio(1); _Pragma("unroll") for (int m = 0; m < 4; ++m) _Pragma("unroll") for (int n = 0; n < 2; ++n) _Pragma("unroll") for (int k = 0; k < 2; ++k) \
;         acc[ai][bj][m][n] = __builtin_amdgcn_mfma_f32_16x16x32_bf16(Bt[n][k], At[m][k], acc[ai][bj][m][n], 0, 0, 0); __builtin_amdgcn_s_setprio(0); } while (0)
; #define PG8_WAIT_V(n) asm volatile("s_waitcnt vmcnt(" #n ")" ::: "memory")
; #define PG8_BAR __builtin_amdgcn_s_barrier()
; template <class Epi, class Sched, bool ALIGN_EPI = false, bool SP2 = false>
; __device__ __forceinline__ void gemm_phase(PG8_LAS unsigned char* lds, const Gemm g, const Sched& S, const Epi& E) {
;     ...
;         for (int t = 0; t < nt; t += 2) {
;             const bool last = (t == nt - 2);
;             const char* a1 = cA + (size_t)(t + 1) * kstep;
;             const char* a2 = last ? nA : cA + (size_t)(t + 2) * kstep; const char* b2 = last ? nB : cB + (size_t)(t + 2) * kstep;
;             const char* a3 = a2 + kstep; const char* b3 = b2 + kstep;
;             if (last && has_next) S.a_ready(nxt);
;             if constexpr (SP2) {
;             PG8_LDB(B0, 0, 0); PG8_LDB(B1, 0, 1); PG8_SCHED; PG8_LDA(At, 0, 0); PG8_STAGE(PG8_SA(1, 1), a1 + hstep, voffA);
;             PG8_WAIT_V(8); PG8_WAIT_L(0); PG8_BAR; PG8_MMA(0, 0, At, B0); PG8_MMA(0, 1, At, B1); PG8_BAR; PG8_SCHED;
;             PG8_LDA(At, 0, 1); PG8_STAGE(PG8_SB(0, 0), b2, voffB); PG8_STAGE(PG8_SB(0, 1), b2 + hstep, voffB); PG8_STAGE(PG8_SA(0, 0), a2, voffA);
;             PG8_WAIT_V(8); PG8_WAIT_L(0); PG8_BAR; PG8_MMA(1, 0, At, B0); PG8_MMA(1, 1, At, B1); PG8_BAR; PG8_SCHED;
.LBB0_1940:
	ds_read_b128 v[128:131], v163
	ds_read_b128 v[132:135], v163 offset:1024
	ds_read_b128 v[136:139], v163 offset:2048
	ds_read_b128 v[140:143], v163 offset:3072
	ds_read_b128 v[172:175], v193
	ds_read_b128 v[176:179], v193 offset:1024
	ds_read_b128 v[180:183], v193 offset:2048
	ds_read_b128 v[184:187], v193 offset:3072
	s_add_i32 s89, s86, 2
	s_add_u32 s90, s14, 0x80
	s_addc_u32 s87, s15, 0
	s_cmp_eq_u32 s37, s86
	s_cselect_b32 s86, s80, s90
	s_cselect_b32 s87, s81, s87
	s_cselect_b32 s91, s83, s85
	s_cselect_b32 s90, s82, s67
	v_lshl_add_u64 v[220:221], s[14:15], 0, v[166:167]
	s_add_i32 m0, s70, 0xc000
	ds_read_b128 v[188:191], v195
	ds_read_b128 v[196:199], v195 offset:1024
	ds_read_b128 v[200:203], v195 offset:2048
	ds_read_b128 v[204:207], v195 offset:3072
	ds_read_b128 v[208:211], v195 offset:4096
	ds_read_b128 v[212:215], v195 offset:5120
	ds_read_b128 v[216:219], v195 offset:6144
	ds_read_b128 v[224:227], v195 offset:7168
	global_load_lds_dwordx4 v[220:221], off
	v_lshl_add_u64 v[220:221], s[14:15], 0, v[168:169]
	s_add_i32 m0, s70, 0xe000
	s_nop 0
	global_load_lds_dwordx4 v[220:221], off
	s_waitcnt vmcnt(8)
	s_waitcnt lgkmcnt(0)
	s_barrier
	s_setprio 1
	v_mfma_f32_16x16x32_bf16 v[124:127], v[128:131], v[188:191], v[124:127]
	v_mfma_f32_16x16x32_bf16 v[120:123], v[136:139], v[188:191], v[120:123]
	v_mfma_f32_16x16x32_bf16 v[108:111], v[128:131], v[200:203], v[108:111]
	v_mfma_f32_16x16x32_bf16 v[104:107], v[136:139], v[200:203], v[104:107]
	v_mfma_f32_16x16x32_bf16 v[92:95], v[128:131], v[208:211], v[92:95]
	v_mfma_f32_16x16x32_bf16 v[88:91], v[136:139], v[208:211], v[88:91]
	v_mfma_f32_16x16x32_bf16 v[76:79], v[128:131], v[216:219], v[76:79]
	v_mfma_f32_16x16x32_bf16 v[72:75], v[136:139], v[216:219], v[72:75]
	v_mfma_f32_16x16x32_bf16 v[124:127], v[132:135], v[196:199], v[124:127]
	v_mfma_f32_16x16x32_bf16 v[120:123], v[140:143], v[196:199], v[120:123]
	v_mfma_f32_16x16x32_bf16 v[108:111], v[132:135], v[204:207], v[108:111]
	v_mfma_f32_16x16x32_bf16 v[104:107], v[140:143], v[204:207], v[104:107]
	v_mfma_f32_16x16x32_bf16 v[92:95], v[132:135], v[212:215], v[92:95]
	v_mfma_f32_16x16x32_bf16 v[88:91], v[140:143], v[212:215], v[88:91]
	v_mfma_f32_16x16x32_bf16 v[76:79], v[132:135], v[224:227], v[76:79]
	v_mfma_f32_16x16x32_bf16 v[72:75], v[140:143], v[224:227], v[72:75]
	s_setprio 0
	s_setprio 1
	v_mfma_f32_16x16x32_bf16 v[116:119], v[172:175], v[188:191], v[116:119]
	v_mfma_f32_16x16x32_bf16 v[112:115], v[180:183], v[188:191], v[112:115]
	v_mfma_f32_16x16x32_bf16 v[100:103], v[172:175], v[200:203], v[100:103]
	v_mfma_f32_16x16x32_bf16 v[96:99], v[180:183], v[200:203], v[96:99]
	v_mfma_f32_16x16x32_bf16 v[84:87], v[172:175], v[208:211], v[84:87]
	v_mfma_f32_16x16x32_bf16 v[80:83], v[180:183], v[208:211], v[80:83]
	v_mfma_f32_16x16x32_bf16 v[68:71], v[172:175], v[216:219], v[68:71]
	v_mfma_f32_16x16x32_bf16 v[64:67], v[180:183], v[216:219], v[64:67]
	v_mfma_f32_16x16x32_bf16 v[116:119], v[176:179], v[196:199], v[116:119]
	v_mfma_f32_16x16x32_bf16 v[112:115], v[184:187], v[196:199], v[112:115]
	v_mfma_f32_16x16x32_bf16 v[100:103], v[176:179], v[204:207], v[100:103]
	v_mfma_f32_16x16x32_bf16 v[96:99], v[184:187], v[204:207], v[96:99]
	v_mfma_f32_16x16x32_bf16 v[84:87], v[176:179], v[212:215], v[84:87]
	v_mfma_f32_16x16x32_bf16 v[80:83], v[184:187], v[212:215], v[80:83]
	v_mfma_f32_16x16x32_bf16 v[68:71], v[176:179], v[224:227], v[68:71]
	v_mfma_f32_16x16x32_bf16 v[64:67], v[184:187], v[224:227], v[64:67]
	s_setprio 0
	s_barrier
	s_add_i32 s92, s79, s17
	v_lshl_add_u64 v[220:221], s[90:91], 0, v[146:147]
	s_mov_b32 m0, s92
	ds_read_b128 v[188:191], v195 offset:16384
	ds_read_b128 v[196:199], v195 offset:17408
	ds_read_b128 v[200:203], v195 offset:18432
	ds_read_b128 v[204:207], v195 offset:19456
	ds_read_b128 v[208:211], v195 offset:20480
	ds_read_b128 v[212:215], v195 offset:21504
	ds_read_b128 v[216:219], v195 offset:22528
	ds_read_b128 v[224:227], v195 offset:23552
	global_load_lds_dwordx4 v[220:221], off
	s_add_i32 m0, s92, 0x2000
	v_lshl_add_u64 v[228:229], s[90:91], 0, v[150:151]
	s_add_u32 s90, s90, s20
	s_addc_u32 s91, s91, s21
	s_add_i32 s92, s46, s17
	global_load_lds_dwordx4 v[228:229], off
	v_lshl_add_u64 v[230:231], s[90:91], 0, v[146:147]
	s_mov_b32 m0, s92
	v_lshl_add_u64 v[232:233], s[90:91], 0, v[150:151]
	global_load_lds_dwordx4 v[230:231], off
	s_add_i32 m0, s92, 0x2000
	v_lshl_add_u64 v[234:235], s[86:87], 0, v[144:145]
	global_load_lds_dwordx4 v[232:233], off
	s_mov_b32 m0, s70
	v_lshl_add_u64 v[236:237], s[86:87], 0, v[148:149]
	global_load_lds_dwordx4 v[234:235], off
	s_mov_b32 m0, s71
	s_nop 0
	global_load_lds_dwordx4 v[236:237], off
	s_waitcnt vmcnt(8)
	s_waitcnt lgkmcnt(0)
	s_barrier
; #define PG8_STAGE(bufoff, gbase, voff) do { _Pragma("unroll") for (int _i = 0; _i < 2; ++_i) \
;         __builtin_amdgcn_global_load_lds((const unsigned*)((const char*)(gbase) + (voff)[_i]), (PG8_LAS unsigned*)(lds + (bufoff) + ldsw + _i * 8192), 16, 0, 0); } while (0)
; #define PG8_LDA(dst, b, h) do { _Pragma("unroll") for (int m = 0; m < 4; ++m) _Pragma("unroll") for (int k = 0; k < 2; ++k) dst[m][k] = *(const PG8_LAS bf16x8*)(lds + PG8_SA(b, h) + aoff + m * 2048 + k * 1024); } while (0)
; #define PG8_LDB(dst, b, h) do { _Pragma("unroll") for (int n = 0; n < 2; ++n) _Pragma("unroll") for (int k = 0; k < 2; ++k) dst[n][k] = *(const PG8_LAS bf16x8*)(lds + PG8_SB(b, h) + boff + n * 2048 + k * 1024); } while (0)
; #define PG8_MMA(ai, bj, At, Bt) do { __builtin_amdgcn_s_setprio(1); _Pragma("unroll") for (int m = 0; m < 4; ++m) _Pragma("unroll") for (int n = 0; n < 2; ++n) _Pragma("unroll") for (int k = 0; k < 2; ++k) \
;         acc[ai][bj][m][n] = __builtin_amdgcn_mfma_f32_16x16x32_bf16(Bt[n][k], At[m][k], acc[ai][bj][m][n], 0, 0, 0); __builtin_amdgcn_s_setprio(0); } while (0)
; #define PG8_WAIT_V(n) asm volatile("s_waitcnt vmcnt(" #n ")" ::: "memory")
; #define PG8_WAIT_L(n) asm volatile("s_waitcnt lgkmcnt(" #n ")" ::: "memory")
; #define PG8_BAR __builtin_amdgcn_s_barrier()
; #define PG8_SCHED __builtin_amdgcn_sched_barrier(0)
; template <class Epi, class Sched, bool ALIGN_EPI = false, bool SP2 = false>
; __device__ __forceinline__ void gemm_phase(PG8_LAS unsigned char* lds, const Gemm g, const Sched& S, const Epi& E) {
;     ...
;             PG8_WAIT_V(8); PG8_WAIT_L(0); PG8_BAR; PG8_MMA(1, 0, At, B0); PG8_MMA(1, 1, At, B1); PG8_BAR; PG8_SCHED;
;             PG8_LDB(B0, 1, 0); PG8_LDB(B1, 1, 1); PG8_SCHED; PG8_LDA(At, 1, 0); PG8_STAGE(PG8_SA(0, 1), a2 + hstep, voffA);
;             PG8_WAIT_V(8); PG8_WAIT_L(0); PG8_BAR; PG8_MMA(0, 0, At, B0); PG8_MMA(0, 1, At, B1); PG8_BAR; PG8_SCHED;
	s_setprio 1
	v_mfma_f32_16x16x32_bf16 v[60:63], v[128:131], v[188:191], v[60:63]
	v_mfma_f32_16x16x32_bf16 v[56:59], v[136:139], v[188:191], v[56:59]
	v_mfma_f32_16x16x32_bf16 v[44:47], v[128:131], v[200:203], v[44:47]
	v_mfma_f32_16x16x32_bf16 v[40:43], v[136:139], v[200:203], v[40:43]
	v_mfma_f32_16x16x32_bf16 v[28:31], v[128:131], v[208:211], v[28:31]
	v_mfma_f32_16x16x32_bf16 v[24:27], v[136:139], v[208:211], v[24:27]
	v_mfma_f32_16x16x32_bf16 v[12:15], v[128:131], v[216:219], v[12:15]
	v_mfma_f32_16x16x32_bf16 v[8:11], v[136:139], v[216:219], v[8:11]
	v_mfma_f32_16x16x32_bf16 v[60:63], v[132:135], v[196:199], v[60:63]
	v_mfma_f32_16x16x32_bf16 v[56:59], v[140:143], v[196:199], v[56:59]
	v_mfma_f32_16x16x32_bf16 v[44:47], v[132:135], v[204:207], v[44:47]
	v_mfma_f32_16x16x32_bf16 v[40:43], v[140:143], v[204:207], v[40:43]
	v_mfma_f32_16x16x32_bf16 v[28:31], v[132:135], v[212:215], v[28:31]
	v_mfma_f32_16x16x32_bf16 v[24:27], v[140:143], v[212:215], v[24:27]
	v_mfma_f32_16x16x32_bf16 v[12:15], v[132:135], v[224:227], v[12:15]
	v_mfma_f32_16x16x32_bf16 v[8:11], v[140:143], v[224:227], v[8:11]
	s_setprio 0
	s_setprio 1
	v_mfma_f32_16x16x32_bf16 v[52:55], v[172:175], v[188:191], v[52:55]
	v_mfma_f32_16x16x32_bf16 v[48:51], v[180:183], v[188:191], v[48:51]
	v_mfma_f32_16x16x32_bf16 v[36:39], v[172:175], v[200:203], v[36:39]
	v_mfma_f32_16x16x32_bf16 v[32:35], v[180:183], v[200:203], v[32:35]
	v_mfma_f32_16x16x32_bf16 v[20:23], v[172:175], v[208:211], v[20:23]
	v_mfma_f32_16x16x32_bf16 v[16:19], v[180:183], v[208:211], v[16:19]
	v_mfma_f32_16x16x32_bf16 v[4:7], v[172:175], v[216:219], v[4:7]
	v_mfma_f32_16x16x32_bf16 v[0:3], v[180:183], v[216:219], v[0:3]
	v_mfma_f32_16x16x32_bf16 v[52:55], v[176:179], v[196:199], v[52:55]
	v_mfma_f32_16x16x32_bf16 v[48:51], v[184:187], v[196:199], v[48:51]
	v_mfma_f32_16x16x32_bf16 v[36:39], v[176:179], v[204:207], v[36:39]
	v_mfma_f32_16x16x32_bf16 v[32:35], v[184:187], v[204:207], v[32:35]
	v_mfma_f32_16x16x32_bf16 v[20:23], v[176:179], v[212:215], v[20:23]
	v_mfma_f32_16x16x32_bf16 v[16:19], v[184:187], v[212:215], v[16:19]
	v_mfma_f32_16x16x32_bf16 v[4:7], v[176:179], v[224:227], v[4:7]
	v_mfma_f32_16x16x32_bf16 v[0:3], v[184:187], v[224:227], v[0:3]
	s_setprio 0
	s_barrier
	s_add_i32 s90, 0, 0x18000
	s_add_i32 s91, 0, 0x1c000
	v_add_u32_e32 v140, s90, v159
	v_add_u32_e32 v152, s91, v159
	ds_read_b128 v[128:131], v140
	ds_read_b128 v[132:135], v140 offset:1024
	ds_read_b128 v[136:139], v140 offset:2048
	ds_read_b128 v[140:143], v140 offset:3072
	ds_read_b128 v[172:175], v152
	ds_read_b128 v[176:179], v152 offset:1024
	ds_read_b128 v[180:183], v152 offset:2048
	ds_read_b128 v[184:187], v152 offset:3072
	s_add_u32 s86, s86, s20
	s_addc_u32 s87, s87, s21
	s_mov_b32 m0, s34
	v_lshl_add_u64 v[238:239], s[86:87], 0, v[144:145]
	ds_read_b128 v[188:191], v195 offset:32768
	ds_read_b128 v[196:199], v195 offset:33792
	ds_read_b128 v[200:203], v195 offset:34816
	ds_read_b128 v[204:207], v195 offset:35840
	ds_read_b128 v[208:211], v195 offset:36864
	ds_read_b128 v[212:215], v195 offset:37888
	ds_read_b128 v[216:219], v195 offset:38912
	ds_read_b128 v[224:227], v195 offset:39936
	global_load_lds_dwordx4 v[238:239], off
	v_lshl_add_u64 v[238:239], s[86:87], 0, v[148:149]
	s_mov_b32 m0, s35
	s_nop 0
	global_load_lds_dwordx4 v[238:239], off
	s_waitcnt vmcnt(8)
	s_waitcnt lgkmcnt(0)
	s_barrier
	s_setprio 1
	v_mfma_f32_16x16x32_bf16 v[124:127], v[128:131], v[188:191], v[124:127]
	v_mfma_f32_16x16x32_bf16 v[120:123], v[136:139], v[188:191], v[120:123]
	v_mfma_f32_16x16x32_bf16 v[108:111], v[128:131], v[200:203], v[108:111]
	v_mfma_f32_16x16x32_bf16 v[104:107], v[136:139], v[200:203], v[104:107]
	v_mfma_f32_16x16x32_bf16 v[92:95], v[128:131], v[208:211], v[92:95]
	v_mfma_f32_16x16x32_bf16 v[88:91], v[136:139], v[208:211], v[88:91]
	v_mfma_f32_16x16x32_bf16 v[76:79], v[128:131], v[216:219], v[76:79]
	v_mfma_f32_16x16x32_bf16 v[72:75], v[136:139], v[216:219], v[72:75]
	v_mfma_f32_16x16x32_bf16 v[124:127], v[132:135], v[196:199], v[124:127]
	v_mfma_f32_16x16x32_bf16 v[120:123], v[140:143], v[196:199], v[120:123]
	v_mfma_f32_16x16x32_bf16 v[108:111], v[132:135], v[204:207], v[108:111]
	v_mfma_f32_16x16x32_bf16 v[104:107], v[140:143], v[204:207], v[104:107]
	v_mfma_f32_16x16x32_bf16 v[92:95], v[132:135], v[212:215], v[92:95]
	v_mfma_f32_16x16x32_bf16 v[88:91], v[140:143], v[212:215], v[88:91]
	v_mfma_f32_16x16x32_bf16 v[76:79], v[132:135], v[224:227], v[76:79]
	v_mfma_f32_16x16x32_bf16 v[72:75], v[140:143], v[224:227], v[72:75]
	s_setprio 0
	s_setprio 1
	v_mfma_f32_16x16x32_bf16 v[116:119], v[172:175], v[188:191], v[116:119]
	v_mfma_f32_16x16x32_bf16 v[112:115], v[180:183], v[188:191], v[112:115]
	v_mfma_f32_16x16x32_bf16 v[100:103], v[172:175], v[200:203], v[100:103]
	v_mfma_f32_16x16x32_bf16 v[96:99], v[180:183], v[200:203], v[96:99]
	v_mfma_f32_16x16x32_bf16 v[84:87], v[172:175], v[208:211], v[84:87]
	v_mfma_f32_16x16x32_bf16 v[80:83], v[180:183], v[208:211], v[80:83]
	v_mfma_f32_16x16x32_bf16 v[68:71], v[172:175], v[216:219], v[68:71]
	v_mfma_f32_16x16x32_bf16 v[64:67], v[180:183], v[216:219], v[64:67]
	v_mfma_f32_16x16x32_bf16 v[116:119], v[176:179], v[196:199], v[116:119]
	v_mfma_f32_16x16x32_bf16 v[112:115], v[184:187], v[196:199], v[112:115]
	v_mfma_f32_16x16x32_bf16 v[100:103], v[176:179], v[204:207], v[100:103]
	v_mfma_f32_16x16x32_bf16 v[96:99], v[184:187], v[204:207], v[96:99]
	v_mfma_f32_16x16x32_bf16 v[84:87], v[176:179], v[212:215], v[84:87]
	v_mfma_f32_16x16x32_bf16 v[80:83], v[184:187], v[212:215], v[80:83]
	v_mfma_f32_16x16x32_bf16 v[68:71], v[176:179], v[224:227], v[68:71]
	v_mfma_f32_16x16x32_bf16 v[64:67], v[184:187], v[224:227], v[64:67]
	s_setprio 0
	s_barrier
; #define PG8_STAGE(bufoff, gbase, voff) do { _Pragma("unroll") for (int _i = 0; _i < 2; ++_i) \
;         __builtin_amdgcn_global_load_lds((const unsigned*)((const char*)(gbase) + (voff)[_i]), (PG8_LAS unsigned*)(lds + (bufoff) + ldsw + _i * 8192), 16, 0, 0); } while (0)
; #define PG8_LDA(dst, b, h) do { _Pragma("unroll") for (int m = 0; m < 4; ++m) _Pragma("unroll") for (int k = 0; k < 2; ++k) dst[m][k] = *(const PG8_LAS bf16x8*)(lds + PG8_SA(b, h) + aoff + m * 2048 + k * 1024); } while (0)
; #define PG8_MMA(ai, bj, At, Bt) do { __builtin_amdgcn_s_setprio(1); _Pragma("unroll") for (int m = 0; m < 4; ++m) _Pragma("unroll") for (int n = 0; n < 2; ++n) _Pragma("unroll") for (int k = 0; k < 2; ++k) \
;         acc[ai][bj][m][n] = __builtin_amdgcn_mfma_f32_16x16x32_bf16(Bt[n][k], At[m][k], acc[ai][bj][m][n], 0, 0, 0); __builtin_amdgcn_s_setprio(0); } while (0)
; #define PG8_WAIT_V(n) asm volatile("s_waitcnt vmcnt(" #n ")" ::: "memory")
; #define PG8_WAIT_L(n) asm volatile("s_waitcnt lgkmcnt(" #n ")" ::: "memory")
; #define PG8_BAR __builtin_amdgcn_s_barrier()
; #define PG8_SCHED __builtin_amdgcn_sched_barrier(0)
; template <class Epi, class Sched, bool ALIGN_EPI = false, bool SP2 = false>
; __device__ __forceinline__ void gemm_phase(PG8_LAS unsigned char* lds, const Gemm g, const Sched& S, const Epi& E) {
;     ...
;         for (int t = 0; t < nt; t += 2) {
;     ...
;             PG8_LDA(At, 1, 1); PG8_STAGE(PG8_SB(1, 0), b3, voffB); PG8_STAGE(PG8_SB(1, 1), b3 + hstep, voffB); PG8_STAGE(PG8_SA(1, 0), a3, voffA);
;             PG8_WAIT_V(8); PG8_WAIT_L(0); PG8_BAR; PG8_MMA(1, 0, At, B0); PG8_MMA(1, 1, At, B1); PG8_BAR; PG8_SCHED;
	s_add_i32 s86, s90, s17
	v_lshl_add_u64 v[220:221], v[220:221], 0, s[26:27]
	s_mov_b32 m0, s86
	ds_read_b128 v[188:191], v195 offset:49152
	ds_read_b128 v[196:199], v195 offset:50176
	ds_read_b128 v[200:203], v195 offset:51200
	ds_read_b128 v[204:207], v195 offset:52224
	ds_read_b128 v[208:211], v195 offset:53248
	ds_read_b128 v[212:215], v195 offset:54272
	ds_read_b128 v[216:219], v195 offset:55296
	ds_read_b128 v[224:227], v195 offset:56320
	global_load_lds_dwordx4 v[220:221], off
	v_lshl_add_u64 v[220:221], v[228:229], 0, s[26:27]
	s_add_i32 m0, s86, 0x2000
	s_add_i32 s86, s91, s17
	global_load_lds_dwordx4 v[220:221], off
	v_lshl_add_u64 v[220:221], v[230:231], 0, s[26:27]
	s_mov_b32 m0, s86
	s_nop 0
	global_load_lds_dwordx4 v[220:221], off
	v_lshl_add_u64 v[220:221], v[232:233], 0, s[26:27]
	s_add_i32 m0, s86, 0x2000
	s_nop 0
	global_load_lds_dwordx4 v[220:221], off
	v_lshl_add_u64 v[220:221], v[234:235], 0, s[26:27]
	s_mov_b32 m0, s38
	s_nop 0
	global_load_lds_dwordx4 v[220:221], off
	v_lshl_add_u64 v[220:221], v[236:237], 0, s[26:27]
	s_mov_b32 m0, s39
	s_nop 0
	global_load_lds_dwordx4 v[220:221], off
	s_waitcnt vmcnt(8)
	s_waitcnt lgkmcnt(0)
	s_barrier
	s_setprio 1
	v_mfma_f32_16x16x32_bf16 v[60:63], v[128:131], v[188:191], v[60:63]
	v_mfma_f32_16x16x32_bf16 v[56:59], v[136:139], v[188:191], v[56:59]
	v_mfma_f32_16x16x32_bf16 v[44:47], v[128:131], v[200:203], v[44:47]
	v_mfma_f32_16x16x32_bf16 v[40:43], v[136:139], v[200:203], v[40:43]
	v_mfma_f32_16x16x32_bf16 v[28:31], v[128:131], v[208:211], v[28:31]
	v_mfma_f32_16x16x32_bf16 v[24:27], v[136:139], v[208:211], v[24:27]
	v_mfma_f32_16x16x32_bf16 v[12:15], v[128:131], v[216:219], v[12:15]
	v_mfma_f32_16x16x32_bf16 v[8:11], v[136:139], v[216:219], v[8:11]
	v_mfma_f32_16x16x32_bf16 v[60:63], v[132:135], v[196:199], v[60:63]
	v_mfma_f32_16x16x32_bf16 v[56:59], v[140:143], v[196:199], v[56:59]
	v_mfma_f32_16x16x32_bf16 v[44:47], v[132:135], v[204:207], v[44:47]
	v_mfma_f32_16x16x32_bf16 v[40:43], v[140:143], v[204:207], v[40:43]
	v_mfma_f32_16x16x32_bf16 v[28:31], v[132:135], v[212:215], v[28:31]
	v_mfma_f32_16x16x32_bf16 v[24:27], v[140:143], v[212:215], v[24:27]
	v_mfma_f32_16x16x32_bf16 v[12:15], v[132:135], v[224:227], v[12:15]
	v_mfma_f32_16x16x32_bf16 v[8:11], v[140:143], v[224:227], v[8:11]
	s_setprio 0
	s_setprio 1
	v_mfma_f32_16x16x32_bf16 v[52:55], v[172:175], v[188:191], v[52:55]
	v_mfma_f32_16x16x32_bf16 v[48:51], v[180:183], v[188:191], v[48:51]
	v_mfma_f32_16x16x32_bf16 v[36:39], v[172:175], v[200:203], v[36:39]
	v_mfma_f32_16x16x32_bf16 v[32:35], v[180:183], v[200:203], v[32:35]
	v_mfma_f32_16x16x32_bf16 v[20:23], v[172:175], v[208:211], v[20:23]
	v_mfma_f32_16x16x32_bf16 v[16:19], v[180:183], v[208:211], v[16:19]
	v_mfma_f32_16x16x32_bf16 v[4:7], v[172:175], v[216:219], v[4:7]
	v_mfma_f32_16x16x32_bf16 v[0:3], v[180:183], v[216:219], v[0:3]
	v_mfma_f32_16x16x32_bf16 v[52:55], v[176:179], v[196:199], v[52:55]
	v_mfma_f32_16x16x32_bf16 v[48:51], v[184:187], v[196:199], v[48:51]
	v_mfma_f32_16x16x32_bf16 v[36:39], v[176:179], v[204:207], v[36:39]
	v_mfma_f32_16x16x32_bf16 v[32:35], v[184:187], v[204:207], v[32:35]
	v_mfma_f32_16x16x32_bf16 v[20:23], v[176:179], v[212:215], v[20:23]
	v_mfma_f32_16x16x32_bf16 v[16:19], v[184:187], v[212:215], v[16:19]
	v_mfma_f32_16x16x32_bf16 v[4:7], v[176:179], v[224:227], v[4:7]
	v_mfma_f32_16x16x32_bf16 v[0:3], v[184:187], v[224:227], v[0:3]
	s_setprio 0
	s_barrier
	s_add_u32 s14, s14, 0x100
	s_addc_u32 s15, s15, 0
	s_add_u32 s67, s67, 0x100
	s_addc_u32 s85, s85, 0
	s_cmp_ge_i32 s89, s78
	s_mov_b32 s86, s89
	s_cbranch_scc0 .LBB0_1940

.LBB0_1946:
	s_lshl_b32 s86, s84, 7
	v_or_b32_e32 v128, s86, v154
	v_ashrrev_i32_e32 v129, 31, v128
	v_lshl_add_u64 v[132:133], v[128:129], 2, s[40:41]
	s_mov_b64 s[14:15], 0x1000
	global_load_dwordx4 v[128:131], v[132:133], off offset:16
	global_load_dwordx4 v[136:139], v[132:133], off
	v_lshl_add_u64 v[134:135], v[132:133], 0, s[14:15]
	v_add_co_u32_e32 v132, vcc, 0x1000, v132
	s_lshl_b64 s[14:15], s[88:89], 2
	s_nop 0
	v_addc_co_u32_e32 v133, vcc, 0, v133, vcc
	global_load_dwordx4 v[140:143], v[132:133], off
	s_nop 0
	global_load_dwordx4 v[132:135], v[134:135], off offset:16
	v_readlane_b32 s28, v255, 17
	s_add_u32 s92, s14, s28
	v_readlane_b32 s14, v255, 24
	s_addc_u32 s93, s15, s14
	s_ashr_i32 s85, s84, 31
	s_lshl_b64 s[90:91], s[84:85], 7
	s_ashr_i32 s87, s86, 31
	s_lshl_b64 s[14:15], s[92:93], 10
	s_add_u32 s67, s14, s90
	s_addc_u32 s85, s15, s91
	s_lshl_b64 s[94:95], s[92:93], 12
	v_lshlrev_b32_e32 v237, 2, v154
	s_waitcnt vmcnt(0)
	v_sub_f32_e32 v136, v136, v140
	v_mul_f32_e32 v136, 0x3fb8aa3b, v136
	v_exp_f32_e32 v136, v136
	s_nop 0
	v_add_f32_e32 v136, 1.0, v136
	v_rcp_f32_e32 v140, v136
	v_sub_f32_e32 v136, v137, v141
	v_and_or_b32 v137, v222, 64, v155
	v_lshl_or_b32 v232, v137, 2, 60
	v_add_f32_e32 v137, 1.0, v231
	v_rcp_f32_e32 v176, v137
	v_add_f32_e32 v137, 1.0, v230
	v_mul_f32_e32 v136, 0x3fb8aa3b, v136
	v_rcp_f32_e32 v177, v137
	v_add_f32_e32 v137, 1.0, v229
	v_exp_f32_e32 v136, v136
	v_rcp_f32_e32 v184, v137
	v_add_f32_e32 v137, 1.0, v228
	v_rcp_f32_e32 v185, v137
	v_add_f32_e32 v137, 1.0, v227
	v_rcp_f32_e32 v182, v137
	v_add_f32_e32 v137, 1.0, v226
	v_rcp_f32_e32 v183, v137
	v_add_f32_e32 v137, 1.0, v225
	v_add_f32_e32 v136, 1.0, v136
	v_rcp_f32_e32 v180, v137
	v_add_f32_e32 v137, 1.0, v224
	v_rcp_f32_e32 v141, v136
	v_and_b32_e32 v136, 0x70, v222
	v_rcp_f32_e32 v181, v137
	v_add_u32_e32 v137, -1, v222
	v_cmp_lt_i32_e32 vcc, v137, v136
	v_pk_add_f32 v[174:175], v[140:141], 1.0 op_sel_hi:[1,0] neg_lo:[1,0] neg_hi:[1,0]
	s_nop 0
	v_cndmask_b32_e32 v137, v137, v222, vcc
	v_lshlrev_b32_e32 v235, 2, v137
	v_add_u32_e32 v137, -2, v222
	v_cmp_lt_i32_e32 vcc, v137, v136
	v_pk_fma_f32 v[176:177], v[176:177], v[174:175], v[140:141]
	v_pk_fma_f32 v[184:185], v[184:185], v[174:175], v[140:141]
	v_cndmask_b32_e32 v137, v137, v222, vcc
	v_lshlrev_b32_e32 v234, 2, v137
	v_add_u32_e32 v137, -4, v222
	v_cmp_lt_i32_e32 vcc, v137, v136
	v_pk_fma_f32 v[182:183], v[182:183], v[174:175], v[140:141]
	v_pk_fma_f32 v[180:181], v[180:181], v[174:175], v[140:141]
	v_cndmask_b32_e32 v137, v137, v222, vcc
	v_lshlrev_b32_e32 v233, 2, v137
	v_add_u32_e32 v137, -8, v222
	v_cmp_lt_i32_e32 vcc, v137, v136
	s_nop 1
	v_cndmask_b32_e32 v136, v137, v222, vcc
	v_cmp_gt_f32_e32 vcc, s47, v176
	v_lshlrev_b32_e32 v236, 2, v136
	v_mov_b32_e32 v137, s85
	v_cndmask_b32_e64 v152, 0, 32, vcc
	v_ldexp_f32 v152, v176, v152
	v_log_f32_e32 v152, v152
	v_or_b32_e32 v136, s67, v154
	v_lshlrev_b64 v[136:137], 7, v[136:137]
	v_lshl_add_u64 v[136:137], v[164:165], 0, v[136:137]
	v_mul_f32_e32 v178, 0x3f317217, v152
	v_fma_f32 v178, v152, s96, -v178
	v_fmac_f32_e32 v178, 0x3377d1cf, v152
	v_fmac_f32_e32 v178, 0x3f317217, v152
	v_cmp_lt_f32_e64 s[14:15], |v152|, s1
	s_nop 1
	v_cndmask_b32_e64 v152, v152, v178, s[14:15]
	v_cndmask_b32_e32 v178, 0, v223, vcc
	v_cmp_gt_f32_e32 vcc, s47, v177
	v_sub_f32_e32 v152, v152, v178
	s_nop 0
	v_cndmask_b32_e64 v178, 0, 32, vcc
	v_ldexp_f32 v178, v177, v178
	v_log_f32_e32 v178, v178
	v_pk_add_f32 v[176:177], v[176:177], 1.0 op_sel_hi:[1,0] neg_lo:[1,0] neg_hi:[1,0]
	v_mul_f32_e32 v179, 0x3f317217, v178
	v_fma_f32 v179, v178, s96, -v179
	v_fmac_f32_e32 v179, 0x3377d1cf, v178
	v_fmac_f32_e32 v179, 0x3f317217, v178
	v_cmp_lt_f32_e64 s[14:15], |v178|, s1
	s_nop 1
	v_cndmask_b32_e64 v178, v178, v179, s[14:15]
	v_cndmask_b32_e32 v179, 0, v223, vcc
	v_sub_f32_e32 v178, v178, v179
	v_cmp_gt_f32_e32 vcc, s47, v184
	s_waitcnt lgkmcnt(0)
	v_add_f32_dpp v152, v152, v152 row_shr:1 row_mask:0xf bank_mask:0xf
	v_add_f32_dpp v178, v178, v178 row_shr:1 row_mask:0xf bank_mask:0xf
	s_nop 1
	v_add_f32_dpp v152, v152, v152 row_shr:2 row_mask:0xf bank_mask:0xf
	v_add_f32_dpp v178, v178, v178 row_shr:2 row_mask:0xf bank_mask:0xf
	s_nop 1
	v_add_f32_dpp v152, v152, v152 row_shr:4 row_mask:0xf bank_mask:0xf
	v_add_f32_dpp v178, v178, v178 row_shr:4 row_mask:0xf bank_mask:0xf
	s_nop 1
	v_add_f32_dpp v152, v152, v152 row_shr:8 row_mask:0xf bank_mask:0xf
	v_add_f32_e32 v187, 0, v152
	v_add_f32_dpp v178, v178, v178 row_shr:8 row_mask:0xf bank_mask:0xf
	v_mov_b32_dpp v179, v152 row_newbcast:15 row_mask:0xf bank_mask:0xf
	v_add_f32_e32 v188, 0, v178
	v_add_f32_e32 v152, 0, v179
	v_mov_b32_dpp v179, v178 row_newbcast:15 row_mask:0xf bank_mask:0xf
	v_mul_f32_e32 v178, 0xbfb8aa3b, v187
	v_cndmask_b32_e64 v187, 0, 32, vcc
	v_ldexp_f32 v187, v184, v187
	v_log_f32_e32 v187, v187
	v_add_f32_e32 v186, 0, v179
	v_mul_f32_e32 v179, 0xbfb8aa3b, v188
	v_exp_f32_e32 v178, v178
	v_mul_f32_e32 v188, 0x3f317217, v187
	v_fma_f32 v188, v187, s96, -v188
	v_fmac_f32_e32 v188, 0x3377d1cf, v187
	v_fmac_f32_e32 v188, 0x3f317217, v187
	v_cmp_lt_f32_e64 s[14:15], |v187|, s1
	v_exp_f32_e32 v179, v179
	s_nop 0
	v_cndmask_b32_e64 v187, v187, v188, s[14:15]
	v_cndmask_b32_e32 v188, 0, v223, vcc
	v_cmp_gt_f32_e32 vcc, s47, v185
	v_sub_f32_e32 v187, v187, v188
	v_pk_mul_f32 v[176:177], v[176:177], v[178:179]
	v_cndmask_b32_e64 v188, 0, 32, vcc
	v_ldexp_f32 v188, v185, v188
	v_log_f32_e32 v188, v188
	v_pk_add_f32 v[184:185], v[184:185], 1.0 op_sel_hi:[1,0] neg_lo:[1,0] neg_hi:[1,0]
	v_mul_f32_e32 v189, 0x3f317217, v188
	v_fma_f32 v189, v188, s96, -v189
	v_fmac_f32_e32 v189, 0x3377d1cf, v188
	v_fmac_f32_e32 v189, 0x3f317217, v188
	v_cmp_lt_f32_e64 s[14:15], |v188|, s1
	s_nop 1
	v_cndmask_b32_e64 v188, v188, v189, s[14:15]
	v_cndmask_b32_e32 v189, 0, v223, vcc
	v_sub_f32_e32 v188, v188, v189
	v_cmp_gt_f32_e32 vcc, s47, v182
	v_add_f32_dpp v187, v187, v187 row_shr:1 row_mask:0xf bank_mask:0xf
	v_add_f32_dpp v188, v188, v188 row_shr:1 row_mask:0xf bank_mask:0xf
	s_nop 1
	v_add_f32_dpp v187, v187, v187 row_shr:2 row_mask:0xf bank_mask:0xf
	v_add_f32_dpp v188, v188, v188 row_shr:2 row_mask:0xf bank_mask:0xf
	s_nop 1
	v_add_f32_dpp v187, v187, v187 row_shr:4 row_mask:0xf bank_mask:0xf
	v_add_f32_dpp v188, v188, v188 row_shr:4 row_mask:0xf bank_mask:0xf
	s_nop 1
	v_add_f32_dpp v187, v187, v187 row_shr:8 row_mask:0xf bank_mask:0xf
	v_add_f32_dpp v188, v188, v188 row_shr:8 row_mask:0xf bank_mask:0xf
	s_nop 1
	v_mov_b32_dpp v189, v187 row_newbcast:15 row_mask:0xf bank_mask:0xf
	v_mov_b32_dpp v190, v188 row_newbcast:15 row_mask:0xf bank_mask:0xf
	v_add_f32_e32 v187, v187, v152
	v_add_f32_e32 v188, v188, v186
	s_waitcnt lgkmcnt(1)
	v_add_f32_e32 v152, v152, v189
	v_add_f32_e32 v189, v186, v190
	v_mul_f32_e32 v186, 0xbfb8aa3b, v187
	v_mul_f32_e32 v187, 0xbfb8aa3b, v188
	v_cndmask_b32_e64 v188, 0, 32, vcc
	v_ldexp_f32 v188, v182, v188
	v_log_f32_e32 v188, v188
	v_exp_f32_e32 v186, v186
	v_exp_f32_e32 v187, v187
	v_mul_f32_e32 v190, 0x3f317217, v188
	v_fma_f32 v190, v188, s96, -v190
	v_fmac_f32_e32 v190, 0x3377d1cf, v188
	v_fmac_f32_e32 v190, 0x3f317217, v188
	v_cmp_lt_f32_e64 s[14:15], |v188|, s1
	v_pk_mul_f32 v[184:185], v[184:185], v[186:187]
	s_nop 0
	v_cndmask_b32_e64 v188, v188, v190, s[14:15]
	v_cndmask_b32_e32 v190, 0, v223, vcc
	v_cmp_gt_f32_e32 vcc, s47, v183
	v_sub_f32_e32 v188, v188, v190
	s_nop 0
	v_cndmask_b32_e64 v190, 0, 32, vcc
	v_ldexp_f32 v190, v183, v190
	v_log_f32_e32 v190, v190
	v_pk_add_f32 v[182:183], v[182:183], 1.0 op_sel_hi:[1,0] neg_lo:[1,0] neg_hi:[1,0]
	v_mul_f32_e32 v191, 0x3f317217, v190
	v_fma_f32 v191, v190, s96, -v191
	v_fmac_f32_e32 v191, 0x3377d1cf, v190
	v_fmac_f32_e32 v191, 0x3f317217, v190
	v_cmp_lt_f32_e64 s[14:15], |v190|, s1
	s_nop 1
	v_cndmask_b32_e64 v190, v190, v191, s[14:15]
	v_cndmask_b32_e32 v191, 0, v223, vcc
	v_sub_f32_e32 v190, v190, v191
	v_cmp_gt_f32_e32 vcc, s47, v180
	v_add_f32_dpp v188, v188, v188 row_shr:1 row_mask:0xf bank_mask:0xf
	v_add_f32_dpp v190, v190, v190 row_shr:1 row_mask:0xf bank_mask:0xf
	s_nop 1
	v_add_f32_dpp v188, v188, v188 row_shr:2 row_mask:0xf bank_mask:0xf
	v_add_f32_dpp v190, v190, v190 row_shr:2 row_mask:0xf bank_mask:0xf
	s_nop 1
	v_add_f32_dpp v188, v188, v188 row_shr:4 row_mask:0xf bank_mask:0xf
	v_add_f32_dpp v190, v190, v190 row_shr:4 row_mask:0xf bank_mask:0xf
	s_nop 1
	v_add_f32_dpp v188, v188, v188 row_shr:8 row_mask:0xf bank_mask:0xf
	v_add_f32_dpp v190, v190, v190 row_shr:8 row_mask:0xf bank_mask:0xf
	s_nop 1
	v_mov_b32_dpp v191, v188 row_newbcast:15 row_mask:0xf bank_mask:0xf
	v_add_f32_e32 v188, v188, v152
	v_mov_b32_dpp v196, v190 row_newbcast:15 row_mask:0xf bank_mask:0xf
	v_add_f32_e32 v190, v190, v189
	v_mul_f32_e32 v188, 0xbfb8aa3b, v188
	v_exp_f32_e32 v198, v188
	v_mul_f32_e32 v188, 0xbfb8aa3b, v190
	v_exp_f32_e32 v199, v188
	v_cndmask_b32_e64 v188, 0, 32, vcc
	v_ldexp_f32 v188, v180, v188
	v_log_f32_e32 v188, v188
	s_waitcnt lgkmcnt(1)
	v_add_f32_e32 v152, v152, v191
	v_add_f32_e32 v189, v189, v196
	v_pk_mul_f32 v[182:183], v[182:183], v[198:199]
	v_mul_f32_e32 v190, 0x3f317217, v188
	v_fma_f32 v190, v188, s96, -v190
	v_fmac_f32_e32 v190, 0x3377d1cf, v188
	v_fmac_f32_e32 v190, 0x3f317217, v188
	v_cmp_lt_f32_e64 s[14:15], |v188|, s1
	s_nop 1
	v_cndmask_b32_e64 v188, v188, v190, s[14:15]
	v_cndmask_b32_e32 v190, 0, v223, vcc
	v_cmp_gt_f32_e32 vcc, s47, v181
	v_sub_f32_e32 v188, v188, v190
	s_nop 0
	v_cndmask_b32_e64 v190, 0, 32, vcc
	v_ldexp_f32 v190, v181, v190
	v_log_f32_e32 v190, v190
	v_pk_add_f32 v[180:181], v[180:181], 1.0 op_sel_hi:[1,0] neg_lo:[1,0] neg_hi:[1,0]
	v_mul_f32_e32 v191, 0x3f317217, v190
	v_fma_f32 v191, v190, s96, -v191
	v_fmac_f32_e32 v191, 0x3377d1cf, v190
	v_fmac_f32_e32 v191, 0x3f317217, v190
	v_cmp_lt_f32_e64 s[14:15], |v190|, s1
	s_nop 1
	v_cndmask_b32_e64 v190, v190, v191, s[14:15]
	v_cndmask_b32_e32 v191, 0, v223, vcc
	v_sub_f32_e32 v190, v190, v191
	v_add_f32_dpp v188, v188, v188 row_shr:1 row_mask:0xf bank_mask:0xf
	s_nop 1
	v_add_f32_dpp v190, v190, v190 row_shr:1 row_mask:0xf bank_mask:0xf
	v_add_f32_dpp v188, v188, v188 row_shr:2 row_mask:0xf bank_mask:0xf
	s_nop 1
	v_add_f32_dpp v190, v190, v190 row_shr:2 row_mask:0xf bank_mask:0xf
	v_add_f32_dpp v188, v188, v188 row_shr:4 row_mask:0xf bank_mask:0xf
	s_nop 1
	v_add_f32_dpp v190, v190, v190 row_shr:4 row_mask:0xf bank_mask:0xf
	v_add_f32_dpp v188, v188, v188 row_shr:8 row_mask:0xf bank_mask:0xf
	v_add_f32_e32 v197, v188, v152
	v_add_f32_dpp v190, v190, v190 row_shr:8 row_mask:0xf bank_mask:0xf
	v_mov_b32_dpp v191, v188 row_newbcast:15 row_mask:0xf bank_mask:0xf
	s_nop 1
	v_mov_b32_dpp v196, v190 row_newbcast:15 row_mask:0xf bank_mask:0xf
	v_add_f32_e32 v190, v190, v189
	s_waitcnt lgkmcnt(1)
	v_add_f32_e32 v152, v152, v191
	v_mul_f32_e32 v152, 0x3fb8aa3b, v152
	v_add_f32_e32 v189, v189, v196
	v_exp_f32_e32 v188, v152
	v_mul_f32_e32 v152, 0x3fb8aa3b, v189
	v_exp_f32_e32 v189, v152
	v_mul_f32_e32 v152, v176, v188
	v_cvt_pk_bf16_f32 v152, v152, s0
	global_store_short v[136:137], v152, off
	v_mul_f32_e32 v152, v177, v189
	v_cvt_pk_bf16_f32 v152, v152, s0
	global_store_short v[136:137], v152, off offset:128
	v_mul_f32_e32 v152, v184, v188
	v_cvt_pk_bf16_f32 v152, v152, s0
	global_store_short v[136:137], v152, off offset:32
	v_mul_f32_e32 v152, v185, v189
	v_cvt_pk_bf16_f32 v152, v152, s0
	global_store_short v[136:137], v152, off offset:160
	v_mul_f32_e32 v152, v182, v188
	v_cvt_pk_bf16_f32 v152, v152, s0
	global_store_short v[136:137], v152, off offset:64
	v_mul_f32_e32 v152, v183, v189
	v_cvt_pk_bf16_f32 v152, v152, s0
	global_store_short v[136:137], v152, off offset:192
	v_mul_f32_e32 v152, 0xbfb8aa3b, v197
	v_exp_f32_e32 v200, v152
	v_mul_f32_e32 v152, 0xbfb8aa3b, v190
	v_exp_f32_e32 v201, v152
	s_nop 0
	v_pk_mul_f32 v[180:181], v[180:181], v[200:201]
	s_nop 0
	v_mul_f32_e32 v152, v188, v180
	v_cvt_pk_bf16_f32 v152, v152, s0
	global_store_short v[136:137], v152, off offset:96
	v_mul_f32_e32 v152, v189, v181
	v_cvt_pk_bf16_f32 v152, v152, s0
	global_store_short v[136:137], v152, off offset:224
	s_and_saveexec_b64 s[14:15], s[4:5]
	s_cbranch_execz .LBB0_1948
	s_add_u32 vcc_lo, s33, s94
	s_addc_u32 vcc_hi, s0, s95
	s_lshl_b64 s[88:89], s[86:87], 2
	s_add_u32 s88, vcc_lo, s88
	s_addc_u32 s89, vcc_hi, s89
	global_store_dwordx2 v237, v[188:189], s[88:89]
.LBB0_1948:
	s_or_b64 exec, exec, s[14:15]
	v_sub_f32_e32 v137, v139, v143
	v_mul_f32_e32 v139, 0xbfb8aa3b, v124
	v_mul_f32_e32 v143, 0xbfb8aa3b, v125
	v_exp_f32_e32 v139, v139
	v_exp_f32_e32 v143, v143
	v_sub_f32_e32 v136, v138, v142
	v_rcp_f32_e32 v138, v178
	v_add_f32_e32 v139, 1.0, v139
	v_add_f32_e32 v143, 1.0, v143
	v_rcp_f32_e32 v142, v139
	v_rcp_f32_e32 v143, v143
	v_rcp_f32_e32 v139, v179
	v_cvt_pk_bf16_f32 v190, v184, v185
	v_mul_f32_e32 v136, 0x3fb8aa3b, v136
	v_pk_mul_f32 v[142:143], v[124:125], v[142:143]
	v_mul_f32_e32 v137, 0x3fb8aa3b, v137
	v_pk_mul_f32 v[138:139], v[142:143], v[138:139]
	v_mul_f32_e32 v143, 0xbfb8aa3b, v109
	v_cvt_pk_bf16_f32 v188, v138, v139
	v_mul_f32_e32 v139, 0xbfb8aa3b, v108
	v_exp_f32_e32 v139, v139
	v_exp_f32_e32 v143, v143
	v_cvt_pk_bf16_f32 v142, v176, v177
	v_rcp_f32_e32 v138, v186
	v_add_f32_e32 v139, 1.0, v139
	v_add_f32_e32 v143, 1.0, v143
	v_rcp_f32_e32 v176, v139
	v_rcp_f32_e32 v177, v143
	v_rcp_f32_e32 v139, v187
	v_mul_f32_e32 v143, 0xbfb8aa3b, v93
	v_exp_f32_e32 v143, v143
	v_pk_mul_f32 v[176:177], v[108:109], v[176:177]
	v_exp_f32_e32 v136, v136
	v_pk_mul_f32 v[138:139], v[176:177], v[138:139]
	v_add_f32_e32 v143, 1.0, v143
	v_cvt_pk_bf16_f32 v196, v138, v139
	v_mul_f32_e32 v139, 0xbfb8aa3b, v92
	v_exp_f32_e32 v139, v139
	v_rcp_f32_e32 v177, v143
	v_rcp_f32_e32 v138, v198
	v_mul_f32_e32 v143, 0xbfb8aa3b, v77
	v_add_f32_e32 v139, 1.0, v139
	v_rcp_f32_e32 v176, v139
	v_rcp_f32_e32 v139, v199
	v_exp_f32_e32 v143, v143
	v_cvt_pk_bf16_f32 v198, v180, v181
	v_pk_mul_f32 v[176:177], v[92:93], v[176:177]
	v_exp_f32_e32 v137, v137
	v_pk_mul_f32 v[138:139], v[176:177], v[138:139]
	v_add_f32_e32 v143, 1.0, v143
	v_cvt_pk_bf16_f32 v204, v138, v139
	v_mul_f32_e32 v139, 0xbfb8aa3b, v76
	v_exp_f32_e32 v139, v139
	v_rcp_f32_e32 v177, v143
	v_mul_f32_e32 v143, 0xbfb8aa3b, v118
	v_exp_f32_e32 v143, v143
	v_add_f32_e32 v139, 1.0, v139
	v_rcp_f32_e32 v176, v139
	v_rcp_f32_e32 v138, v200
	v_rcp_f32_e32 v139, v201
	v_add_f32_e32 v143, 1.0, v143
	v_pk_mul_f32 v[176:177], v[76:77], v[176:177]
	v_add_f32_e32 v136, 1.0, v136
	v_pk_mul_f32 v[138:139], v[176:177], v[138:139]
	v_rcp_f32_e32 v176, v143
	v_mul_f32_e32 v143, 0xbfb8aa3b, v119
	v_exp_f32_e32 v143, v143
	v_add_f32_e32 v137, 1.0, v137
	v_rcp_f32_e32 v136, v136
	v_rcp_f32_e32 v137, v137
	v_add_f32_e32 v143, 1.0, v143
	v_rcp_f32_e32 v177, v143
	v_mul_f32_e32 v143, 0xbfb8aa3b, v102
	v_exp_f32_e32 v143, v143
	v_cvt_pk_bf16_f32 v200, v138, v139
	v_pk_add_f32 v[138:139], v[136:137], 1.0 op_sel_hi:[1,0] neg_lo:[1,0] neg_hi:[1,0]
	v_mov_b32_e32 v179, s85
	v_add_f32_e32 v143, 1.0, v143
	v_rcp_f32_e32 v180, v143
	v_mul_f32_e32 v143, 0xbfb8aa3b, v103
	v_exp_f32_e32 v143, v143
	v_pk_fma_f32 v[176:177], v[176:177], v[138:139], v[136:137]
	v_or_b32_e32 v178, s67, v158
	v_cmp_gt_f32_e32 vcc, s47, v176
	v_add_f32_e32 v143, 1.0, v143
	v_rcp_f32_e32 v181, v143
	v_mul_f32_e32 v143, 0xbfb8aa3b, v86
	v_exp_f32_e32 v143, v143
	v_lshlrev_b64 v[178:179], 7, v[178:179]
	v_lshl_add_u64 v[206:207], v[164:165], 0, v[178:179]
	v_pk_fma_f32 v[180:181], v[180:181], v[138:139], v[136:137]
	v_add_f32_e32 v143, 1.0, v143
	v_rcp_f32_e32 v184, v143
	v_mul_f32_e32 v143, 0xbfb8aa3b, v87
	v_exp_f32_e32 v143, v143
	v_cvt_pk_bf16_f32 v202, v182, v183
	v_lshlrev_b64 v[208:209], 11, v[172:173]
	s_lshl_b64 s[88:89], s[86:87], 1
	v_add_f32_e32 v143, 1.0, v143
	v_rcp_f32_e32 v185, v143
	v_mul_f32_e32 v143, 0xbfb8aa3b, v70
	v_exp_f32_e32 v143, v143
	v_pk_fma_f32 v[184:185], v[184:185], v[138:139], v[136:137]
	v_add_f32_e32 v143, 1.0, v143
	v_rcp_f32_e32 v210, v143
	v_mul_f32_e32 v143, 0xbfb8aa3b, v71
	v_exp_f32_e32 v143, v143
	s_nop 0
	v_add_f32_e32 v143, 1.0, v143
	v_rcp_f32_e32 v211, v143
	v_cndmask_b32_e64 v143, 0, 32, vcc
	v_ldexp_f32 v143, v176, v143
	v_log_f32_e32 v143, v143
	v_pk_fma_f32 v[210:211], v[210:211], v[138:139], v[136:137]
	v_mul_f32_e32 v152, 0x3f317217, v143
	v_fma_f32 v152, v143, s96, -v152
	v_fmac_f32_e32 v152, 0x3377d1cf, v143
	v_fmac_f32_e32 v152, 0x3f317217, v143
	v_cmp_lt_f32_e64 s[14:15], |v143|, s1
	s_nop 1
	v_cndmask_b32_e64 v143, v143, v152, s[14:15]
	v_cndmask_b32_e32 v152, 0, v223, vcc
	v_cmp_gt_f32_e32 vcc, s47, v177
	v_sub_f32_e32 v143, v143, v152
	s_nop 0
	v_cndmask_b32_e64 v152, 0, 32, vcc
	v_ldexp_f32 v152, v177, v152
	v_log_f32_e32 v152, v152
	v_pk_add_f32 v[176:177], v[176:177], 1.0 op_sel_hi:[1,0] neg_lo:[1,0] neg_hi:[1,0]
	v_mul_f32_e32 v178, 0x3f317217, v152
	v_fma_f32 v178, v152, s96, -v178
	v_fmac_f32_e32 v178, 0x3377d1cf, v152
	v_fmac_f32_e32 v178, 0x3f317217, v152
	v_cmp_lt_f32_e64 s[14:15], |v152|, s1
	s_nop 1
	v_cndmask_b32_e64 v152, v152, v178, s[14:15]
	v_cndmask_b32_e32 v178, 0, v223, vcc
	v_cmp_gt_f32_e32 vcc, s47, v180
	v_sub_f32_e32 v152, v152, v178
	v_cndmask_b32_e64 v186, 0, 32, vcc
	v_ldexp_f32 v186, v180, v186
	v_log_f32_e32 v186, v186
	s_waitcnt lgkmcnt(0)
	v_add_f32_dpp v143, v143, v143 row_shr:1 row_mask:0xf bank_mask:0xf
	v_mul_f32_e32 v187, 0x3f317217, v186
	v_fma_f32 v187, v186, s96, -v187
	v_fmac_f32_e32 v187, 0x3377d1cf, v186
	v_fmac_f32_e32 v187, 0x3f317217, v186
	v_cmp_lt_f32_e64 s[14:15], |v186|, s1
	v_cndmask_b32_e64 v186, v186, v187, s[14:15]
	v_cndmask_b32_e32 v187, 0, v223, vcc
	v_cmp_gt_f32_e32 vcc, s47, v181
	v_sub_f32_e32 v186, v186, v187
	v_add_f32_dpp v152, v152, v152 row_shr:1 row_mask:0xf bank_mask:0xf
	v_cndmask_b32_e64 v187, 0, 32, vcc
	v_ldexp_f32 v187, v181, v187
	v_log_f32_e32 v187, v187
	v_pk_add_f32 v[180:181], v[180:181], 1.0 op_sel_hi:[1,0] neg_lo:[1,0] neg_hi:[1,0]
	v_mul_f32_e32 v191, 0x3f317217, v187
	v_fma_f32 v191, v187, s96, -v191
	v_fmac_f32_e32 v191, 0x3377d1cf, v187
	v_fmac_f32_e32 v191, 0x3f317217, v187
	v_cmp_lt_f32_e64 s[14:15], |v187|, s1
	v_add_f32_dpp v143, v143, v143 row_shr:2 row_mask:0xf bank_mask:0xf
	v_cndmask_b32_e64 v187, v187, v191, s[14:15]
	v_cndmask_b32_e32 v191, 0, v223, vcc
	v_sub_f32_e32 v187, v187, v191
	v_cmp_gt_f32_e32 vcc, s47, v184
	s_waitcnt lgkmcnt(1)
	v_add_f32_dpp v186, v186, v186 row_shr:1 row_mask:0xf bank_mask:0xf
	s_waitcnt lgkmcnt(1)
	v_add_f32_dpp v152, v152, v152 row_shr:2 row_mask:0xf bank_mask:0xf
	s_waitcnt lgkmcnt(1)
	v_add_f32_dpp v187, v187, v187 row_shr:1 row_mask:0xf bank_mask:0xf
	s_waitcnt lgkmcnt(1)
	v_add_f32_dpp v143, v143, v143 row_shr:4 row_mask:0xf bank_mask:0xf
	s_waitcnt lgkmcnt(1)
	v_add_f32_dpp v186, v186, v186 row_shr:2 row_mask:0xf bank_mask:0xf
	s_waitcnt lgkmcnt(1)
	v_add_f32_dpp v152, v152, v152 row_shr:4 row_mask:0xf bank_mask:0xf
	s_waitcnt lgkmcnt(1)
	v_add_f32_dpp v187, v187, v187 row_shr:2 row_mask:0xf bank_mask:0xf
	s_waitcnt lgkmcnt(1)
	v_add_f32_dpp v143, v143, v143 row_shr:8 row_mask:0xf bank_mask:0xf
	s_waitcnt lgkmcnt(1)
	v_add_f32_dpp v186, v186, v186 row_shr:4 row_mask:0xf bank_mask:0xf
	s_waitcnt lgkmcnt(1)
	v_add_f32_dpp v152, v152, v152 row_shr:8 row_mask:0xf bank_mask:0xf
	v_mov_b32_dpp v178, v143 row_newbcast:15 row_mask:0xf bank_mask:0xf
	v_add_f32_e32 v143, 0, v143
	s_waitcnt lgkmcnt(1)
	v_add_f32_dpp v187, v187, v187 row_shr:4 row_mask:0xf bank_mask:0xf
	s_waitcnt lgkmcnt(1)
	v_add_f32_e32 v182, 0, v178
	v_mov_b32_dpp v178, v152 row_newbcast:15 row_mask:0xf bank_mask:0xf
	v_add_f32_e32 v152, 0, v152
	v_mul_f32_e32 v143, 0xbfb8aa3b, v143
	s_waitcnt lgkmcnt(1)
	v_add_f32_dpp v186, v186, v186 row_shr:8 row_mask:0xf bank_mask:0xf
	s_waitcnt lgkmcnt(1)
	v_add_f32_e32 v183, 0, v178
	v_exp_f32_e32 v178, v143
	v_mul_f32_e32 v143, 0xbfb8aa3b, v152
	v_exp_f32_e32 v179, v143
	v_add_f32_dpp v187, v187, v187 row_shr:8 row_mask:0xf bank_mask:0xf
	v_mov_b32_dpp v191, v186 row_newbcast:15 row_mask:0xf bank_mask:0xf
	v_add_f32_e32 v186, v186, v182
	v_mov_b32_dpp v197, v187 row_newbcast:15 row_mask:0xf bank_mask:0xf
	v_add_f32_e32 v187, v187, v183
	v_mul_f32_e32 v143, 0xbfb8aa3b, v126
	s_waitcnt lgkmcnt(1)
	v_add_f32_e32 v199, v182, v191
	v_mul_f32_e32 v182, 0xbfb8aa3b, v186
	v_cndmask_b32_e64 v186, 0, 32, vcc
	v_ldexp_f32 v186, v184, v186
	v_log_f32_e32 v186, v186
	v_add_f32_e32 v201, v183, v197
	v_mul_f32_e32 v183, 0xbfb8aa3b, v187
	v_exp_f32_e32 v182, v182
	v_mul_f32_e32 v187, 0x3f317217, v186
	v_fma_f32 v187, v186, s96, -v187
	v_fmac_f32_e32 v187, 0x3377d1cf, v186
	v_fmac_f32_e32 v187, 0x3f317217, v186
	v_cmp_lt_f32_e64 s[14:15], |v186|, s1
	v_exp_f32_e32 v183, v183
	v_exp_f32_e32 v143, v143
	v_cndmask_b32_e64 v186, v186, v187, s[14:15]
	v_cndmask_b32_e32 v187, 0, v223, vcc
	v_cmp_gt_f32_e32 vcc, s47, v185
	v_sub_f32_e32 v186, v186, v187
	v_pk_mul_f32 v[214:215], v[180:181], v[182:183]
	v_cndmask_b32_e64 v187, 0, 32, vcc
	v_ldexp_f32 v187, v185, v187
	v_log_f32_e32 v187, v187
	v_mul_f32_e32 v181, 0xbfb8aa3b, v110
	v_add_f32_e32 v143, 1.0, v143
	v_exp_f32_e32 v181, v181
	v_mul_f32_e32 v203, 0x3f317217, v187
	v_fma_f32 v203, v187, s96, -v203
	v_fmac_f32_e32 v203, 0x3377d1cf, v187
	v_fmac_f32_e32 v203, 0x3f317217, v187
	v_cmp_lt_f32_e64 s[14:15], |v187|, s1
	v_pk_mul_f32 v[212:213], v[176:177], v[178:179]
	v_rcp_f32_e32 v176, v178
	v_cndmask_b32_e64 v187, v187, v203, s[14:15]
	v_cndmask_b32_e32 v203, 0, v223, vcc
	v_cmp_gt_f32_e32 vcc, s47, v210
	v_sub_f32_e32 v187, v187, v203
	v_cndmask_b32_e64 v218, 0, 32, vcc
	v_ldexp_f32 v218, v210, v218
	v_log_f32_e32 v218, v218
	v_rcp_f32_e32 v178, v143
	v_add_f32_dpp v186, v186, v186 row_shr:1 row_mask:0xf bank_mask:0xf
	v_mul_f32_e32 v219, 0x3f317217, v218
	v_fma_f32 v219, v218, s96, -v219
	v_fmac_f32_e32 v219, 0x3377d1cf, v218
	v_fmac_f32_e32 v219, 0x3f317217, v218
	v_cmp_lt_f32_e64 s[14:15], |v218|, s1
	v_mul_f32_e32 v143, 0xbfb8aa3b, v127
	v_cndmask_b32_e64 v218, v218, v219, s[14:15]
	v_cndmask_b32_e32 v219, 0, v223, vcc
	v_cmp_gt_f32_e32 vcc, s47, v211
	v_sub_f32_e32 v218, v218, v219
	v_cndmask_b32_e64 v219, 0, 32, vcc
	v_ldexp_f32 v219, v211, v219
	v_log_f32_e32 v219, v219
	v_add_f32_dpp v187, v187, v187 row_shr:1 row_mask:0xf bank_mask:0xf
	v_exp_f32_e32 v143, v143
	v_mul_f32_e32 v220, 0x3f317217, v219
	v_fma_f32 v220, v219, s96, -v220
	v_fmac_f32_e32 v220, 0x3377d1cf, v219
	v_fmac_f32_e32 v220, 0x3f317217, v219
	v_cmp_lt_f32_e64 s[14:15], |v219|, s1
	v_add_f32_dpp v186, v186, v186 row_shr:2 row_mask:0xf bank_mask:0xf
	v_cndmask_b32_e64 v219, v219, v220, s[14:15]
	v_cndmask_b32_e32 v220, 0, v223, vcc
	v_sub_f32_e32 v219, v219, v220
	v_pk_add_f32 v[184:185], v[184:185], 1.0 op_sel_hi:[1,0] neg_lo:[1,0] neg_hi:[1,0]
	v_add_f32_e32 v181, 1.0, v181
	v_rcp_f32_e32 v180, v182
	s_waitcnt lgkmcnt(1)
	v_add_f32_dpp v218, v218, v218 row_shr:1 row_mask:0xf bank_mask:0xf
	s_waitcnt lgkmcnt(1)
	v_add_f32_dpp v187, v187, v187 row_shr:2 row_mask:0xf bank_mask:0xf
	v_rcp_f32_e32 v182, v181
	s_waitcnt lgkmcnt(1)
	v_add_f32_dpp v219, v219, v219 row_shr:1 row_mask:0xf bank_mask:0xf
	s_waitcnt lgkmcnt(1)
	v_add_f32_dpp v186, v186, v186 row_shr:4 row_mask:0xf bank_mask:0xf
	v_rcp_f32_e32 v181, v183
	s_waitcnt lgkmcnt(1)
	v_add_f32_dpp v218, v218, v218 row_shr:2 row_mask:0xf bank_mask:0xf
	s_waitcnt lgkmcnt(1)
	v_add_f32_dpp v187, v187, v187 row_shr:4 row_mask:0xf bank_mask:0xf
	v_mul_f32_e32 v183, 0xbfb8aa3b, v111
	s_waitcnt lgkmcnt(1)
	v_add_f32_dpp v219, v219, v219 row_shr:2 row_mask:0xf bank_mask:0xf
	s_waitcnt lgkmcnt(1)
	v_add_f32_dpp v186, v186, v186 row_shr:8 row_mask:0xf bank_mask:0xf
	v_add_f32_e32 v143, 1.0, v143
	s_waitcnt lgkmcnt(1)
	v_add_f32_dpp v218, v218, v218 row_shr:4 row_mask:0xf bank_mask:0xf
	s_waitcnt lgkmcnt(1)
	v_add_f32_dpp v187, v187, v187 row_shr:8 row_mask:0xf bank_mask:0xf
	v_mov_b32_dpp v203, v186 row_newbcast:15 row_mask:0xf bank_mask:0xf
	s_nop 1
	v_mov_b32_dpp v205, v187 row_newbcast:15 row_mask:0xf bank_mask:0xf
	s_waitcnt lgkmcnt(2)
	v_add_f32_dpp v219, v219, v219 row_shr:4 row_mask:0xf bank_mask:0xf
	v_add_f32_e32 v186, v186, v199
	v_add_f32_e32 v187, v187, v201
	v_mul_f32_e32 v186, 0xbfb8aa3b, v186
	v_mul_f32_e32 v187, 0xbfb8aa3b, v187
	v_add_f32_dpp v218, v218, v218 row_shr:8 row_mask:0xf bank_mask:0xf
	v_exp_f32_e32 v186, v186
	v_exp_f32_e32 v187, v187
	v_add_f32_e32 v199, v199, v203
	v_add_f32_e32 v238, v218, v199
	v_add_f32_dpp v219, v219, v219 row_shr:8 row_mask:0xf bank_mask:0xf
	v_mov_b32_dpp v220, v218 row_newbcast:15 row_mask:0xf bank_mask:0xf
	s_nop 1
	v_mov_b32_dpp v221, v219 row_newbcast:15 row_mask:0xf bank_mask:0xf
	v_pk_mul_f32 v[216:217], v[184:185], v[186:187]
	v_mul_f32_e32 v185, 0xbfb8aa3b, v94
	v_exp_f32_e32 v185, v185
	s_waitcnt lgkmcnt(1)
	v_add_f32_e32 v199, v199, v220
	v_exp_f32_e32 v183, v183
	v_add_f32_e32 v201, v201, v205
	v_mul_f32_e32 v199, 0x3fb8aa3b, v199
	v_rcp_f32_e32 v177, v179
	v_rcp_f32_e32 v179, v143
	v_add_f32_e32 v220, v219, v201
	v_add_f32_e32 v201, v201, v221
	v_exp_f32_e32 v218, v199
	v_add_f32_e32 v185, 1.0, v185
	v_mul_f32_e32 v199, 0x3fb8aa3b, v201
	v_rcp_f32_e32 v184, v186
	v_rcp_f32_e32 v186, v185
	v_rcp_f32_e32 v185, v187
	v_mul_f32_e32 v187, 0xbfb8aa3b, v95
	v_exp_f32_e32 v219, v199
	v_add_f32_e32 v183, 1.0, v183
	v_exp_f32_e32 v187, v187
	v_pk_mul_f32 v[178:179], v[126:127], v[178:179]
	v_rcp_f32_e32 v183, v183
	v_mul_f32_e32 v199, v212, v218
	v_pk_mul_f32 v[176:177], v[178:179], v[176:177]
	v_cvt_pk_bf16_f32 v199, v199, s0
	v_cvt_pk_bf16_f32 v189, v176, v177
	v_lshl_add_u64 v[176:177], s[44:45], 0, v[208:209]
	v_lshl_add_u64 v[178:179], s[48:49], 0, v[208:209]
	global_store_short v[206:207], v199, off
	v_mul_f32_e32 v199, v213, v219
	v_lshl_add_u64 v[176:177], v[176:177], 0, s[88:89]
	v_lshlrev_b32_e32 v152, 1, v154
	v_lshl_add_u64 v[178:179], v[178:179], 0, s[88:89]
	v_add_f32_e32 v187, 1.0, v187
	v_cvt_pk_bf16_f32 v199, v199, s0
	v_cvt_pk_bf16_f32 v143, v212, v213
	v_lshl_add_u64 v[176:177], v[176:177], 0, v[152:153]
	v_lshl_add_u64 v[178:179], v[178:179], 0, v[152:153]
	v_pk_mul_f32 v[182:183], v[110:111], v[182:183]
	v_rcp_f32_e32 v187, v187
	global_store_short v[206:207], v199, off offset:128
	global_store_dwordx2 v[176:177], v[188:189], off
	global_store_dwordx2 v[178:179], v[142:143], off
	v_mul_f32_e32 v142, v214, v218
	v_pk_mul_f32 v[180:181], v[182:183], v[180:181]
	v_or_b32_e32 v182, 0x8000, v208
	v_mov_b32_e32 v183, v209
	v_cvt_pk_bf16_f32 v142, v142, s0
	v_cvt_pk_bf16_f32 v197, v180, v181
	v_lshl_add_u64 v[180:181], s[44:45], 0, v[182:183]
	v_lshl_add_u64 v[182:183], s[48:49], 0, v[182:183]
	global_store_short v[206:207], v142, off offset:32
	v_mul_f32_e32 v142, v215, v219
	v_lshl_add_u64 v[180:181], v[180:181], 0, s[88:89]
	v_lshl_add_u64 v[182:183], v[182:183], 0, s[88:89]
	v_cvt_pk_bf16_f32 v142, v142, s0
	v_cvt_pk_bf16_f32 v191, v214, v215
	v_lshl_add_u64 v[180:181], v[180:181], 0, v[152:153]
	v_lshl_add_u64 v[182:183], v[182:183], 0, v[152:153]
	v_pk_mul_f32 v[186:187], v[94:95], v[186:187]
	global_store_short v[206:207], v142, off offset:160
	global_store_dwordx2 v[180:181], v[196:197], off
	global_store_dwordx2 v[182:183], v[190:191], off
	v_mul_f32_e32 v142, v216, v218
	v_pk_mul_f32 v[184:185], v[186:187], v[184:185]
	v_or_b32_e32 v186, 0x10000, v208
	v_mov_b32_e32 v187, v209
	v_cvt_pk_bf16_f32 v142, v142, s0
	v_cvt_pk_bf16_f32 v205, v184, v185
	v_lshl_add_u64 v[184:185], s[44:45], 0, v[186:187]
	v_lshl_add_u64 v[186:187], s[48:49], 0, v[186:187]
	global_store_short v[206:207], v142, off offset:64
	v_mul_f32_e32 v142, v217, v219
	v_lshl_add_u64 v[184:185], v[184:185], 0, s[88:89]
	v_lshl_add_u64 v[186:187], v[186:187], 0, s[88:89]
	v_cvt_pk_bf16_f32 v142, v142, s0
	v_cvt_pk_bf16_f32 v203, v216, v217
	v_lshl_add_u64 v[184:185], v[184:185], 0, v[152:153]
	v_lshl_add_u64 v[186:187], v[186:187], 0, v[152:153]
	global_store_short v[206:207], v142, off offset:192
	global_store_dwordx2 v[184:185], v[204:205], off
	global_store_dwordx2 v[186:187], v[202:203], off
	v_mul_f32_e32 v142, 0xbfb8aa3b, v238
	v_mul_f32_e32 v143, 0xbfb8aa3b, v220
	v_exp_f32_e32 v142, v142
	v_exp_f32_e32 v143, v143
	v_pk_add_f32 v[210:211], v[210:211], 1.0 op_sel_hi:[1,0] neg_lo:[1,0] neg_hi:[1,0]
	v_mul_f32_e32 v191, 0xbfb8aa3b, v79
	v_exp_f32_e32 v191, v191
	v_pk_mul_f32 v[188:189], v[210:211], v[142:143]
	v_rcp_f32_e32 v142, v142
	v_mul_f32_e32 v190, v218, v188
	v_cvt_pk_bf16_f32 v190, v190, s0
	global_store_short v[206:207], v190, off offset:96
	v_mul_f32_e32 v190, v219, v189
	v_cvt_pk_bf16_f32 v190, v190, s0
	global_store_short v[206:207], v190, off offset:224
	v_mul_f32_e32 v190, 0xbfb8aa3b, v78
	v_exp_f32_e32 v190, v190
	v_add_f32_e32 v191, 1.0, v191
	v_rcp_f32_e32 v191, v191
	v_rcp_f32_e32 v143, v143
	v_add_f32_e32 v190, 1.0, v190
	v_rcp_f32_e32 v190, v190
	v_or_b32_e32 v208, 0x18000, v208
	v_cvt_pk_bf16_f32 v199, v188, v189
	v_pk_mul_f32 v[190:191], v[78:79], v[190:191]
	s_nop 0
	v_pk_mul_f32 v[142:143], v[190:191], v[142:143]
	s_nop 0
	v_cvt_pk_bf16_f32 v201, v142, v143
	v_lshl_add_u64 v[142:143], s[44:45], 0, v[208:209]
	v_lshl_add_u64 v[142:143], v[142:143], 0, s[88:89]
	v_lshl_add_u64 v[188:189], v[142:143], 0, v[152:153]
	v_lshl_add_u64 v[142:143], s[48:49], 0, v[208:209]
	v_lshl_add_u64 v[142:143], v[142:143], 0, s[88:89]
	v_lshl_add_u64 v[190:191], v[142:143], 0, v[152:153]
	global_store_dwordx2 v[188:189], v[200:201], off
	global_store_dwordx2 v[190:191], v[198:199], off
	s_and_saveexec_b64 s[14:15], s[4:5]
	s_cbranch_execz .LBB0_1950
	s_add_u32 s28, s33, s94
	s_addc_u32 s29, s0, s95
	s_lshl_b64 vcc, s[86:87], 2
	s_add_u32 vcc_lo, s28, vcc_lo
	s_addc_u32 vcc_hi, s29, vcc_hi
	global_store_dwordx2 v237, v[218:219], vcc offset:8
.LBB0_1950:
	s_or_b64 exec, exec, s[14:15]
	v_sub_f32_e32 v128, v128, v132
	v_mul_f32_e32 v128, 0x3fb8aa3b, v128
	v_exp_f32_e32 v128, v128
	s_nop 0
	v_add_f32_e32 v128, 1.0, v128
	v_rcp_f32_e32 v132, v128
	v_sub_f32_e32 v128, v129, v133
	v_mul_f32_e32 v128, 0x3fb8aa3b, v128
	v_exp_f32_e32 v128, v128
	v_mov_b32_e32 v129, s85
	v_add_f32_e32 v128, 1.0, v128
	v_rcp_f32_e32 v133, v128
	v_mul_f32_e32 v128, 0xbfb8aa3b, v112
	v_exp_f32_e32 v128, v128
	v_pk_add_f32 v[142:143], v[132:133], 1.0 op_sel_hi:[1,0] neg_lo:[1,0] neg_hi:[1,0]
	v_add_f32_e32 v128, 1.0, v128
	v_rcp_f32_e32 v196, v128
	v_mul_f32_e32 v128, 0xbfb8aa3b, v113
	v_exp_f32_e32 v128, v128
	s_nop 0
	v_add_f32_e32 v128, 1.0, v128
	v_rcp_f32_e32 v197, v128
	v_mul_f32_e32 v128, 0xbfb8aa3b, v96
	v_exp_f32_e32 v128, v128
	v_pk_fma_f32 v[196:197], v[196:197], v[142:143], v[132:133]
	s_nop 0
	v_cmp_gt_f32_e32 vcc, s47, v196
	v_add_f32_e32 v128, 1.0, v128
	v_rcp_f32_e32 v202, v128
	v_cndmask_b32_e64 v198, 0, 32, vcc
	v_ldexp_f32 v198, v196, v198
	v_log_f32_e32 v198, v198
	v_mul_f32_e32 v128, 0xbfb8aa3b, v97
	v_exp_f32_e32 v128, v128
	v_mul_f32_e32 v199, 0x3f317217, v198
	v_fma_f32 v199, v198, s96, -v199
	v_fmac_f32_e32 v199, 0x3377d1cf, v198
	v_fmac_f32_e32 v199, 0x3f317217, v198
	v_cmp_lt_f32_e64 s[14:15], |v198|, s1
	v_add_f32_e32 v128, 1.0, v128
	v_rcp_f32_e32 v203, v128
	v_cndmask_b32_e64 v198, v198, v199, s[14:15]
	v_cndmask_b32_e32 v199, 0, v223, vcc
	v_cmp_gt_f32_e32 vcc, s47, v197
	v_sub_f32_e32 v198, v198, v199
	v_pk_fma_f32 v[202:203], v[202:203], v[142:143], v[132:133]
	v_cndmask_b32_e64 v199, 0, 32, vcc
	v_ldexp_f32 v199, v197, v199
	v_log_f32_e32 v199, v199
	v_mul_f32_e32 v128, 0xbfb8aa3b, v80
	v_exp_f32_e32 v128, v128
	v_pk_add_f32 v[196:197], v[196:197], 1.0 op_sel_hi:[1,0] neg_lo:[1,0] neg_hi:[1,0]
	v_mul_f32_e32 v204, 0x3f317217, v199
	v_fma_f32 v204, v199, s96, -v204
	v_fmac_f32_e32 v204, 0x3377d1cf, v199
	v_fmac_f32_e32 v204, 0x3f317217, v199
	v_cmp_lt_f32_e64 s[14:15], |v199|, s1
	v_add_f32_e32 v128, 1.0, v128
	v_rcp_f32_e32 v206, v128
	v_cndmask_b32_e64 v199, v199, v204, s[14:15]
	v_cndmask_b32_e32 v204, 0, v223, vcc
	v_sub_f32_e32 v199, v199, v204
	v_cmp_gt_f32_e32 vcc, s47, v202
	v_mul_f32_e32 v128, 0xbfb8aa3b, v81
	v_exp_f32_e32 v128, v128
	s_waitcnt lgkmcnt(0)
	v_add_f32_dpp v198, v198, v198 row_shr:1 row_mask:0xf bank_mask:0xf
	v_add_f32_e32 v128, 1.0, v128
	v_rcp_f32_e32 v207, v128
	v_mul_f32_e32 v128, 0xbfb8aa3b, v64
	v_exp_f32_e32 v128, v128
	v_add_f32_dpp v199, v199, v199 row_shr:1 row_mask:0xf bank_mask:0xf
	v_pk_fma_f32 v[206:207], v[206:207], v[142:143], v[132:133]
	v_add_f32_e32 v128, 1.0, v128
	v_rcp_f32_e32 v200, v128
	v_mul_f32_e32 v128, 0xbfb8aa3b, v65
	v_add_f32_dpp v198, v198, v198 row_shr:2 row_mask:0xf bank_mask:0xf
	v_exp_f32_e32 v128, v128
	v_add_f32_dpp v199, v199, v199 row_shr:2 row_mask:0xf bank_mask:0xf
	v_add_f32_e32 v128, 1.0, v128
	v_rcp_f32_e32 v201, v128
	v_or_b32_e32 v128, s67, v160
	v_lshlrev_b64 v[128:129], 7, v[128:129]
	v_add_f32_dpp v198, v198, v198 row_shr:4 row_mask:0xf bank_mask:0xf
	v_pk_fma_f32 v[200:201], v[200:201], v[142:143], v[132:133]
	v_lshl_add_u64 v[128:129], v[164:165], 0, v[128:129]
	v_add_f32_dpp v199, v199, v199 row_shr:4 row_mask:0xf bank_mask:0xf
	v_add_f32_dpp v198, v198, v198 row_shr:8 row_mask:0xf bank_mask:0xf
	s_nop 1
	v_add_f32_dpp v199, v199, v199 row_shr:8 row_mask:0xf bank_mask:0xf
	v_mov_b32_dpp v204, v198 row_newbcast:15 row_mask:0xf bank_mask:0xf
	v_add_f32_e32 v198, 0, v198
	v_mul_f32_e32 v198, 0xbfb8aa3b, v198
	v_exp_f32_e32 v198, v198
	v_add_f32_e32 v208, 0, v204
	v_mov_b32_dpp v204, v199 row_newbcast:15 row_mask:0xf bank_mask:0xf
	v_add_f32_e32 v199, 0, v199
	v_mul_f32_e32 v199, 0xbfb8aa3b, v199
	v_exp_f32_e32 v199, v199
	v_add_f32_e32 v209, 0, v204
	v_cndmask_b32_e64 v204, 0, 32, vcc
	v_ldexp_f32 v204, v202, v204
	v_log_f32_e32 v204, v204
	v_pk_mul_f32 v[196:197], v[196:197], v[198:199]
	v_mul_f32_e32 v205, 0x3f317217, v204
	v_fma_f32 v205, v204, s96, -v205
	v_fmac_f32_e32 v205, 0x3377d1cf, v204
	v_fmac_f32_e32 v205, 0x3f317217, v204
	v_cmp_lt_f32_e64 s[14:15], |v204|, s1
	s_nop 1
	v_cndmask_b32_e64 v204, v204, v205, s[14:15]
	v_cndmask_b32_e32 v205, 0, v223, vcc
	v_cmp_gt_f32_e32 vcc, s47, v203
	v_sub_f32_e32 v210, v204, v205
	s_nop 0
	v_cndmask_b32_e64 v204, 0, 32, vcc
	v_ldexp_f32 v204, v203, v204
	v_log_f32_e32 v204, v204
	s_nop 0
	v_mul_f32_e32 v205, 0x3f317217, v204
	v_fma_f32 v205, v204, s96, -v205
	v_fmac_f32_e32 v205, 0x3377d1cf, v204
	v_fmac_f32_e32 v205, 0x3f317217, v204
	v_cmp_lt_f32_e64 s[14:15], |v204|, s1
	s_nop 1
	v_cndmask_b32_e64 v204, v204, v205, s[14:15]
	v_cndmask_b32_e32 v205, 0, v223, vcc
	v_sub_f32_e32 v211, v204, v205
	v_pk_add_f32 v[204:205], v[202:203], 1.0 op_sel_hi:[1,0] neg_lo:[1,0] neg_hi:[1,0]
	v_cmp_gt_f32_e32 vcc, s47, v206
	s_waitcnt lgkmcnt(1)
	v_mov_b32_e32 v202, v210
	s_nop 1
	v_add_f32_dpp v202, v210, v210 row_shr:1 row_mask:0xf bank_mask:0xf
	s_waitcnt lgkmcnt(1)
	v_mov_b32_e32 v203, v211
	s_nop 1
	v_add_f32_dpp v203, v211, v211 row_shr:1 row_mask:0xf bank_mask:0xf
	v_add_f32_dpp v202, v202, v202 row_shr:2 row_mask:0xf bank_mask:0xf
	s_nop 1
	v_add_f32_dpp v203, v203, v203 row_shr:2 row_mask:0xf bank_mask:0xf
	v_add_f32_dpp v202, v202, v202 row_shr:4 row_mask:0xf bank_mask:0xf
	s_nop 1
	v_add_f32_dpp v203, v203, v203 row_shr:4 row_mask:0xf bank_mask:0xf
	v_add_f32_dpp v202, v202, v202 row_shr:8 row_mask:0xf bank_mask:0xf
	s_nop 1
	v_add_f32_dpp v203, v203, v203 row_shr:8 row_mask:0xf bank_mask:0xf
	v_mov_b32_dpp v210, v202 row_newbcast:15 row_mask:0xf bank_mask:0xf
	v_add_f32_e32 v202, v202, v208
	v_mov_b32_dpp v211, v203 row_newbcast:15 row_mask:0xf bank_mask:0xf
	v_add_f32_e32 v203, v203, v209
	v_mul_f32_e32 v202, 0xbfb8aa3b, v202
	s_waitcnt lgkmcnt(1)
	v_add_f32_e32 v208, v208, v210
	v_cndmask_b32_e64 v210, 0, 32, vcc
	v_ldexp_f32 v210, v206, v210
	v_log_f32_e32 v210, v210
	v_add_f32_e32 v209, v209, v211
	v_mul_f32_e32 v203, 0xbfb8aa3b, v203
	v_exp_f32_e32 v202, v202
	v_mul_f32_e32 v211, 0x3f317217, v210
	v_fma_f32 v211, v210, s96, -v211
	v_fmac_f32_e32 v211, 0x3377d1cf, v210
	v_fmac_f32_e32 v211, 0x3f317217, v210
	v_cmp_lt_f32_e64 s[14:15], |v210|, s1
	v_exp_f32_e32 v203, v203
	s_nop 0
	v_cndmask_b32_e64 v210, v210, v211, s[14:15]
	v_cndmask_b32_e32 v211, 0, v223, vcc
	v_cmp_gt_f32_e32 vcc, s47, v207
	v_sub_f32_e32 v210, v210, v211
	v_pk_mul_f32 v[204:205], v[204:205], v[202:203]
	v_cndmask_b32_e64 v211, 0, 32, vcc
	v_ldexp_f32 v211, v207, v211
	v_log_f32_e32 v211, v211
	v_pk_add_f32 v[206:207], v[206:207], 1.0 op_sel_hi:[1,0] neg_lo:[1,0] neg_hi:[1,0]
	v_mul_f32_e32 v212, 0x3f317217, v211
	v_fma_f32 v212, v211, s96, -v212
	v_fmac_f32_e32 v212, 0x3377d1cf, v211
	v_fmac_f32_e32 v212, 0x3f317217, v211
	v_cmp_lt_f32_e64 s[14:15], |v211|, s1
	s_nop 1
	v_cndmask_b32_e64 v211, v211, v212, s[14:15]
	v_cndmask_b32_e32 v212, 0, v223, vcc
	v_sub_f32_e32 v211, v211, v212
	v_cmp_gt_f32_e32 vcc, s47, v200
	v_add_f32_dpp v210, v210, v210 row_shr:1 row_mask:0xf bank_mask:0xf
	v_add_f32_dpp v211, v211, v211 row_shr:1 row_mask:0xf bank_mask:0xf
	s_nop 1
	v_add_f32_dpp v210, v210, v210 row_shr:2 row_mask:0xf bank_mask:0xf
	v_add_f32_dpp v211, v211, v211 row_shr:2 row_mask:0xf bank_mask:0xf
	s_nop 1
	v_add_f32_dpp v210, v210, v210 row_shr:4 row_mask:0xf bank_mask:0xf
	v_add_f32_dpp v211, v211, v211 row_shr:4 row_mask:0xf bank_mask:0xf
	s_nop 1
	v_add_f32_dpp v210, v210, v210 row_shr:8 row_mask:0xf bank_mask:0xf
	v_add_f32_dpp v211, v211, v211 row_shr:8 row_mask:0xf bank_mask:0xf
	s_nop 1
	v_mov_b32_dpp v212, v210 row_newbcast:15 row_mask:0xf bank_mask:0xf
	v_add_f32_e32 v210, v210, v208
	v_mov_b32_dpp v213, v211 row_newbcast:15 row_mask:0xf bank_mask:0xf
	v_add_f32_e32 v211, v211, v209
	s_waitcnt lgkmcnt(1)
	v_add_f32_e32 v212, v208, v212
	v_mul_f32_e32 v208, 0xbfb8aa3b, v210
	v_cndmask_b32_e64 v210, 0, 32, vcc
	v_ldexp_f32 v210, v200, v210
	v_log_f32_e32 v210, v210
	v_add_f32_e32 v213, v209, v213
	v_mul_f32_e32 v209, 0xbfb8aa3b, v211
	v_exp_f32_e32 v208, v208
	v_mul_f32_e32 v211, 0x3f317217, v210
	v_fma_f32 v211, v210, s96, -v211
	v_fmac_f32_e32 v211, 0x3377d1cf, v210
	v_fmac_f32_e32 v211, 0x3f317217, v210
	v_cmp_lt_f32_e64 s[14:15], |v210|, s1
	v_exp_f32_e32 v209, v209
	s_nop 0
	v_cndmask_b32_e64 v210, v210, v211, s[14:15]
	v_cndmask_b32_e32 v211, 0, v223, vcc
	v_cmp_gt_f32_e32 vcc, s47, v201
	v_sub_f32_e32 v210, v210, v211
	v_pk_mul_f32 v[206:207], v[206:207], v[208:209]
	v_cndmask_b32_e64 v211, 0, 32, vcc
	v_ldexp_f32 v211, v201, v211
	v_log_f32_e32 v211, v211
	v_pk_add_f32 v[200:201], v[200:201], 1.0 op_sel_hi:[1,0] neg_lo:[1,0] neg_hi:[1,0]
	v_mul_f32_e32 v214, 0x3f317217, v211
	v_fma_f32 v214, v211, s96, -v214
	v_fmac_f32_e32 v214, 0x3377d1cf, v211
	v_fmac_f32_e32 v214, 0x3f317217, v211
	v_cmp_lt_f32_e64 s[14:15], |v211|, s1
	s_nop 1
	v_cndmask_b32_e64 v211, v211, v214, s[14:15]
	v_cndmask_b32_e32 v214, 0, v223, vcc
	v_sub_f32_e32 v211, v211, v214
	v_add_f32_dpp v210, v210, v210 row_shr:1 row_mask:0xf bank_mask:0xf
	s_nop 1
	v_add_f32_dpp v211, v211, v211 row_shr:1 row_mask:0xf bank_mask:0xf
	v_add_f32_dpp v210, v210, v210 row_shr:2 row_mask:0xf bank_mask:0xf
	s_nop 1
	v_add_f32_dpp v211, v211, v211 row_shr:2 row_mask:0xf bank_mask:0xf
	v_add_f32_dpp v210, v210, v210 row_shr:4 row_mask:0xf bank_mask:0xf
	s_nop 1
	v_add_f32_dpp v211, v211, v211 row_shr:4 row_mask:0xf bank_mask:0xf
	v_add_f32_dpp v210, v210, v210 row_shr:8 row_mask:0xf bank_mask:0xf
	v_add_f32_e32 v216, v210, v212
	v_add_f32_dpp v211, v211, v211 row_shr:8 row_mask:0xf bank_mask:0xf
	v_mov_b32_dpp v214, v210 row_newbcast:15 row_mask:0xf bank_mask:0xf
	s_nop 1
	v_mov_b32_dpp v215, v211 row_newbcast:15 row_mask:0xf bank_mask:0xf
	s_waitcnt lgkmcnt(1)
	v_add_f32_e32 v210, v212, v214
	v_mul_f32_e32 v210, 0x3fb8aa3b, v210
	v_add_f32_e32 v212, v211, v213
	v_add_f32_e32 v211, v213, v215
	v_exp_f32_e32 v210, v210
	v_mul_f32_e32 v211, 0x3fb8aa3b, v211
	v_exp_f32_e32 v211, v211
	v_mul_f32_e32 v212, 0xbfb8aa3b, v212
	v_mul_f32_e32 v213, v196, v210
	v_cvt_pk_bf16_f32 v213, v213, s0
	global_store_short v[128:129], v213, off
	v_mul_f32_e32 v213, v197, v211
	v_cvt_pk_bf16_f32 v213, v213, s0
	global_store_short v[128:129], v213, off offset:128
	v_mul_f32_e32 v213, v204, v210
	v_cvt_pk_bf16_f32 v213, v213, s0
	global_store_short v[128:129], v213, off offset:32
	v_mul_f32_e32 v213, v205, v211
	v_cvt_pk_bf16_f32 v213, v213, s0
	global_store_short v[128:129], v213, off offset:160
	v_mul_f32_e32 v213, v206, v210
	v_cvt_pk_bf16_f32 v213, v213, s0
	global_store_short v[128:129], v213, off offset:64
	v_mul_f32_e32 v213, v207, v211
	v_cvt_pk_bf16_f32 v213, v213, s0
	global_store_short v[128:129], v213, off offset:192
	v_mul_f32_e32 v213, 0xbfb8aa3b, v216
	v_exp_f32_e32 v214, v213
	v_exp_f32_e32 v215, v212
	s_nop 0
	v_pk_mul_f32 v[212:213], v[200:201], v[214:215]
	s_nop 0
	v_mul_f32_e32 v200, v210, v212
	v_cvt_pk_bf16_f32 v200, v200, s0
	global_store_short v[128:129], v200, off offset:96
	v_mul_f32_e32 v200, v211, v213
	v_cvt_pk_bf16_f32 v200, v200, s0
	global_store_short v[128:129], v200, off offset:224
	s_and_saveexec_b64 s[14:15], s[4:5]
	s_cbranch_execz .LBB0_1952
	s_add_u32 s28, s33, s94
	s_addc_u32 s29, s0, s95
	s_lshl_b64 vcc, s[86:87], 2
	s_add_u32 vcc_lo, s28, vcc_lo
	s_addc_u32 vcc_hi, s29, vcc_hi
	global_store_dwordx2 v237, v[210:211], vcc offset:16
.LBB0_1952:
	s_or_b64 exec, exec, s[14:15]
	v_mul_f32_e32 v129, 0xbfb8aa3b, v120
	v_exp_f32_e32 v129, v129
	v_rcp_f32_e32 v128, v198
	v_cvt_pk_bf16_f32 v196, v196, v197
	v_mul_f32_e32 v197, 0xbfb8aa3b, v105
	v_add_f32_e32 v129, 1.0, v129
	v_rcp_f32_e32 v198, v129
	v_rcp_f32_e32 v129, v199
	v_mul_f32_e32 v199, 0xbfb8aa3b, v121
	v_exp_f32_e32 v199, v199
	v_exp_f32_e32 v197, v197
	v_add_f32_e32 v199, 1.0, v199
	v_rcp_f32_e32 v199, v199
	v_add_f32_e32 v197, 1.0, v197
	v_rcp_f32_e32 v201, v197
	v_mul_f32_e32 v197, 0xbfb8aa3b, v89
	v_pk_mul_f32 v[198:199], v[120:121], v[198:199]
	v_exp_f32_e32 v197, v197
	v_pk_mul_f32 v[128:129], v[198:199], v[128:129]
	v_add_f32_e32 v197, 1.0, v197
	v_cvt_pk_bf16_f32 v198, v128, v129
	v_mul_f32_e32 v129, 0xbfb8aa3b, v104
	v_exp_f32_e32 v129, v129
	v_rcp_f32_e32 v128, v202
	v_add_f32_e32 v129, 1.0, v129
	v_rcp_f32_e32 v200, v129
	v_rcp_f32_e32 v129, v203
	v_pk_mul_f32 v[200:201], v[104:105], v[200:201]
	s_nop 0
	v_pk_mul_f32 v[128:129], v[200:201], v[128:129]
	v_cvt_pk_bf16_f32 v200, v204, v205
	v_cvt_pk_bf16_f32 v202, v128, v129
	v_mul_f32_e32 v129, 0xbfb8aa3b, v88
	v_exp_f32_e32 v129, v129
	v_rcp_f32_e32 v205, v197
	v_rcp_f32_e32 v128, v208
	v_mul_f32_e32 v197, 0xbfb8aa3b, v73
	v_add_f32_e32 v129, 1.0, v129
	v_rcp_f32_e32 v204, v129
	v_rcp_f32_e32 v129, v209
	v_exp_f32_e32 v197, v197
	v_cvt_pk_bf16_f32 v208, v206, v207
	v_pk_mul_f32 v[204:205], v[88:89], v[204:205]
	v_add_f32_e32 v197, 1.0, v197
	v_pk_mul_f32 v[128:129], v[204:205], v[128:129]
	v_rcp_f32_e32 v205, v197
	v_cvt_pk_bf16_f32 v210, v128, v129
	v_mul_f32_e32 v129, 0xbfb8aa3b, v72
	v_exp_f32_e32 v129, v129
	v_rcp_f32_e32 v128, v214
	v_add_f32_e32 v129, 1.0, v129
	v_rcp_f32_e32 v204, v129
	v_rcp_f32_e32 v129, v215
	v_pk_mul_f32 v[204:205], v[72:73], v[204:205]
	s_nop 0
	v_pk_mul_f32 v[128:129], v[204:205], v[128:129]
	v_cvt_pk_bf16_f32 v204, v212, v213
	v_cvt_pk_bf16_f32 v206, v128, v129
	v_sub_f32_e32 v128, v130, v134
	v_mul_f32_e32 v134, 0xbfb8aa3b, v114
	v_exp_f32_e32 v134, v134
	v_sub_f32_e32 v129, v131, v135
	v_mul_f32_e32 v128, 0x3fb8aa3b, v128
	v_mul_f32_e32 v129, 0x3fb8aa3b, v129
	v_add_f32_e32 v134, 1.0, v134
	v_exp_f32_e32 v128, v128
	v_exp_f32_e32 v129, v129
	v_rcp_f32_e32 v214, v134
	v_mul_f32_e32 v134, 0xbfb8aa3b, v115
	v_exp_f32_e32 v134, v134
	v_add_f32_e32 v128, 1.0, v128
	v_add_f32_e32 v129, 1.0, v129
	v_rcp_f32_e32 v128, v128
	v_rcp_f32_e32 v129, v129
	v_add_f32_e32 v134, 1.0, v134
	v_rcp_f32_e32 v215, v134
	v_mul_f32_e32 v134, 0xbfb8aa3b, v98
	v_pk_add_f32 v[130:131], v[128:129], 1.0 op_sel_hi:[1,0] neg_lo:[1,0] neg_hi:[1,0]
	v_exp_f32_e32 v134, v134
	v_pk_fma_f32 v[214:215], v[214:215], v[130:131], v[128:129]
	v_mov_b32_e32 v135, s85
	v_cmp_gt_f32_e32 vcc, s47, v214
	v_add_f32_e32 v134, 1.0, v134
	v_rcp_f32_e32 v218, v134
	v_cndmask_b32_e64 v197, 0, 32, vcc
	v_ldexp_f32 v197, v214, v197
	v_log_f32_e32 v197, v197
	v_mul_f32_e32 v134, 0xbfb8aa3b, v99
	v_exp_f32_e32 v134, v134
	v_mul_f32_e32 v199, 0x3f317217, v197
	v_fma_f32 v199, v197, s96, -v199
	v_fmac_f32_e32 v199, 0x3377d1cf, v197
	v_fmac_f32_e32 v199, 0x3f317217, v197
	v_cmp_lt_f32_e64 s[14:15], |v197|, s1
	v_add_f32_e32 v134, 1.0, v134
	v_rcp_f32_e32 v219, v134
	v_cndmask_b32_e64 v197, v197, v199, s[14:15]
	v_cndmask_b32_e32 v199, 0, v223, vcc
	v_cmp_gt_f32_e32 vcc, s47, v215
	v_sub_f32_e32 v197, v197, v199
	v_pk_fma_f32 v[218:219], v[218:219], v[130:131], v[128:129]
	v_cndmask_b32_e64 v199, 0, 32, vcc
	v_ldexp_f32 v199, v215, v199
	v_log_f32_e32 v199, v199
	v_mul_f32_e32 v134, 0xbfb8aa3b, v82
	v_exp_f32_e32 v134, v134
	v_pk_add_f32 v[214:215], v[214:215], 1.0 op_sel_hi:[1,0] neg_lo:[1,0] neg_hi:[1,0]
	v_mul_f32_e32 v201, 0x3f317217, v199
	v_fma_f32 v201, v199, s96, -v201
	v_fmac_f32_e32 v201, 0x3377d1cf, v199
	v_fmac_f32_e32 v201, 0x3f317217, v199
	v_cmp_lt_f32_e64 s[14:15], |v199|, s1
	v_add_f32_e32 v134, 1.0, v134
	v_rcp_f32_e32 v216, v134
	v_cndmask_b32_e64 v199, v199, v201, s[14:15]
	v_cndmask_b32_e32 v201, 0, v223, vcc
	v_cmp_gt_f32_e32 vcc, s47, v218
	v_sub_f32_e32 v199, v199, v201
	v_cndmask_b32_e64 v205, 0, 32, vcc
	v_ldexp_f32 v205, v218, v205
	v_log_f32_e32 v205, v205
	v_mul_f32_e32 v134, 0xbfb8aa3b, v83
	s_waitcnt lgkmcnt(0)
	v_add_f32_dpp v197, v197, v197 row_shr:1 row_mask:0xf bank_mask:0xf
	v_mul_f32_e32 v207, 0x3f317217, v205
	v_fma_f32 v207, v205, s96, -v207
	v_fmac_f32_e32 v207, 0x3377d1cf, v205
	v_fmac_f32_e32 v207, 0x3f317217, v205
	v_cmp_lt_f32_e64 s[14:15], |v205|, s1
	v_exp_f32_e32 v134, v134
	v_cndmask_b32_e64 v205, v205, v207, s[14:15]
	v_cndmask_b32_e32 v207, 0, v223, vcc
	v_cmp_gt_f32_e32 vcc, s47, v219
	v_sub_f32_e32 v205, v205, v207
	v_cndmask_b32_e64 v207, 0, 32, vcc
	v_ldexp_f32 v207, v219, v207
	v_log_f32_e32 v207, v207
	v_add_f32_dpp v199, v199, v199 row_shr:1 row_mask:0xf bank_mask:0xf
	v_add_f32_e32 v134, 1.0, v134
	v_mul_f32_e32 v209, 0x3f317217, v207
	v_fma_f32 v209, v207, s96, -v209
	v_fmac_f32_e32 v209, 0x3377d1cf, v207
	v_fmac_f32_e32 v209, 0x3f317217, v207
	v_cmp_lt_f32_e64 s[14:15], |v207|, s1
	v_add_f32_dpp v197, v197, v197 row_shr:2 row_mask:0xf bank_mask:0xf
	v_cndmask_b32_e64 v207, v207, v209, s[14:15]
	v_cndmask_b32_e32 v209, 0, v223, vcc
	v_sub_f32_e32 v207, v207, v209
	v_rcp_f32_e32 v217, v134
	v_pk_add_f32 v[218:219], v[218:219], 1.0 op_sel_hi:[1,0] neg_lo:[1,0] neg_hi:[1,0]
	v_mul_f32_e32 v134, 0xbfb8aa3b, v66
	s_waitcnt lgkmcnt(1)
	v_add_f32_dpp v205, v205, v205 row_shr:1 row_mask:0xf bank_mask:0xf
	s_waitcnt lgkmcnt(1)
	v_add_f32_dpp v199, v199, v199 row_shr:2 row_mask:0xf bank_mask:0xf
	v_pk_fma_f32 v[216:217], v[216:217], v[130:131], v[128:129]
	s_waitcnt lgkmcnt(1)
	v_add_f32_dpp v207, v207, v207 row_shr:1 row_mask:0xf bank_mask:0xf
	s_waitcnt lgkmcnt(1)
	v_add_f32_dpp v197, v197, v197 row_shr:4 row_mask:0xf bank_mask:0xf
	v_cmp_gt_f32_e32 vcc, s47, v216
	s_waitcnt lgkmcnt(1)
	v_add_f32_dpp v205, v205, v205 row_shr:2 row_mask:0xf bank_mask:0xf
	s_waitcnt lgkmcnt(1)
	v_add_f32_dpp v199, v199, v199 row_shr:4 row_mask:0xf bank_mask:0xf
	v_exp_f32_e32 v134, v134
	s_waitcnt lgkmcnt(1)
	v_add_f32_dpp v207, v207, v207 row_shr:2 row_mask:0xf bank_mask:0xf
	s_waitcnt lgkmcnt(1)
	v_add_f32_dpp v197, v197, v197 row_shr:8 row_mask:0xf bank_mask:0xf
	v_add_f32_e32 v134, 1.0, v134
	s_waitcnt lgkmcnt(1)
	v_add_f32_dpp v205, v205, v205 row_shr:4 row_mask:0xf bank_mask:0xf
	s_waitcnt lgkmcnt(1)
	v_add_f32_dpp v199, v199, v199 row_shr:8 row_mask:0xf bank_mask:0xf
	v_mov_b32_dpp v201, v197 row_newbcast:15 row_mask:0xf bank_mask:0xf
	v_add_f32_e32 v197, 0, v197
	v_mov_b32_dpp v203, v199 row_newbcast:15 row_mask:0xf bank_mask:0xf
	v_add_f32_e32 v199, 0, v199
	v_mul_f32_e32 v197, 0xbfb8aa3b, v197
	s_waitcnt lgkmcnt(2)
	v_exp_f32_e32 v220, v197
	v_mul_f32_e32 v197, 0xbfb8aa3b, v199
	v_add_f32_dpp v207, v207, v207 row_shr:4 row_mask:0xf bank_mask:0xf
	v_exp_f32_e32 v221, v197
	v_mul_f32_e32 v197, 0xbfb8aa3b, v122
	v_exp_f32_e32 v197, v197
	s_waitcnt lgkmcnt(2)
	v_add_f32_e32 v201, 0, v201
	v_add_f32_dpp v205, v205, v205 row_shr:8 row_mask:0xf bank_mask:0xf
	v_add_f32_e32 v197, 1.0, v197
	v_rcp_f32_e32 v238, v197
	v_mul_f32_e32 v197, 0xbfb8aa3b, v123
	v_exp_f32_e32 v197, v197
	v_pk_mul_f32 v[214:215], v[214:215], v[220:221]
	v_add_f32_dpp v207, v207, v207 row_shr:8 row_mask:0xf bank_mask:0xf
	v_add_f32_e32 v197, 1.0, v197
	v_mov_b32_dpp v209, v205 row_newbcast:15 row_mask:0xf bank_mask:0xf
	v_rcp_f32_e32 v239, v197
	v_rcp_f32_e32 v220, v220
	v_rcp_f32_e32 v221, v221
	v_mov_b32_dpp v211, v207 row_newbcast:15 row_mask:0xf bank_mask:0xf
	v_add_f32_e32 v203, 0, v203
	v_pk_mul_f32 v[238:239], v[122:123], v[238:239]
	v_add_f32_e32 v205, v205, v201
	s_waitcnt lgkmcnt(1)
	v_add_f32_e32 v209, v201, v209
	v_add_f32_e32 v201, v207, v203
	v_pk_mul_f32 v[220:221], v[238:239], v[220:221]
	v_mul_f32_e32 v201, 0xbfb8aa3b, v201
	v_cvt_pk_bf16_f32 v199, v220, v221
	v_exp_f32_e32 v221, v201
	v_mul_f32_e32 v201, 0xbfb8aa3b, v106
	v_add_f32_e32 v207, v203, v211
	v_mul_f32_e32 v203, 0xbfb8aa3b, v205
	v_exp_f32_e32 v201, v201
	v_cndmask_b32_e64 v205, 0, 32, vcc
	v_ldexp_f32 v205, v216, v205
	v_log_f32_e32 v205, v205
	v_add_f32_e32 v201, 1.0, v201
	v_rcp_f32_e32 v238, v201
	v_mul_f32_e32 v201, 0xbfb8aa3b, v107
	v_exp_f32_e32 v201, v201
	v_mul_f32_e32 v211, 0x3f317217, v205
	v_fma_f32 v211, v205, s96, -v211
	v_exp_f32_e32 v220, v203
	v_fmac_f32_e32 v211, 0x3377d1cf, v205
	v_fmac_f32_e32 v211, 0x3f317217, v205
	v_cmp_lt_f32_e64 s[14:15], |v205|, s1
	v_add_f32_e32 v201, 1.0, v201
	v_rcp_f32_e32 v239, v201
	v_cndmask_b32_e64 v205, v205, v211, s[14:15]
	v_cndmask_b32_e32 v211, 0, v223, vcc
	v_cmp_gt_f32_e32 vcc, s47, v217
	v_sub_f32_e32 v205, v205, v211
	v_pk_mul_f32 v[218:219], v[218:219], v[220:221]
	v_cndmask_b32_e64 v211, 0, 32, vcc
	v_rcp_f32_e32 v220, v220
	v_rcp_f32_e32 v221, v221
	v_ldexp_f32 v211, v217, v211
	v_log_f32_e32 v211, v211
	v_pk_mul_f32 v[238:239], v[106:107], v[238:239]
	v_rcp_f32_e32 v212, v134
	v_pk_mul_f32 v[220:221], v[238:239], v[220:221]
	v_cmp_lt_f32_e64 s[14:15], |v211|, s1
	v_cvt_pk_bf16_f32 v203, v220, v221
	v_mul_f32_e32 v220, 0x3f317217, v211
	v_fma_f32 v220, v211, s96, -v220
	v_fmac_f32_e32 v220, 0x3377d1cf, v211
	v_fmac_f32_e32 v220, 0x3f317217, v211
	v_cndmask_b32_e64 v211, v211, v220, s[14:15]
	v_cndmask_b32_e32 v220, 0, v223, vcc
	v_sub_f32_e32 v211, v211, v220
	v_mul_f32_e32 v134, 0xbfb8aa3b, v67
	v_exp_f32_e32 v134, v134
	v_pk_add_f32 v[216:217], v[216:217], 1.0 op_sel_hi:[1,0] neg_lo:[1,0] neg_hi:[1,0]
	v_cvt_pk_bf16_f32 v197, v214, v215
	v_add_f32_dpp v205, v205, v205 row_shr:1 row_mask:0xf bank_mask:0xf
	v_add_f32_e32 v134, 1.0, v134
	v_rcp_f32_e32 v213, v134
	v_or_b32_e32 v134, s67, v162
	v_lshlrev_b64 v[134:135], 7, v[134:135]
	v_add_f32_dpp v211, v211, v211 row_shr:1 row_mask:0xf bank_mask:0xf
	v_pk_fma_f32 v[212:213], v[212:213], v[130:131], v[128:129]
	v_lshl_add_u64 v[134:135], v[164:165], 0, v[134:135]
	v_cmp_gt_f32_e32 vcc, s47, v212
	v_cvt_pk_bf16_f32 v201, v218, v219
	v_add_f32_dpp v205, v205, v205 row_shr:2 row_mask:0xf bank_mask:0xf
	v_add_f32_dpp v211, v211, v211 row_shr:2 row_mask:0xf bank_mask:0xf
	s_nop 1
	v_add_f32_dpp v205, v205, v205 row_shr:4 row_mask:0xf bank_mask:0xf
	v_add_f32_dpp v211, v211, v211 row_shr:4 row_mask:0xf bank_mask:0xf
	s_nop 1
	v_add_f32_dpp v205, v205, v205 row_shr:8 row_mask:0xf bank_mask:0xf
	v_add_f32_dpp v211, v211, v211 row_shr:8 row_mask:0xf bank_mask:0xf
	s_nop 1
	v_mov_b32_dpp v220, v205 row_newbcast:15 row_mask:0xf bank_mask:0xf
	v_mov_b32_dpp v221, v211 row_newbcast:15 row_mask:0xf bank_mask:0xf
	v_add_f32_e32 v205, v205, v209
	v_mul_f32_e32 v205, 0xbfb8aa3b, v205
	s_waitcnt lgkmcnt(1)
	v_add_f32_e32 v240, v209, v220
	v_add_f32_e32 v209, v211, v207
	v_exp_f32_e32 v220, v205
	v_mul_f32_e32 v205, 0xbfb8aa3b, v209
	v_add_f32_e32 v207, v207, v221
	v_exp_f32_e32 v221, v205
	v_mul_f32_e32 v205, 0xbfb8aa3b, v90
	v_exp_f32_e32 v205, v205
	v_pk_mul_f32 v[216:217], v[216:217], v[220:221]
	v_rcp_f32_e32 v220, v220
	v_add_f32_e32 v205, 1.0, v205
	v_rcp_f32_e32 v238, v205
	v_mul_f32_e32 v205, 0xbfb8aa3b, v91
	v_exp_f32_e32 v205, v205
	v_rcp_f32_e32 v221, v221
	v_cvt_pk_bf16_f32 v209, v216, v217
	v_add_f32_e32 v205, 1.0, v205
	v_rcp_f32_e32 v239, v205
	v_cndmask_b32_e64 v205, 0, 32, vcc
	v_ldexp_f32 v205, v212, v205
	v_log_f32_e32 v205, v205
	v_pk_mul_f32 v[238:239], v[90:91], v[238:239]
	v_cmp_lt_f32_e64 s[14:15], |v205|, s1
	v_pk_mul_f32 v[220:221], v[238:239], v[220:221]
	s_nop 0
	v_cvt_pk_bf16_f32 v211, v220, v221
	v_mul_f32_e32 v220, 0x3f317217, v205
	v_fma_f32 v220, v205, s96, -v220
	v_fmac_f32_e32 v220, 0x3377d1cf, v205
	v_fmac_f32_e32 v220, 0x3f317217, v205
	v_cndmask_b32_e64 v205, v205, v220, s[14:15]
	v_cndmask_b32_e32 v220, 0, v223, vcc
	v_cmp_gt_f32_e32 vcc, s47, v213
	v_sub_f32_e32 v205, v205, v220
	s_nop 0
	v_cndmask_b32_e64 v220, 0, 32, vcc
	v_ldexp_f32 v220, v213, v220
	v_log_f32_e32 v220, v220
	v_pk_add_f32 v[212:213], v[212:213], 1.0 op_sel_hi:[1,0] neg_lo:[1,0] neg_hi:[1,0]
	v_mul_f32_e32 v221, 0x3f317217, v220
	v_fma_f32 v221, v220, s96, -v221
	v_fmac_f32_e32 v221, 0x3377d1cf, v220
	v_fmac_f32_e32 v221, 0x3f317217, v220
	v_cmp_lt_f32_e64 s[14:15], |v220|, s1
	s_nop 1
	v_cndmask_b32_e64 v220, v220, v221, s[14:15]
	v_cndmask_b32_e32 v221, 0, v223, vcc
	v_sub_f32_e32 v220, v220, v221
	v_add_f32_dpp v205, v205, v205 row_shr:1 row_mask:0xf bank_mask:0xf
	s_nop 1
	v_add_f32_dpp v220, v220, v220 row_shr:1 row_mask:0xf bank_mask:0xf
	v_add_f32_dpp v205, v205, v205 row_shr:2 row_mask:0xf bank_mask:0xf
	s_nop 1
	v_add_f32_dpp v220, v220, v220 row_shr:2 row_mask:0xf bank_mask:0xf
	v_add_f32_dpp v205, v205, v205 row_shr:4 row_mask:0xf bank_mask:0xf
	s_nop 1
	v_add_f32_dpp v220, v220, v220 row_shr:4 row_mask:0xf bank_mask:0xf
	v_add_f32_dpp v205, v205, v205 row_shr:8 row_mask:0xf bank_mask:0xf
	s_nop 1
	v_add_f32_dpp v220, v220, v220 row_shr:8 row_mask:0xf bank_mask:0xf
	v_mov_b32_dpp v221, v205 row_newbcast:15 row_mask:0xf bank_mask:0xf
	s_nop 1
	v_mov_b32_dpp v238, v220 row_newbcast:15 row_mask:0xf bank_mask:0xf
	v_add_f32_e32 v239, v220, v207
	v_add_f32_e32 v205, v205, v240
	s_waitcnt lgkmcnt(1)
	v_add_f32_e32 v221, v240, v221
	v_mul_f32_e32 v220, 0x3fb8aa3b, v221
	v_add_f32_e32 v207, v207, v238
	v_exp_f32_e32 v220, v220
	v_mul_f32_e32 v207, 0x3fb8aa3b, v207
	v_exp_f32_e32 v221, v207
	v_mul_f32_e32 v207, v214, v220
	v_cvt_pk_bf16_f32 v207, v207, s0
	global_store_short v[134:135], v207, off
	v_mul_f32_e32 v207, v215, v221
	v_cvt_pk_bf16_f32 v207, v207, s0
	global_store_short v[134:135], v207, off offset:128
	global_store_dwordx2 v[176:177], v[198:199], off offset:8
	global_store_dwordx2 v[178:179], v[196:197], off offset:8
	v_mul_f32_e32 v176, v218, v220
	v_cvt_pk_bf16_f32 v176, v176, s0
	global_store_short v[134:135], v176, off offset:32
	v_mul_f32_e32 v176, v219, v221
	v_cvt_pk_bf16_f32 v176, v176, s0
	global_store_short v[134:135], v176, off offset:160
	global_store_dwordx2 v[180:181], v[202:203], off offset:8
	global_store_dwordx2 v[182:183], v[200:201], off offset:8
	v_mul_f32_e32 v176, v216, v220
	v_cvt_pk_bf16_f32 v176, v176, s0
	global_store_short v[134:135], v176, off offset:64
	v_mul_f32_e32 v176, v217, v221
	v_cvt_pk_bf16_f32 v176, v176, s0
	global_store_short v[134:135], v176, off offset:192
	global_store_dwordx2 v[184:185], v[210:211], off offset:8
	global_store_dwordx2 v[186:187], v[208:209], off offset:8
	v_mul_f32_e32 v176, 0xbfb8aa3b, v205
	v_mul_f32_e32 v177, 0xbfb8aa3b, v239
	v_exp_f32_e32 v176, v176
	v_exp_f32_e32 v177, v177
	s_nop 0
	v_pk_mul_f32 v[178:179], v[212:213], v[176:177]
	s_nop 0
	v_mul_f32_e32 v180, v220, v178
	v_cvt_pk_bf16_f32 v180, v180, s0
	global_store_short v[134:135], v180, off offset:96
	v_mul_f32_e32 v180, v221, v179
	v_cvt_pk_bf16_f32 v180, v180, s0
	global_store_short v[134:135], v180, off offset:224
	v_mul_f32_e32 v135, 0xbfb8aa3b, v74
	v_exp_f32_e32 v135, v135
	v_rcp_f32_e32 v134, v176
	v_cvt_pk_bf16_f32 v205, v178, v179
	v_add_f32_e32 v135, 1.0, v135
	v_rcp_f32_e32 v176, v135
	v_rcp_f32_e32 v135, v177
	v_mul_f32_e32 v177, 0xbfb8aa3b, v75
	v_exp_f32_e32 v177, v177
	s_nop 0
	v_add_f32_e32 v177, 1.0, v177
	v_rcp_f32_e32 v177, v177
	s_nop 0
	v_pk_mul_f32 v[176:177], v[74:75], v[176:177]
	s_nop 0
	v_pk_mul_f32 v[134:135], v[176:177], v[134:135]
	s_nop 0
	v_cvt_pk_bf16_f32 v207, v134, v135
	global_store_dwordx2 v[188:189], v[206:207], off offset:8
	global_store_dwordx2 v[190:191], v[204:205], off offset:8
	s_and_saveexec_b64 s[14:15], s[4:5]
	s_cbranch_execz .LBB0_1954
	s_add_u32 s28, s33, s94
	s_addc_u32 s29, s0, s95
	s_lshl_b64 s[94:95], s[86:87], 2
	s_add_u32 s94, s28, s94
	s_addc_u32 s95, s29, s95
	global_store_dwordx2 v237, v[220:221], s[94:95] offset:24
.LBB0_1954:
	s_or_b64 exec, exec, s[14:15]
	v_mul_f32_e32 v134, 0xbfb8aa3b, v52
	v_exp_f32_e32 v134, v134
	s_add_u32 s14, s92, 2
	s_addc_u32 s15, s93, 0
	s_lshl_b64 s[92:93], s[14:15], 10
	v_add_f32_e32 v134, 1.0, v134
	v_rcp_f32_e32 v176, v134
	v_mul_f32_e32 v134, 0xbfb8aa3b, v53
	v_exp_f32_e32 v134, v134
	s_add_u32 s67, s92, s90
	s_addc_u32 s85, s93, s91
	s_lshl_b64 s[90:91], s[14:15], 12
	v_add_f32_e32 v134, 1.0, v134
	v_rcp_f32_e32 v177, v134
	v_mul_f32_e32 v134, 0xbfb8aa3b, v36
	v_exp_f32_e32 v134, v134
	v_mov_b32_e32 v135, s85
	v_pk_fma_f32 v[176:177], v[176:177], v[174:175], v[140:141]
	v_add_f32_e32 v134, 1.0, v134
	v_cmp_gt_f32_e32 vcc, s47, v176
	v_rcp_f32_e32 v184, v134
	v_mul_f32_e32 v134, 0xbfb8aa3b, v37
	v_cndmask_b32_e64 v178, 0, 32, vcc
	v_ldexp_f32 v178, v176, v178
	v_log_f32_e32 v178, v178
	v_exp_f32_e32 v134, v134
	v_mul_f32_e32 v179, 0x3f317217, v178
	v_fma_f32 v179, v178, s96, -v179
	v_fmac_f32_e32 v179, 0x3377d1cf, v178
	v_fmac_f32_e32 v179, 0x3f317217, v178
	v_cmp_lt_f32_e64 s[14:15], |v178|, s1
	v_add_f32_e32 v134, 1.0, v134
	v_rcp_f32_e32 v185, v134
	v_cndmask_b32_e64 v178, v178, v179, s[14:15]
	v_cndmask_b32_e32 v179, 0, v223, vcc
	v_cmp_gt_f32_e32 vcc, s47, v177
	v_sub_f32_e32 v178, v178, v179
	v_pk_fma_f32 v[184:185], v[184:185], v[174:175], v[140:141]
	v_cndmask_b32_e64 v179, 0, 32, vcc
	v_ldexp_f32 v179, v177, v179
	v_log_f32_e32 v179, v179
	v_mul_f32_e32 v134, 0xbfb8aa3b, v20
	v_exp_f32_e32 v134, v134
	v_pk_add_f32 v[176:177], v[176:177], 1.0 op_sel_hi:[1,0] neg_lo:[1,0] neg_hi:[1,0]
	v_mul_f32_e32 v186, 0x3f317217, v179
	v_fma_f32 v186, v179, s96, -v186
	v_fmac_f32_e32 v186, 0x3377d1cf, v179
	v_fmac_f32_e32 v186, 0x3f317217, v179
	v_cmp_lt_f32_e64 s[14:15], |v179|, s1
	v_add_f32_e32 v134, 1.0, v134
	v_rcp_f32_e32 v182, v134
	v_cndmask_b32_e64 v179, v179, v186, s[14:15]
	v_cndmask_b32_e32 v186, 0, v223, vcc
	v_cmp_gt_f32_e32 vcc, s47, v184
	v_sub_f32_e32 v179, v179, v186
	v_cndmask_b32_e64 v188, 0, 32, vcc
	v_ldexp_f32 v188, v184, v188
	v_log_f32_e32 v188, v188
	v_mul_f32_e32 v134, 0xbfb8aa3b, v21
	s_waitcnt lgkmcnt(0)
	v_add_f32_dpp v178, v178, v178 row_shr:1 row_mask:0xf bank_mask:0xf
	v_mul_f32_e32 v189, 0x3f317217, v188
	v_fma_f32 v189, v188, s96, -v189
	v_fmac_f32_e32 v189, 0x3377d1cf, v188
	v_fmac_f32_e32 v189, 0x3f317217, v188
	v_cmp_lt_f32_e64 s[14:15], |v188|, s1
	v_exp_f32_e32 v134, v134
	v_cndmask_b32_e64 v188, v188, v189, s[14:15]
	v_cndmask_b32_e32 v189, 0, v223, vcc
	v_cmp_gt_f32_e32 vcc, s47, v185
	v_sub_f32_e32 v188, v188, v189
	v_cndmask_b32_e64 v189, 0, 32, vcc
	v_ldexp_f32 v189, v185, v189
	v_log_f32_e32 v189, v189
	v_add_f32_dpp v179, v179, v179 row_shr:1 row_mask:0xf bank_mask:0xf
	v_add_f32_e32 v134, 1.0, v134
	v_mul_f32_e32 v190, 0x3f317217, v189
	v_fma_f32 v190, v189, s96, -v190
	v_fmac_f32_e32 v190, 0x3377d1cf, v189
	v_fmac_f32_e32 v190, 0x3f317217, v189
	v_cmp_lt_f32_e64 s[14:15], |v189|, s1
	v_add_f32_dpp v178, v178, v178 row_shr:2 row_mask:0xf bank_mask:0xf
	v_cndmask_b32_e64 v189, v189, v190, s[14:15]
	v_cndmask_b32_e32 v190, 0, v223, vcc
	v_sub_f32_e32 v189, v189, v190
	v_rcp_f32_e32 v183, v134
	v_pk_add_f32 v[184:185], v[184:185], 1.0 op_sel_hi:[1,0] neg_lo:[1,0] neg_hi:[1,0]
	v_mul_f32_e32 v134, 0xbfb8aa3b, v4
	s_waitcnt lgkmcnt(1)
	v_add_f32_dpp v188, v188, v188 row_shr:1 row_mask:0xf bank_mask:0xf
	s_waitcnt lgkmcnt(1)
	v_add_f32_dpp v179, v179, v179 row_shr:2 row_mask:0xf bank_mask:0xf
	v_pk_fma_f32 v[182:183], v[182:183], v[174:175], v[140:141]
	s_waitcnt lgkmcnt(1)
	v_add_f32_dpp v189, v189, v189 row_shr:1 row_mask:0xf bank_mask:0xf
	s_waitcnt lgkmcnt(1)
	v_add_f32_dpp v178, v178, v178 row_shr:4 row_mask:0xf bank_mask:0xf
	v_cmp_gt_f32_e32 vcc, s47, v182
	s_waitcnt lgkmcnt(1)
	v_add_f32_dpp v188, v188, v188 row_shr:2 row_mask:0xf bank_mask:0xf
	s_waitcnt lgkmcnt(1)
	v_add_f32_dpp v179, v179, v179 row_shr:4 row_mask:0xf bank_mask:0xf
	v_exp_f32_e32 v134, v134
	s_waitcnt lgkmcnt(1)
	v_add_f32_dpp v189, v189, v189 row_shr:2 row_mask:0xf bank_mask:0xf
	s_waitcnt lgkmcnt(1)
	v_add_f32_dpp v178, v178, v178 row_shr:8 row_mask:0xf bank_mask:0xf
	v_add_f32_e32 v134, 1.0, v134
	s_waitcnt lgkmcnt(1)
	v_add_f32_dpp v188, v188, v188 row_shr:4 row_mask:0xf bank_mask:0xf
	s_waitcnt lgkmcnt(1)
	v_add_f32_dpp v179, v179, v179 row_shr:8 row_mask:0xf bank_mask:0xf
	v_mov_b32_dpp v186, v178 row_newbcast:15 row_mask:0xf bank_mask:0xf
	s_nop 1
	v_mov_b32_dpp v187, v179 row_newbcast:15 row_mask:0xf bank_mask:0xf
	s_waitcnt lgkmcnt(2)
	v_add_f32_dpp v189, v189, v189 row_shr:4 row_mask:0xf bank_mask:0xf
	s_waitcnt lgkmcnt(2)
	v_add_f32_e32 v186, 0, v186
	s_waitcnt lgkmcnt(1)
	v_add_f32_e32 v187, 0, v187
	v_rcp_f32_e32 v180, v134
	v_mul_f32_e32 v134, 0xbfb8aa3b, v5
	v_add_f32_dpp v188, v188, v188 row_shr:8 row_mask:0xf bank_mask:0xf
	v_exp_f32_e32 v134, v134
	v_add_f32_e32 v178, 0, v178
	v_add_f32_e32 v179, 0, v179
	v_mul_f32_e32 v178, 0xbfb8aa3b, v178
	v_add_f32_dpp v189, v189, v189 row_shr:8 row_mask:0xf bank_mask:0xf
	v_mov_b32_dpp v190, v188 row_newbcast:15 row_mask:0xf bank_mask:0xf
	s_nop 1
	v_mov_b32_dpp v191, v189 row_newbcast:15 row_mask:0xf bank_mask:0xf
	v_add_f32_e32 v188, v188, v186
	v_add_f32_e32 v134, 1.0, v134
	v_rcp_f32_e32 v181, v134
	s_waitcnt lgkmcnt(1)
	v_add_f32_e32 v190, v186, v190
	v_add_f32_e32 v186, v189, v187
	v_add_f32_e32 v191, v187, v191
	v_mul_f32_e32 v187, 0xbfb8aa3b, v188
	v_mul_f32_e32 v186, 0xbfb8aa3b, v186
	v_exp_f32_e32 v188, v187
	v_exp_f32_e32 v189, v186
	v_pk_fma_f32 v[140:141], v[180:181], v[174:175], v[140:141]
	v_mul_f32_e32 v179, 0xbfb8aa3b, v179
	v_exp_f32_e32 v178, v178
	v_pk_mul_f32 v[186:187], v[184:185], v[188:189]
	v_cndmask_b32_e64 v184, 0, 32, vcc
	v_ldexp_f32 v184, v182, v184
	v_log_f32_e32 v184, v184
	v_exp_f32_e32 v179, v179
	v_or_b32_e32 v134, s67, v154
	v_lshlrev_b64 v[134:135], 7, v[134:135]
	v_mul_f32_e32 v185, 0x3f317217, v184
	v_fma_f32 v185, v184, s96, -v185
	v_fmac_f32_e32 v185, 0x3377d1cf, v184
	v_fmac_f32_e32 v185, 0x3f317217, v184
	v_cmp_lt_f32_e64 s[14:15], |v184|, s1
	v_pk_mul_f32 v[176:177], v[176:177], v[178:179]
	v_lshl_add_u64 v[134:135], v[164:165], 0, v[134:135]
	v_cndmask_b32_e64 v184, v184, v185, s[14:15]
	v_cndmask_b32_e32 v185, 0, v223, vcc
	v_cmp_gt_f32_e32 vcc, s47, v183
	v_sub_f32_e32 v184, v184, v185
	s_nop 0
	v_cndmask_b32_e64 v185, 0, 32, vcc
	v_ldexp_f32 v185, v183, v185
	v_log_f32_e32 v185, v185
	v_pk_add_f32 v[182:183], v[182:183], 1.0 op_sel_hi:[1,0] neg_lo:[1,0] neg_hi:[1,0]
	v_mul_f32_e32 v196, 0x3f317217, v185
	v_fma_f32 v196, v185, s96, -v196
	v_fmac_f32_e32 v196, 0x3377d1cf, v185
	v_fmac_f32_e32 v196, 0x3f317217, v185
	v_cmp_lt_f32_e64 s[14:15], |v185|, s1
	s_nop 1
	v_cndmask_b32_e64 v185, v185, v196, s[14:15]
	v_cndmask_b32_e32 v196, 0, v223, vcc
	v_cmp_gt_f32_e32 vcc, s47, v140
	v_sub_f32_e32 v185, v185, v196
	v_cndmask_b32_e64 v174, 0, 32, vcc
	v_ldexp_f32 v174, v140, v174
	v_log_f32_e32 v174, v174
	v_add_f32_dpp v184, v184, v184 row_shr:1 row_mask:0xf bank_mask:0xf
	v_mul_f32_e32 v175, 0x3f317217, v174
	v_fma_f32 v175, v174, s96, -v175
	v_fmac_f32_e32 v175, 0x3377d1cf, v174
	v_fmac_f32_e32 v175, 0x3f317217, v174
	v_cmp_lt_f32_e64 s[14:15], |v174|, s1
	v_cndmask_b32_e64 v174, v174, v175, s[14:15]
	v_cndmask_b32_e32 v175, 0, v223, vcc
	v_cmp_gt_f32_e32 vcc, s47, v141
	v_sub_f32_e32 v174, v174, v175
	v_add_f32_dpp v185, v185, v185 row_shr:1 row_mask:0xf bank_mask:0xf
	v_cndmask_b32_e64 v175, 0, 32, vcc
	v_ldexp_f32 v175, v141, v175
	v_log_f32_e32 v175, v175
	v_pk_add_f32 v[140:141], v[140:141], 1.0 op_sel_hi:[1,0] neg_lo:[1,0] neg_hi:[1,0]
	v_mul_f32_e32 v180, 0x3f317217, v175
	v_fma_f32 v180, v175, s96, -v180
	v_fmac_f32_e32 v180, 0x3377d1cf, v175
	v_fmac_f32_e32 v180, 0x3f317217, v175
	v_cmp_lt_f32_e64 s[14:15], |v175|, s1
	v_add_f32_dpp v184, v184, v184 row_shr:2 row_mask:0xf bank_mask:0xf
	v_cndmask_b32_e64 v175, v175, v180, s[14:15]
	v_cndmask_b32_e32 v180, 0, v223, vcc
	v_sub_f32_e32 v175, v175, v180
	s_waitcnt lgkmcnt(1)
	v_add_f32_dpp v174, v174, v174 row_shr:1 row_mask:0xf bank_mask:0xf
	s_waitcnt lgkmcnt(1)
	v_add_f32_dpp v185, v185, v185 row_shr:2 row_mask:0xf bank_mask:0xf
	s_waitcnt lgkmcnt(1)
	v_add_f32_dpp v175, v175, v175 row_shr:1 row_mask:0xf bank_mask:0xf
	s_waitcnt lgkmcnt(1)
	v_add_f32_dpp v184, v184, v184 row_shr:4 row_mask:0xf bank_mask:0xf
	s_waitcnt lgkmcnt(1)
	v_add_f32_dpp v174, v174, v174 row_shr:2 row_mask:0xf bank_mask:0xf
	s_waitcnt lgkmcnt(1)
	v_add_f32_dpp v185, v185, v185 row_shr:4 row_mask:0xf bank_mask:0xf
	s_waitcnt lgkmcnt(1)
	v_add_f32_dpp v175, v175, v175 row_shr:2 row_mask:0xf bank_mask:0xf
	s_waitcnt lgkmcnt(1)
	v_add_f32_dpp v184, v184, v184 row_shr:8 row_mask:0xf bank_mask:0xf
	s_waitcnt lgkmcnt(1)
	v_add_f32_dpp v174, v174, v174 row_shr:4 row_mask:0xf bank_mask:0xf
	s_waitcnt lgkmcnt(1)
	v_add_f32_dpp v185, v185, v185 row_shr:8 row_mask:0xf bank_mask:0xf
	v_mov_b32_dpp v196, v184 row_newbcast:15 row_mask:0xf bank_mask:0xf
	s_nop 1
	v_mov_b32_dpp v197, v185 row_newbcast:15 row_mask:0xf bank_mask:0xf
	s_waitcnt lgkmcnt(2)
	v_add_f32_dpp v175, v175, v175 row_shr:4 row_mask:0xf bank_mask:0xf
	v_add_f32_e32 v184, v184, v190
	s_waitcnt lgkmcnt(2)
	v_add_f32_e32 v198, v190, v196
	v_add_f32_e32 v185, v185, v191
	v_mul_f32_e32 v184, 0xbfb8aa3b, v184
	v_add_f32_dpp v174, v174, v174 row_shr:8 row_mask:0xf bank_mask:0xf
	v_add_f32_e32 v199, v191, v197
	v_exp_f32_e32 v196, v184
	v_mul_f32_e32 v184, 0xbfb8aa3b, v185
	v_exp_f32_e32 v197, v184
	v_add_f32_dpp v175, v175, v175 row_shr:8 row_mask:0xf bank_mask:0xf
	v_mov_b32_dpp v180, v174 row_newbcast:15 row_mask:0xf bank_mask:0xf
	s_nop 1
	v_mov_b32_dpp v181, v175 row_newbcast:15 row_mask:0xf bank_mask:0xf
	v_pk_mul_f32 v[190:191], v[182:183], v[196:197]
	v_add_f32_e32 v174, v174, v198
	v_add_f32_e32 v175, v175, v199
	s_waitcnt lgkmcnt(1)
	v_add_f32_e32 v180, v198, v180
	v_mul_f32_e32 v180, 0x3fb8aa3b, v180
	v_add_f32_e32 v181, v199, v181
	v_exp_f32_e32 v180, v180
	v_mul_f32_e32 v181, 0x3fb8aa3b, v181
	v_exp_f32_e32 v181, v181
	v_mul_f32_e32 v174, 0xbfb8aa3b, v174
	v_mul_f32_e32 v182, v176, v180
	v_cvt_pk_bf16_f32 v182, v182, s0
	global_store_short v[134:135], v182, off
	v_mul_f32_e32 v182, v177, v181
	v_cvt_pk_bf16_f32 v182, v182, s0
	global_store_short v[134:135], v182, off offset:128
	v_mul_f32_e32 v182, v186, v180
	v_cvt_pk_bf16_f32 v182, v182, s0
	global_store_short v[134:135], v182, off offset:32
	v_mul_f32_e32 v182, v187, v181
	v_mul_f32_e32 v175, 0xbfb8aa3b, v175
	v_cvt_pk_bf16_f32 v182, v182, s0
	v_exp_f32_e32 v174, v174
	v_exp_f32_e32 v175, v175
	global_store_short v[134:135], v182, off offset:160
	v_mul_f32_e32 v182, v190, v180
	v_cvt_pk_bf16_f32 v182, v182, s0
	global_store_short v[134:135], v182, off offset:64
	v_mul_f32_e32 v182, v191, v181
	v_cvt_pk_bf16_f32 v182, v182, s0
	v_pk_mul_f32 v[140:141], v[140:141], v[174:175]
	global_store_short v[134:135], v182, off offset:192
	v_mul_f32_e32 v182, v180, v140
	v_cvt_pk_bf16_f32 v182, v182, s0
	global_store_short v[134:135], v182, off offset:96
	v_mul_f32_e32 v182, v181, v141
	v_cvt_pk_bf16_f32 v182, v182, s0
	global_store_short v[134:135], v182, off offset:224
	s_and_saveexec_b64 s[14:15], s[4:5]
	s_cbranch_execz .LBB0_1956
	s_add_u32 s28, s33, s90
	s_addc_u32 s29, s0, s91
	s_lshl_b64 s[92:93], s[86:87], 2
	s_add_u32 s92, s28, s92
	s_addc_u32 s93, s29, s93
	global_store_dwordx2 v237, v[180:181], s[92:93]
.LBB0_1956:
	s_or_b64 exec, exec, s[14:15]
	v_mul_f32_e32 v180, 0xbfb8aa3b, v60
	v_mul_f32_e32 v181, 0xbfb8aa3b, v61
	v_exp_f32_e32 v180, v180
	v_exp_f32_e32 v181, v181
	v_rcp_f32_e32 v178, v178
	v_rcp_f32_e32 v179, v179
	v_add_f32_e32 v180, 1.0, v180
	v_add_f32_e32 v181, 1.0, v181
	v_rcp_f32_e32 v180, v180
	v_rcp_f32_e32 v181, v181
	v_cvt_pk_bf16_f32 v182, v176, v177
	v_mul_f32_e32 v177, 0xbfb8aa3b, v44
	v_exp_f32_e32 v177, v177
	v_pk_mul_f32 v[180:181], v[60:61], v[180:181]
	v_rcp_f32_e32 v176, v188
	v_pk_mul_f32 v[178:179], v[180:181], v[178:179]
	v_add_f32_e32 v177, 1.0, v177
	v_cvt_pk_bf16_f32 v184, v178, v179
	v_mul_f32_e32 v179, 0xbfb8aa3b, v45
	v_exp_f32_e32 v179, v179
	v_rcp_f32_e32 v178, v177
	v_rcp_f32_e32 v177, v189
	v_rcp_f32_e32 v174, v174
	v_add_f32_e32 v179, 1.0, v179
	v_rcp_f32_e32 v179, v179
	v_rcp_f32_e32 v175, v175
	v_cvt_pk_bf16_f32 v198, v190, v191
	v_cvt_pk_bf16_f32 v190, v140, v141
	v_pk_mul_f32 v[178:179], v[44:45], v[178:179]
	v_mul_f32_e32 v140, 0xbfb8aa3b, v54
	v_pk_mul_f32 v[176:177], v[178:179], v[176:177]
	v_mul_f32_e32 v179, 0xbfb8aa3b, v29
	v_cvt_pk_bf16_f32 v188, v176, v177
	v_mul_f32_e32 v177, 0xbfb8aa3b, v28
	v_exp_f32_e32 v177, v177
	v_exp_f32_e32 v179, v179
	v_rcp_f32_e32 v176, v196
	v_mul_f32_e32 v141, 0xbfb8aa3b, v55
	v_add_f32_e32 v177, 1.0, v177
	v_add_f32_e32 v179, 1.0, v179
	v_rcp_f32_e32 v178, v177
	v_rcp_f32_e32 v179, v179
	v_rcp_f32_e32 v177, v197
	v_exp_f32_e32 v140, v140
	v_exp_f32_e32 v141, v141
	v_pk_mul_f32 v[178:179], v[28:29], v[178:179]
	v_lshlrev_b64 v[134:135], 10, v[172:173]
	v_pk_mul_f32 v[176:177], v[178:179], v[176:177]
	v_add_f32_e32 v140, 1.0, v140
	v_cvt_pk_bf16_f32 v200, v176, v177
	v_mul_f32_e32 v176, 0xbfb8aa3b, v12
	v_mul_f32_e32 v177, 0xbfb8aa3b, v13
	v_exp_f32_e32 v176, v176
	v_exp_f32_e32 v177, v177
	v_add_f32_e32 v141, 1.0, v141
	v_rcp_f32_e32 v140, v140
	v_add_f32_e32 v176, 1.0, v176
	v_add_f32_e32 v177, 1.0, v177
	v_rcp_f32_e32 v176, v176
	v_rcp_f32_e32 v177, v177
	v_rcp_f32_e32 v141, v141
	v_lshlrev_b64 v[204:205], 1, v[134:135]
	v_cvt_pk_bf16_f32 v186, v186, v187
	v_pk_mul_f32 v[176:177], v[12:13], v[176:177]
	v_pk_fma_f32 v[140:141], v[140:141], v[138:139], v[136:137]
	v_pk_mul_f32 v[174:175], v[176:177], v[174:175]
	v_mul_f32_e32 v176, 0xbfb8aa3b, v22
	v_exp_f32_e32 v176, v176
	v_mov_b32_e32 v177, s85
	v_cmp_gt_f32_e32 vcc, s47, v140
	v_cvt_pk_bf16_f32 v196, v174, v175
	v_add_f32_e32 v176, 1.0, v176
	v_rcp_f32_e32 v178, v176
	v_mul_f32_e32 v176, 0xbfb8aa3b, v23
	v_exp_f32_e32 v176, v176
	v_mul_f32_e32 v174, 0xbfb8aa3b, v38
	v_mul_f32_e32 v175, 0xbfb8aa3b, v39
	v_exp_f32_e32 v174, v174
	v_add_f32_e32 v176, 1.0, v176
	v_rcp_f32_e32 v179, v176
	v_mul_f32_e32 v176, 0xbfb8aa3b, v6
	v_exp_f32_e32 v176, v176
	v_exp_f32_e32 v175, v175
	v_add_f32_e32 v174, 1.0, v174
	v_rcp_f32_e32 v174, v174
	v_add_f32_e32 v176, 1.0, v176
	v_rcp_f32_e32 v206, v176
	v_mul_f32_e32 v176, 0xbfb8aa3b, v7
	v_exp_f32_e32 v176, v176
	v_add_f32_e32 v175, 1.0, v175
	v_rcp_f32_e32 v175, v175
	v_pk_fma_f32 v[178:179], v[178:179], v[138:139], v[136:137]
	v_add_f32_e32 v176, 1.0, v176
	v_rcp_f32_e32 v207, v176
	v_or_b32_e32 v176, s67, v158
	v_lshlrev_b64 v[176:177], 7, v[176:177]
	v_lshl_add_u64 v[202:203], v[164:165], 0, v[176:177]
	v_cndmask_b32_e64 v176, 0, 32, vcc
	v_ldexp_f32 v176, v140, v176
	v_log_f32_e32 v176, v176
	v_pk_fma_f32 v[174:175], v[174:175], v[138:139], v[136:137]
	v_pk_fma_f32 v[136:137], v[206:207], v[138:139], v[136:137]
	v_mul_f32_e32 v177, 0x3f317217, v176
	v_fma_f32 v177, v176, s96, -v177
	v_fmac_f32_e32 v177, 0x3377d1cf, v176
	v_fmac_f32_e32 v177, 0x3f317217, v176
	v_cmp_lt_f32_e64 s[14:15], |v176|, s1
	s_nop 1
	v_cndmask_b32_e64 v176, v176, v177, s[14:15]
	v_cndmask_b32_e32 v177, 0, v223, vcc
	v_cmp_gt_f32_e32 vcc, s47, v141
	v_sub_f32_e32 v176, v176, v177
	s_nop 0
	v_cndmask_b32_e64 v177, 0, 32, vcc
	v_ldexp_f32 v177, v141, v177
	v_log_f32_e32 v177, v177
	v_pk_add_f32 v[140:141], v[140:141], 1.0 op_sel_hi:[1,0] neg_lo:[1,0] neg_hi:[1,0]
	v_mul_f32_e32 v180, 0x3f317217, v177
	v_fma_f32 v180, v177, s96, -v180
	v_fmac_f32_e32 v180, 0x3377d1cf, v177
	v_fmac_f32_e32 v180, 0x3f317217, v177
	v_cmp_lt_f32_e64 s[14:15], |v177|, s1
	s_nop 1
	v_cndmask_b32_e64 v177, v177, v180, s[14:15]
	v_cndmask_b32_e32 v180, 0, v223, vcc
	v_sub_f32_e32 v177, v177, v180
	v_cmp_gt_f32_e32 vcc, s47, v174
	s_mov_b64 s[14:15], 0x40000
	s_waitcnt lgkmcnt(0)
	v_add_f32_dpp v176, v176, v176 row_shr:1 row_mask:0xf bank_mask:0xf
	v_add_f32_dpp v177, v177, v177 row_shr:1 row_mask:0xf bank_mask:0xf
	s_nop 1
	v_add_f32_dpp v176, v176, v176 row_shr:2 row_mask:0xf bank_mask:0xf
	v_add_f32_dpp v177, v177, v177 row_shr:2 row_mask:0xf bank_mask:0xf
	s_nop 1
	v_add_f32_dpp v176, v176, v176 row_shr:4 row_mask:0xf bank_mask:0xf
	v_add_f32_dpp v177, v177, v177 row_shr:4 row_mask:0xf bank_mask:0xf
	s_nop 1
	v_add_f32_dpp v176, v176, v176 row_shr:8 row_mask:0xf bank_mask:0xf
	v_add_f32_dpp v177, v177, v177 row_shr:8 row_mask:0xf bank_mask:0xf
	s_nop 1
	v_mov_b32_dpp v180, v176 row_newbcast:15 row_mask:0xf bank_mask:0xf
	v_add_f32_e32 v176, 0, v176
	v_mov_b32_dpp v181, v177 row_newbcast:15 row_mask:0xf bank_mask:0xf
	v_add_f32_e32 v177, 0, v177
	v_mul_f32_e32 v176, 0xbfb8aa3b, v176
	v_mul_f32_e32 v177, 0xbfb8aa3b, v177
	v_exp_f32_e32 v176, v176
	v_exp_f32_e32 v177, v177
	s_waitcnt lgkmcnt(1)
	v_add_f32_e32 v180, 0, v180
	v_add_f32_e32 v181, 0, v181
	v_pk_mul_f32 v[208:209], v[140:141], v[176:177]
	v_mul_f32_e32 v141, 0xbfb8aa3b, v62
	v_exp_f32_e32 v141, v141
	v_rcp_f32_e32 v140, v176
	v_cvt_pk_bf16_f32 v183, v208, v209
	v_add_f32_e32 v141, 1.0, v141
	v_rcp_f32_e32 v176, v141
	v_rcp_f32_e32 v141, v177
	v_mul_f32_e32 v177, 0xbfb8aa3b, v63
	v_exp_f32_e32 v177, v177
	s_nop 0
	v_add_f32_e32 v177, 1.0, v177
	v_rcp_f32_e32 v177, v177
	s_nop 0
	v_pk_mul_f32 v[176:177], v[62:63], v[176:177]
	s_nop 0
	v_pk_mul_f32 v[140:141], v[176:177], v[140:141]
	v_cndmask_b32_e64 v176, 0, 32, vcc
	v_ldexp_f32 v176, v174, v176
	v_log_f32_e32 v176, v176
	v_cvt_pk_bf16_f32 v185, v140, v141
	v_lshl_add_u64 v[140:141], v[204:205], 0, s[14:15]
	v_lshl_add_u64 v[134:135], s[44:45], 0, v[140:141]
	v_mul_f32_e32 v177, 0x3f317217, v176
	v_fma_f32 v177, v176, s96, -v177
	v_fmac_f32_e32 v177, 0x3377d1cf, v176
	v_fmac_f32_e32 v177, 0x3f317217, v176
	v_cmp_lt_f32_e64 s[14:15], |v176|, s1
	v_lshl_add_u64 v[140:141], s[48:49], 0, v[140:141]
	v_lshl_add_u64 v[134:135], v[134:135], 0, s[88:89]
	v_cndmask_b32_e64 v176, v176, v177, s[14:15]
	v_cndmask_b32_e32 v177, 0, v223, vcc
	v_cmp_gt_f32_e32 vcc, s47, v175
	v_sub_f32_e32 v176, v176, v177
	v_lshl_add_u64 v[140:141], v[140:141], 0, s[88:89]
	v_cndmask_b32_e64 v177, 0, 32, vcc
	v_ldexp_f32 v177, v175, v177
	v_log_f32_e32 v177, v177
	v_pk_add_f32 v[174:175], v[174:175], 1.0 op_sel_hi:[1,0] neg_lo:[1,0] neg_hi:[1,0]
	v_lshl_add_u64 v[134:135], v[134:135], 0, v[152:153]
	v_lshl_add_u64 v[140:141], v[140:141], 0, v[152:153]
	v_mul_f32_e32 v187, 0x3f317217, v177
	v_fma_f32 v187, v177, s96, -v187
	v_fmac_f32_e32 v187, 0x3377d1cf, v177
	v_fmac_f32_e32 v187, 0x3f317217, v177
	v_cmp_lt_f32_e64 s[14:15], |v177|, s1
	s_nop 1
	v_cndmask_b32_e64 v177, v177, v187, s[14:15]
	v_cndmask_b32_e32 v187, 0, v223, vcc
	v_sub_f32_e32 v177, v177, v187
	v_cmp_gt_f32_e32 vcc, s47, v178
	s_mov_b64 s[14:15], 0x48000
	v_add_f32_dpp v176, v176, v176 row_shr:1 row_mask:0xf bank_mask:0xf
	v_cndmask_b32_e64 v191, 0, 32, vcc
	v_ldexp_f32 v191, v178, v191
	v_log_f32_e32 v191, v191
	v_add_f32_dpp v177, v177, v177 row_shr:1 row_mask:0xf bank_mask:0xf
	v_mul_f32_e32 v197, 0x3f317217, v191
	v_fma_f32 v197, v191, s96, -v197
	v_fmac_f32_e32 v197, 0x3377d1cf, v191
	v_fmac_f32_e32 v197, 0x3f317217, v191
	v_add_f32_dpp v176, v176, v176 row_shr:2 row_mask:0xf bank_mask:0xf
	v_add_f32_dpp v177, v177, v177 row_shr:2 row_mask:0xf bank_mask:0xf
	s_nop 1
	v_add_f32_dpp v176, v176, v176 row_shr:4 row_mask:0xf bank_mask:0xf
	v_add_f32_dpp v177, v177, v177 row_shr:4 row_mask:0xf bank_mask:0xf
	s_nop 1
	v_add_f32_dpp v176, v176, v176 row_shr:8 row_mask:0xf bank_mask:0xf
	v_add_f32_dpp v177, v177, v177 row_shr:8 row_mask:0xf bank_mask:0xf
	s_nop 1
	v_mov_b32_dpp v187, v176 row_newbcast:15 row_mask:0xf bank_mask:0xf
	v_mov_b32_dpp v189, v177 row_newbcast:15 row_mask:0xf bank_mask:0xf
	v_add_f32_e32 v176, v176, v180
	v_add_f32_e32 v177, v177, v181
	v_mul_f32_e32 v176, 0xbfb8aa3b, v176
	v_mul_f32_e32 v177, 0xbfb8aa3b, v177
	v_exp_f32_e32 v176, v176
	v_exp_f32_e32 v177, v177
	s_waitcnt lgkmcnt(1)
	v_add_f32_e32 v180, v180, v187
	v_add_f32_e32 v181, v181, v189
	v_pk_mul_f32 v[210:211], v[174:175], v[176:177]
	v_mul_f32_e32 v175, 0xbfb8aa3b, v46
	v_exp_f32_e32 v175, v175
	v_rcp_f32_e32 v174, v176
	v_cvt_pk_bf16_f32 v187, v210, v211
	v_add_f32_e32 v175, 1.0, v175
	v_rcp_f32_e32 v176, v175
	v_rcp_f32_e32 v175, v177
	v_mul_f32_e32 v177, 0xbfb8aa3b, v47
	v_exp_f32_e32 v177, v177
	s_nop 0
	v_add_f32_e32 v177, 1.0, v177
	v_rcp_f32_e32 v177, v177
	s_nop 0
	v_pk_mul_f32 v[176:177], v[46:47], v[176:177]
	s_nop 0
	v_pk_mul_f32 v[174:175], v[176:177], v[174:175]
	v_lshl_add_u64 v[176:177], v[204:205], 0, s[14:15]
	v_cmp_lt_f32_e64 s[14:15], |v191|, s1
	v_cvt_pk_bf16_f32 v189, v174, v175
	v_lshl_add_u64 v[174:175], s[44:45], 0, v[176:177]
	v_cndmask_b32_e64 v191, v191, v197, s[14:15]
	v_cndmask_b32_e32 v197, 0, v223, vcc
	v_cmp_gt_f32_e32 vcc, s47, v179
	v_sub_f32_e32 v191, v191, v197
	v_lshl_add_u64 v[176:177], s[48:49], 0, v[176:177]
	v_cndmask_b32_e64 v197, 0, 32, vcc
	v_ldexp_f32 v197, v179, v197
	v_log_f32_e32 v197, v197
	v_pk_add_f32 v[178:179], v[178:179], 1.0 op_sel_hi:[1,0] neg_lo:[1,0] neg_hi:[1,0]
	v_lshl_add_u64 v[174:175], v[174:175], 0, s[88:89]
	v_lshl_add_u64 v[176:177], v[176:177], 0, s[88:89]
	v_mul_f32_e32 v199, 0x3f317217, v197
	v_fma_f32 v199, v197, s96, -v199
	v_fmac_f32_e32 v199, 0x3377d1cf, v197
	v_fmac_f32_e32 v199, 0x3f317217, v197
	v_cmp_lt_f32_e64 s[14:15], |v197|, s1
	v_lshl_add_u64 v[174:175], v[174:175], 0, v[152:153]
	v_lshl_add_u64 v[176:177], v[176:177], 0, v[152:153]
	v_cndmask_b32_e64 v197, v197, v199, s[14:15]
	v_cndmask_b32_e32 v199, 0, v223, vcc
	v_sub_f32_e32 v197, v197, v199
	v_cmp_gt_f32_e32 vcc, s47, v136
	s_mov_b64 s[14:15], 0x50000
	v_add_f32_dpp v191, v191, v191 row_shr:1 row_mask:0xf bank_mask:0xf
	v_cndmask_b32_e64 v138, 0, 32, vcc
	v_ldexp_f32 v138, v136, v138
	v_log_f32_e32 v138, v138
	v_add_f32_dpp v197, v197, v197 row_shr:1 row_mask:0xf bank_mask:0xf
	v_mul_f32_e32 v139, 0x3f317217, v138
	v_fma_f32 v139, v138, s96, -v139
	v_fmac_f32_e32 v139, 0x3377d1cf, v138
	v_fmac_f32_e32 v139, 0x3f317217, v138
	v_add_f32_dpp v191, v191, v191 row_shr:2 row_mask:0xf bank_mask:0xf
	v_add_f32_dpp v197, v197, v197 row_shr:2 row_mask:0xf bank_mask:0xf
	s_nop 1
	v_add_f32_dpp v191, v191, v191 row_shr:4 row_mask:0xf bank_mask:0xf
	v_add_f32_dpp v197, v197, v197 row_shr:4 row_mask:0xf bank_mask:0xf
	s_nop 1
	v_add_f32_dpp v191, v191, v191 row_shr:8 row_mask:0xf bank_mask:0xf
	v_add_f32_dpp v197, v197, v197 row_shr:8 row_mask:0xf bank_mask:0xf
	s_nop 1
	v_mov_b32_dpp v199, v191 row_newbcast:15 row_mask:0xf bank_mask:0xf
	v_mov_b32_dpp v201, v197 row_newbcast:15 row_mask:0xf bank_mask:0xf
	v_add_f32_e32 v191, v191, v180
	v_add_f32_e32 v197, v197, v181
	s_waitcnt lgkmcnt(1)
	v_add_f32_e32 v214, v180, v199
	v_add_f32_e32 v215, v181, v201
	v_mul_f32_e32 v180, 0xbfb8aa3b, v191
	v_mul_f32_e32 v181, 0xbfb8aa3b, v197
	v_exp_f32_e32 v180, v180
	v_exp_f32_e32 v181, v181
	s_nop 0
	v_pk_mul_f32 v[212:213], v[178:179], v[180:181]
	v_mul_f32_e32 v179, 0xbfb8aa3b, v30
	v_exp_f32_e32 v179, v179
	v_rcp_f32_e32 v178, v180
	v_cvt_pk_bf16_f32 v199, v212, v213
	v_add_f32_e32 v179, 1.0, v179
	v_rcp_f32_e32 v180, v179
	v_rcp_f32_e32 v179, v181
	v_mul_f32_e32 v181, 0xbfb8aa3b, v31
	v_exp_f32_e32 v181, v181
	s_nop 0
	v_add_f32_e32 v181, 1.0, v181
	v_rcp_f32_e32 v181, v181
	s_nop 0
	v_pk_mul_f32 v[180:181], v[30:31], v[180:181]
	s_nop 0
	v_pk_mul_f32 v[178:179], v[180:181], v[178:179]
	v_lshl_add_u64 v[180:181], v[204:205], 0, s[14:15]
	v_cmp_lt_f32_e64 s[14:15], |v138|, s1
	v_cvt_pk_bf16_f32 v201, v178, v179
	v_lshl_add_u64 v[178:179], s[44:45], 0, v[180:181]
	v_cndmask_b32_e64 v138, v138, v139, s[14:15]
	v_cndmask_b32_e32 v139, 0, v223, vcc
	v_cmp_gt_f32_e32 vcc, s47, v137
	v_sub_f32_e32 v138, v138, v139
	v_lshl_add_u64 v[180:181], s[48:49], 0, v[180:181]
	v_cndmask_b32_e64 v139, 0, 32, vcc
	v_ldexp_f32 v139, v137, v139
	v_log_f32_e32 v139, v139
	v_pk_add_f32 v[136:137], v[136:137], 1.0 op_sel_hi:[1,0] neg_lo:[1,0] neg_hi:[1,0]
	v_lshl_add_u64 v[178:179], v[178:179], 0, s[88:89]
	v_lshl_add_u64 v[180:181], v[180:181], 0, s[88:89]
	v_mul_f32_e32 v191, 0x3f317217, v139
	v_fma_f32 v191, v139, s96, -v191
	v_fmac_f32_e32 v191, 0x3377d1cf, v139
	v_fmac_f32_e32 v191, 0x3f317217, v139
	v_cmp_lt_f32_e64 s[14:15], |v139|, s1
	v_lshl_add_u64 v[178:179], v[178:179], 0, v[152:153]
	v_lshl_add_u64 v[180:181], v[180:181], 0, v[152:153]
	v_cndmask_b32_e64 v139, v139, v191, s[14:15]
	v_cndmask_b32_e32 v191, 0, v223, vcc
	v_sub_f32_e32 v139, v139, v191
	s_mov_b64 s[14:15], 0x58000
	v_add_f32_dpp v138, v138, v138 row_shr:1 row_mask:0xf bank_mask:0xf
	v_add_f32_dpp v139, v139, v139 row_shr:1 row_mask:0xf bank_mask:0xf
	s_nop 1
	v_add_f32_dpp v138, v138, v138 row_shr:2 row_mask:0xf bank_mask:0xf
	v_add_f32_dpp v139, v139, v139 row_shr:2 row_mask:0xf bank_mask:0xf
	s_nop 1
	v_add_f32_dpp v138, v138, v138 row_shr:4 row_mask:0xf bank_mask:0xf
	v_add_f32_dpp v139, v139, v139 row_shr:4 row_mask:0xf bank_mask:0xf
	s_nop 1
	v_add_f32_dpp v138, v138, v138 row_shr:8 row_mask:0xf bank_mask:0xf
	v_add_f32_dpp v139, v139, v139 row_shr:8 row_mask:0xf bank_mask:0xf
	s_nop 1
	v_mov_b32_dpp v191, v138 row_newbcast:15 row_mask:0xf bank_mask:0xf
	v_mov_b32_dpp v197, v139 row_newbcast:15 row_mask:0xf bank_mask:0xf
	v_add_f32_e32 v138, v138, v214
	v_add_f32_e32 v139, v139, v215
	v_mul_f32_e32 v138, 0xbfb8aa3b, v138
	s_waitcnt lgkmcnt(1)
	v_add_f32_e32 v191, v214, v191
	v_mul_f32_e32 v191, 0x3fb8aa3b, v191
	v_add_f32_e32 v197, v215, v197
	v_exp_f32_e32 v206, v191
	v_mul_f32_e32 v191, 0x3fb8aa3b, v197
	v_exp_f32_e32 v207, v191
	v_mul_f32_e32 v139, 0xbfb8aa3b, v139
	v_mul_f32_e32 v191, v208, v206
	v_cvt_pk_bf16_f32 v191, v191, s0
	global_store_short v[202:203], v191, off
	v_mul_f32_e32 v191, v209, v207
	v_cvt_pk_bf16_f32 v191, v191, s0
	global_store_short v[202:203], v191, off offset:128
	global_store_dwordx2 v[134:135], v[184:185], off
	global_store_dwordx2 v[140:141], v[182:183], off
	v_mul_f32_e32 v182, v210, v206
	v_cvt_pk_bf16_f32 v182, v182, s0
	global_store_short v[202:203], v182, off offset:32
	v_mul_f32_e32 v182, v211, v207
	v_cvt_pk_bf16_f32 v182, v182, s0
	v_exp_f32_e32 v138, v138
	v_exp_f32_e32 v139, v139
	global_store_short v[202:203], v182, off offset:160
	global_store_dwordx2 v[174:175], v[188:189], off
	global_store_dwordx2 v[176:177], v[186:187], off
	v_mul_f32_e32 v182, v212, v206
	v_cvt_pk_bf16_f32 v182, v182, s0
	global_store_short v[202:203], v182, off offset:64
	v_mul_f32_e32 v182, v213, v207
	v_cvt_pk_bf16_f32 v182, v182, s0
	v_pk_mul_f32 v[136:137], v[136:137], v[138:139]
	global_store_short v[202:203], v182, off offset:192
	global_store_dwordx2 v[178:179], v[200:201], off
	global_store_dwordx2 v[180:181], v[198:199], off
	v_mul_f32_e32 v182, v206, v136
	v_cvt_pk_bf16_f32 v182, v182, s0
	global_store_short v[202:203], v182, off offset:96
	v_mul_f32_e32 v182, v207, v137
	v_cvt_pk_bf16_f32 v182, v182, s0
	global_store_short v[202:203], v182, off offset:224
	v_mul_f32_e32 v182, 0xbfb8aa3b, v14
	v_mul_f32_e32 v183, 0xbfb8aa3b, v15
	v_exp_f32_e32 v182, v182
	v_exp_f32_e32 v183, v183
	v_rcp_f32_e32 v138, v138
	v_rcp_f32_e32 v139, v139
	v_add_f32_e32 v182, 1.0, v182
	v_add_f32_e32 v183, 1.0, v183
	v_rcp_f32_e32 v182, v182
	v_rcp_f32_e32 v183, v183
	v_cvt_pk_bf16_f32 v191, v136, v137
	v_pk_mul_f32 v[182:183], v[14:15], v[182:183]
	s_nop 0
	v_pk_mul_f32 v[138:139], v[182:183], v[138:139]
	s_nop 0
	v_cvt_pk_bf16_f32 v197, v138, v139
	v_lshl_add_u64 v[138:139], v[204:205], 0, s[14:15]
	v_lshl_add_u64 v[136:137], s[44:45], 0, v[138:139]
	v_lshl_add_u64 v[138:139], s[48:49], 0, v[138:139]
	v_lshl_add_u64 v[136:137], v[136:137], 0, s[88:89]
	v_lshl_add_u64 v[138:139], v[138:139], 0, s[88:89]
	v_lshl_add_u64 v[136:137], v[136:137], 0, v[152:153]
	v_lshl_add_u64 v[138:139], v[138:139], 0, v[152:153]
	global_store_dwordx2 v[136:137], v[196:197], off
	global_store_dwordx2 v[138:139], v[190:191], off
	s_and_saveexec_b64 s[14:15], s[4:5]
	s_cbranch_execz .LBB0_1958
	s_add_u32 s28, s33, s90
	s_addc_u32 s29, s0, s91
	s_lshl_b64 s[88:89], s[86:87], 2
	s_add_u32 s88, s28, s88
	s_addc_u32 s89, s29, s89
	global_store_dwordx2 v237, v[206:207], s[88:89] offset:8
.LBB0_1958:
	s_or_b64 exec, exec, s[14:15]
	v_mul_f32_e32 v152, 0xbfb8aa3b, v48
	v_exp_f32_e32 v152, v152
	v_mov_b32_e32 v183, s85
	v_or_b32_e32 v182, s67, v160
	v_lshlrev_b64 v[182:183], 7, v[182:183]
	v_add_f32_e32 v152, 1.0, v152
	v_rcp_f32_e32 v184, v152
	v_mul_f32_e32 v152, 0xbfb8aa3b, v49
	v_exp_f32_e32 v152, v152
	v_lshl_add_u64 v[182:183], v[164:165], 0, v[182:183]
	v_add_f32_e32 v152, 1.0, v152
	v_rcp_f32_e32 v185, v152
	v_mul_f32_e32 v152, 0xbfb8aa3b, v32
	v_exp_f32_e32 v152, v152
	v_pk_fma_f32 v[184:185], v[184:185], v[142:143], v[132:133]
	s_nop 0
	v_cmp_gt_f32_e32 vcc, s47, v184
	v_add_f32_e32 v152, 1.0, v152
	v_rcp_f32_e32 v190, v152
	v_mul_f32_e32 v152, 0xbfb8aa3b, v33
	v_exp_f32_e32 v152, v152
	s_nop 0
	v_add_f32_e32 v152, 1.0, v152
	v_rcp_f32_e32 v191, v152
	v_mul_f32_e32 v152, 0xbfb8aa3b, v16
	v_exp_f32_e32 v152, v152
	v_pk_fma_f32 v[190:191], v[190:191], v[142:143], v[132:133]
	v_add_f32_e32 v152, 1.0, v152
	v_rcp_f32_e32 v198, v152
	v_mul_f32_e32 v152, 0xbfb8aa3b, v17
	v_exp_f32_e32 v152, v152
	s_nop 0
	v_add_f32_e32 v152, 1.0, v152
	v_rcp_f32_e32 v199, v152
	v_mul_f32_e32 v152, 0xbfb8aa3b, v0
	v_exp_f32_e32 v152, v152
	v_pk_fma_f32 v[198:199], v[198:199], v[142:143], v[132:133]
	v_add_f32_e32 v152, 1.0, v152
	v_rcp_f32_e32 v188, v152
	v_mul_f32_e32 v152, 0xbfb8aa3b, v1
	v_exp_f32_e32 v152, v152
	s_nop 0
	v_add_f32_e32 v152, 1.0, v152
	v_rcp_f32_e32 v189, v152
	v_cndmask_b32_e64 v152, 0, 32, vcc
	v_ldexp_f32 v152, v184, v152
	v_log_f32_e32 v152, v152
	v_pk_fma_f32 v[132:133], v[188:189], v[142:143], v[132:133]
	v_mul_f32_e32 v186, 0x3f317217, v152
	v_fma_f32 v186, v152, s96, -v186
	v_fmac_f32_e32 v186, 0x3377d1cf, v152
	v_fmac_f32_e32 v186, 0x3f317217, v152
	v_cmp_lt_f32_e64 s[14:15], |v152|, s1
	s_nop 1
	v_cndmask_b32_e64 v152, v152, v186, s[14:15]
	v_cndmask_b32_e32 v186, 0, v223, vcc
	v_cmp_gt_f32_e32 vcc, s47, v185
	v_sub_f32_e32 v152, v152, v186
	s_nop 0
	v_cndmask_b32_e64 v186, 0, 32, vcc
	v_ldexp_f32 v186, v185, v186
	v_log_f32_e32 v186, v186
	v_pk_add_f32 v[184:185], v[184:185], 1.0 op_sel_hi:[1,0] neg_lo:[1,0] neg_hi:[1,0]
	v_mul_f32_e32 v187, 0x3f317217, v186
	v_fma_f32 v187, v186, s96, -v187
	v_fmac_f32_e32 v187, 0x3377d1cf, v186
	v_fmac_f32_e32 v187, 0x3f317217, v186
	v_cmp_lt_f32_e64 s[14:15], |v186|, s1
	s_nop 1
	v_cndmask_b32_e64 v186, v186, v187, s[14:15]
	v_cndmask_b32_e32 v187, 0, v223, vcc
	v_sub_f32_e32 v186, v186, v187
	v_cmp_gt_f32_e32 vcc, s47, v190
	s_waitcnt lgkmcnt(0)
	v_add_f32_dpp v152, v152, v152 row_shr:1 row_mask:0xf bank_mask:0xf
	v_add_f32_dpp v186, v186, v186 row_shr:1 row_mask:0xf bank_mask:0xf
	s_nop 1
	v_add_f32_dpp v152, v152, v152 row_shr:2 row_mask:0xf bank_mask:0xf
	v_add_f32_dpp v186, v186, v186 row_shr:2 row_mask:0xf bank_mask:0xf
	s_nop 1
	v_add_f32_dpp v152, v152, v152 row_shr:4 row_mask:0xf bank_mask:0xf
	v_add_f32_dpp v186, v186, v186 row_shr:4 row_mask:0xf bank_mask:0xf
	s_nop 1
	v_add_f32_dpp v152, v152, v152 row_shr:8 row_mask:0xf bank_mask:0xf
	v_add_f32_dpp v186, v186, v186 row_shr:8 row_mask:0xf bank_mask:0xf
	s_nop 1
	v_mov_b32_dpp v187, v152 row_newbcast:15 row_mask:0xf bank_mask:0xf
	v_add_f32_e32 v152, 0, v152
	v_add_f32_e32 v197, 0, v186
	v_mul_f32_e32 v152, 0xbfb8aa3b, v152
	v_add_f32_e32 v196, 0, v187
	v_mov_b32_dpp v187, v186 row_newbcast:15 row_mask:0xf bank_mask:0xf
	v_exp_f32_e32 v186, v152
	v_mul_f32_e32 v152, 0xbfb8aa3b, v197
	v_add_f32_e32 v200, 0, v187
	v_exp_f32_e32 v187, v152
	v_cndmask_b32_e64 v152, 0, 32, vcc
	v_ldexp_f32 v152, v190, v152
	v_log_f32_e32 v152, v152
	v_pk_mul_f32 v[184:185], v[184:185], v[186:187]
	v_mul_f32_e32 v197, 0x3f317217, v152
	v_fma_f32 v197, v152, s96, -v197
	v_fmac_f32_e32 v197, 0x3377d1cf, v152
	v_fmac_f32_e32 v197, 0x3f317217, v152
	v_cmp_lt_f32_e64 s[14:15], |v152|, s1
	s_nop 1
	v_cndmask_b32_e64 v152, v152, v197, s[14:15]
	v_cndmask_b32_e32 v197, 0, v223, vcc
	v_cmp_gt_f32_e32 vcc, s47, v191
	v_sub_f32_e32 v152, v152, v197
	s_nop 0
	v_cndmask_b32_e64 v197, 0, 32, vcc
	v_ldexp_f32 v197, v191, v197
	v_log_f32_e32 v197, v197
	v_pk_add_f32 v[190:191], v[190:191], 1.0 op_sel_hi:[1,0] neg_lo:[1,0] neg_hi:[1,0]
	v_mul_f32_e32 v201, 0x3f317217, v197
	v_fma_f32 v201, v197, s96, -v201
	v_fmac_f32_e32 v201, 0x3377d1cf, v197
	v_fmac_f32_e32 v201, 0x3f317217, v197
	v_cmp_lt_f32_e64 s[14:15], |v197|, s1
	s_nop 1
	v_cndmask_b32_e64 v197, v197, v201, s[14:15]
	v_cndmask_b32_e32 v201, 0, v223, vcc
	v_sub_f32_e32 v197, v197, v201
	v_cmp_gt_f32_e32 vcc, s47, v198
	v_add_f32_dpp v152, v152, v152 row_shr:1 row_mask:0xf bank_mask:0xf
	v_add_f32_dpp v197, v197, v197 row_shr:1 row_mask:0xf bank_mask:0xf
	s_nop 1
	v_add_f32_dpp v152, v152, v152 row_shr:2 row_mask:0xf bank_mask:0xf
	v_add_f32_dpp v197, v197, v197 row_shr:2 row_mask:0xf bank_mask:0xf
	s_nop 1
	v_add_f32_dpp v152, v152, v152 row_shr:4 row_mask:0xf bank_mask:0xf
	v_add_f32_dpp v197, v197, v197 row_shr:4 row_mask:0xf bank_mask:0xf
	s_nop 1
	v_add_f32_dpp v152, v152, v152 row_shr:8 row_mask:0xf bank_mask:0xf
	v_add_f32_dpp v197, v197, v197 row_shr:8 row_mask:0xf bank_mask:0xf
	s_nop 1
	v_mov_b32_dpp v201, v152 row_newbcast:15 row_mask:0xf bank_mask:0xf
	v_add_f32_e32 v152, v152, v196
	v_mov_b32_dpp v202, v197 row_newbcast:15 row_mask:0xf bank_mask:0xf
	v_add_f32_e32 v197, v197, v200
	v_mul_f32_e32 v152, 0xbfb8aa3b, v152
	s_waitcnt lgkmcnt(1)
	v_add_f32_e32 v201, v196, v201
	v_exp_f32_e32 v196, v152
	v_mul_f32_e32 v152, 0xbfb8aa3b, v197
	v_exp_f32_e32 v197, v152
	v_cndmask_b32_e64 v152, 0, 32, vcc
	v_ldexp_f32 v152, v198, v152
	v_log_f32_e32 v152, v152
	v_add_f32_e32 v200, v200, v202
	v_pk_mul_f32 v[190:191], v[190:191], v[196:197]
	v_mul_f32_e32 v202, 0x3f317217, v152
	v_fma_f32 v202, v152, s96, -v202
	v_fmac_f32_e32 v202, 0x3377d1cf, v152
	v_fmac_f32_e32 v202, 0x3f317217, v152
	v_cmp_lt_f32_e64 s[14:15], |v152|, s1
	s_nop 1
	v_cndmask_b32_e64 v152, v152, v202, s[14:15]
	v_cndmask_b32_e32 v202, 0, v223, vcc
	v_cmp_gt_f32_e32 vcc, s47, v199
	v_sub_f32_e32 v152, v152, v202
	s_nop 0
	v_cndmask_b32_e64 v202, 0, 32, vcc
	v_ldexp_f32 v202, v199, v202
	v_log_f32_e32 v202, v202
	v_pk_add_f32 v[198:199], v[198:199], 1.0 op_sel_hi:[1,0] neg_lo:[1,0] neg_hi:[1,0]
	v_mul_f32_e32 v203, 0x3f317217, v202
	v_fma_f32 v203, v202, s96, -v203
	v_fmac_f32_e32 v203, 0x3377d1cf, v202
	v_fmac_f32_e32 v203, 0x3f317217, v202
	v_cmp_lt_f32_e64 s[14:15], |v202|, s1
	s_nop 1
	v_cndmask_b32_e64 v202, v202, v203, s[14:15]
	v_cndmask_b32_e32 v203, 0, v223, vcc
	v_sub_f32_e32 v202, v202, v203
	v_cmp_gt_f32_e32 vcc, s47, v132
	v_add_f32_dpp v152, v152, v152 row_shr:1 row_mask:0xf bank_mask:0xf
	v_cndmask_b32_e64 v142, 0, 32, vcc
	v_ldexp_f32 v142, v132, v142
	v_log_f32_e32 v142, v142
	v_add_f32_dpp v202, v202, v202 row_shr:1 row_mask:0xf bank_mask:0xf
	v_mul_f32_e32 v143, 0x3f317217, v142
	v_fma_f32 v143, v142, s96, -v143
	v_fmac_f32_e32 v143, 0x3377d1cf, v142
	v_fmac_f32_e32 v143, 0x3f317217, v142
	v_add_f32_dpp v152, v152, v152 row_shr:2 row_mask:0xf bank_mask:0xf
	v_cmp_lt_f32_e64 s[14:15], |v142|, s1
	v_add_f32_dpp v202, v202, v202 row_shr:2 row_mask:0xf bank_mask:0xf
	v_cndmask_b32_e64 v142, v142, v143, s[14:15]
	v_cndmask_b32_e32 v143, 0, v223, vcc
	v_cmp_gt_f32_e32 vcc, s47, v133
	v_sub_f32_e32 v142, v142, v143
	v_add_f32_dpp v152, v152, v152 row_shr:4 row_mask:0xf bank_mask:0xf
	v_cndmask_b32_e64 v143, 0, 32, vcc
	v_ldexp_f32 v143, v133, v143
	v_log_f32_e32 v143, v143
	v_pk_add_f32 v[132:133], v[132:133], 1.0 op_sel_hi:[1,0] neg_lo:[1,0] neg_hi:[1,0]
	v_add_f32_dpp v202, v202, v202 row_shr:4 row_mask:0xf bank_mask:0xf
	v_cmp_lt_f32_e64 s[14:15], |v143|, s1
	v_add_f32_dpp v152, v152, v152 row_shr:8 row_mask:0xf bank_mask:0xf
	v_add_f32_dpp v202, v202, v202 row_shr:8 row_mask:0xf bank_mask:0xf
	s_nop 1
	v_mov_b32_dpp v203, v152 row_newbcast:15 row_mask:0xf bank_mask:0xf
	v_mov_b32_dpp v204, v202 row_newbcast:15 row_mask:0xf bank_mask:0xf
	v_add_f32_e32 v152, v152, v201
	v_mul_f32_e32 v152, 0xbfb8aa3b, v152
	s_waitcnt lgkmcnt(1)
	v_add_f32_e32 v203, v201, v203
	v_add_f32_e32 v201, v202, v200
	v_add_f32_e32 v202, v200, v204
	v_exp_f32_e32 v200, v152
	v_mul_f32_e32 v152, 0xbfb8aa3b, v201
	v_exp_f32_e32 v201, v152
	v_mul_f32_e32 v152, 0x3f317217, v143
	v_fma_f32 v152, v143, s96, -v152
	v_fmac_f32_e32 v152, 0x3377d1cf, v143
	v_fmac_f32_e32 v152, 0x3f317217, v143
	v_cndmask_b32_e64 v143, v143, v152, s[14:15]
	v_cndmask_b32_e32 v152, 0, v223, vcc
	v_sub_f32_e32 v143, v143, v152
	v_pk_mul_f32 v[198:199], v[198:199], v[200:201]
	v_add_f32_dpp v142, v142, v142 row_shr:1 row_mask:0xf bank_mask:0xf
	v_add_f32_dpp v143, v143, v143 row_shr:1 row_mask:0xf bank_mask:0xf
	s_nop 1
	v_add_f32_dpp v142, v142, v142 row_shr:2 row_mask:0xf bank_mask:0xf
	v_add_f32_dpp v143, v143, v143 row_shr:2 row_mask:0xf bank_mask:0xf
	s_nop 1
	v_add_f32_dpp v142, v142, v142 row_shr:4 row_mask:0xf bank_mask:0xf
	v_add_f32_dpp v143, v143, v143 row_shr:4 row_mask:0xf bank_mask:0xf
	s_nop 1
	v_add_f32_dpp v142, v142, v142 row_shr:8 row_mask:0xf bank_mask:0xf
	v_add_f32_e32 v189, v142, v203
	v_add_f32_dpp v143, v143, v143 row_shr:8 row_mask:0xf bank_mask:0xf
	v_mov_b32_dpp v152, v142 row_newbcast:15 row_mask:0xf bank_mask:0xf
	s_nop 1
	v_mov_b32_dpp v188, v143 row_newbcast:15 row_mask:0xf bank_mask:0xf
	s_waitcnt lgkmcnt(1)
	v_add_f32_e32 v142, v203, v152
	v_mul_f32_e32 v142, 0x3fb8aa3b, v142
	v_add_f32_e32 v152, v143, v202
	v_add_f32_e32 v143, v202, v188
	v_exp_f32_e32 v142, v142
	v_mul_f32_e32 v143, 0x3fb8aa3b, v143
	v_exp_f32_e32 v143, v143
	v_mul_f32_e32 v152, 0xbfb8aa3b, v152
	v_mul_f32_e32 v188, v184, v142
	v_cvt_pk_bf16_f32 v188, v188, s0
	global_store_short v[182:183], v188, off
	v_mul_f32_e32 v188, v185, v143
	v_cvt_pk_bf16_f32 v188, v188, s0
	global_store_short v[182:183], v188, off offset:128
	v_mul_f32_e32 v188, v190, v142
	v_cvt_pk_bf16_f32 v188, v188, s0
	global_store_short v[182:183], v188, off offset:32
	v_mul_f32_e32 v188, v191, v143
	v_cvt_pk_bf16_f32 v188, v188, s0
	global_store_short v[182:183], v188, off offset:160
	v_mul_f32_e32 v188, v198, v142
	v_cvt_pk_bf16_f32 v188, v188, s0
	global_store_short v[182:183], v188, off offset:64
	v_mul_f32_e32 v188, v199, v143
	v_cvt_pk_bf16_f32 v188, v188, s0
	global_store_short v[182:183], v188, off offset:192
	v_mul_f32_e32 v188, 0xbfb8aa3b, v189
	v_exp_f32_e32 v188, v188
	v_exp_f32_e32 v189, v152
	s_nop 0
	v_pk_mul_f32 v[202:203], v[132:133], v[188:189]
	s_nop 0
	v_mul_f32_e32 v132, v142, v202
	v_cvt_pk_bf16_f32 v132, v132, s0
	global_store_short v[182:183], v132, off offset:96
	v_mul_f32_e32 v132, v143, v203
	v_cvt_pk_bf16_f32 v132, v132, s0
	global_store_short v[182:183], v132, off offset:224
	s_and_saveexec_b64 s[14:15], s[4:5]
	s_cbranch_execz .LBB0_1960
	s_add_u32 s28, s33, s90
	s_addc_u32 s29, s0, s91
	s_lshl_b64 s[88:89], s[86:87], 2
	s_add_u32 s88, s28, s88
	s_addc_u32 s89, s29, s89
	global_store_dwordx2 v237, v[142:143], s[88:89] offset:16
.LBB0_1960:
	s_or_b64 exec, exec, s[14:15]
	v_mul_f32_e32 v133, 0xbfb8aa3b, v56
	v_mul_f32_e32 v143, 0xbfb8aa3b, v57
	v_exp_f32_e32 v133, v133
	v_exp_f32_e32 v143, v143
	v_rcp_f32_e32 v132, v186
	v_rcp_f32_e32 v182, v196
	v_add_f32_e32 v133, 1.0, v133
	v_add_f32_e32 v143, 1.0, v143
	v_rcp_f32_e32 v142, v133
	v_rcp_f32_e32 v143, v143
	v_rcp_f32_e32 v133, v187
	v_rcp_f32_e32 v183, v197
	v_rcp_f32_e32 v186, v200
	v_pk_mul_f32 v[142:143], v[56:57], v[142:143]
	v_rcp_f32_e32 v187, v201
	v_pk_mul_f32 v[132:133], v[142:143], v[132:133]
	s_nop 0
	v_cvt_pk_bf16_f32 v142, v132, v133
	v_mul_f32_e32 v133, 0xbfb8aa3b, v40
	v_exp_f32_e32 v133, v133
	v_cvt_pk_bf16_f32 v132, v184, v185
	v_add_f32_e32 v133, 1.0, v133
	v_rcp_f32_e32 v184, v133
	v_mul_f32_e32 v133, 0xbfb8aa3b, v41
	v_exp_f32_e32 v133, v133
	s_nop 0
	v_add_f32_e32 v133, 1.0, v133
	v_rcp_f32_e32 v185, v133
	v_mul_f32_e32 v133, 0xbfb8aa3b, v24
	v_exp_f32_e32 v133, v133
	v_pk_mul_f32 v[184:185], v[40:41], v[184:185]
	s_nop 0
	v_pk_mul_f32 v[182:183], v[184:185], v[182:183]
	v_add_f32_e32 v133, 1.0, v133
	v_cvt_pk_bf16_f32 v184, v182, v183
	v_cvt_pk_bf16_f32 v182, v190, v191
	v_rcp_f32_e32 v190, v133
	v_mul_f32_e32 v133, 0xbfb8aa3b, v25
	v_exp_f32_e32 v133, v133
	s_nop 0
	v_add_f32_e32 v133, 1.0, v133
	v_rcp_f32_e32 v191, v133
	v_mul_f32_e32 v133, 0xbfb8aa3b, v8
	v_exp_f32_e32 v133, v133
	v_pk_mul_f32 v[190:191], v[24:25], v[190:191]
	s_nop 0
	v_pk_mul_f32 v[186:187], v[190:191], v[186:187]
	v_add_f32_e32 v133, 1.0, v133
	v_cvt_pk_bf16_f32 v196, v186, v187
	v_rcp_f32_e32 v186, v188
	v_rcp_f32_e32 v188, v133
	v_mul_f32_e32 v133, 0xbfb8aa3b, v9
	v_exp_f32_e32 v133, v133
	v_rcp_f32_e32 v187, v189
	v_cvt_pk_bf16_f32 v190, v198, v199
	v_mov_b32_e32 v199, s85
	v_add_f32_e32 v133, 1.0, v133
	v_rcp_f32_e32 v189, v133
	v_mul_f32_e32 v133, 0xbfb8aa3b, v50
	v_exp_f32_e32 v133, v133
	v_or_b32_e32 v198, s67, v162
	v_pk_mul_f32 v[188:189], v[8:9], v[188:189]
	v_lshlrev_b64 v[198:199], 7, v[198:199]
	v_pk_mul_f32 v[186:187], v[188:189], v[186:187]
	v_add_f32_e32 v133, 1.0, v133
	v_cvt_pk_bf16_f32 v188, v186, v187
	v_cvt_pk_bf16_f32 v186, v202, v203
	v_rcp_f32_e32 v202, v133
	v_mul_f32_e32 v133, 0xbfb8aa3b, v51
	v_exp_f32_e32 v133, v133
	v_lshl_add_u64 v[198:199], v[164:165], 0, v[198:199]
	v_add_f32_e32 v133, 1.0, v133
	v_rcp_f32_e32 v203, v133
	v_mul_f32_e32 v133, 0xbfb8aa3b, v34
	v_exp_f32_e32 v133, v133
	v_pk_fma_f32 v[202:203], v[202:203], v[130:131], v[128:129]
	s_nop 0
	v_cmp_gt_f32_e32 vcc, s47, v202
	v_add_f32_e32 v133, 1.0, v133
	v_rcp_f32_e32 v206, v133
	v_mul_f32_e32 v133, 0xbfb8aa3b, v35
	v_exp_f32_e32 v133, v133
	s_nop 0
	v_add_f32_e32 v133, 1.0, v133
	v_rcp_f32_e32 v207, v133
	v_mul_f32_e32 v133, 0xbfb8aa3b, v18
	v_exp_f32_e32 v133, v133
	v_pk_fma_f32 v[206:207], v[206:207], v[130:131], v[128:129]
	v_add_f32_e32 v133, 1.0, v133
	v_rcp_f32_e32 v204, v133
	v_mul_f32_e32 v133, 0xbfb8aa3b, v19
	v_exp_f32_e32 v133, v133
	s_nop 0
	v_add_f32_e32 v133, 1.0, v133
	v_rcp_f32_e32 v205, v133
	v_mul_f32_e32 v133, 0xbfb8aa3b, v2
	v_exp_f32_e32 v133, v133
	v_pk_fma_f32 v[204:205], v[204:205], v[130:131], v[128:129]
	v_add_f32_e32 v133, 1.0, v133
	v_rcp_f32_e32 v200, v133
	v_mul_f32_e32 v133, 0xbfb8aa3b, v3
	v_exp_f32_e32 v133, v133
	s_nop 0
	v_add_f32_e32 v133, 1.0, v133
	v_rcp_f32_e32 v201, v133
	v_cndmask_b32_e64 v133, 0, 32, vcc
	v_ldexp_f32 v133, v202, v133
	v_log_f32_e32 v133, v133
	v_pk_fma_f32 v[128:129], v[200:201], v[130:131], v[128:129]
	v_mul_f32_e32 v143, 0x3f317217, v133
	v_fma_f32 v143, v133, s96, -v143
	v_fmac_f32_e32 v143, 0x3377d1cf, v133
	v_fmac_f32_e32 v143, 0x3f317217, v133
	v_cmp_lt_f32_e64 s[14:15], |v133|, s1
	s_nop 1
	v_cndmask_b32_e64 v133, v133, v143, s[14:15]
	v_cndmask_b32_e32 v143, 0, v223, vcc
	v_cmp_gt_f32_e32 vcc, s47, v203
	v_sub_f32_e32 v133, v133, v143
	s_nop 0
	v_cndmask_b32_e64 v143, 0, 32, vcc
	v_ldexp_f32 v143, v203, v143
	v_log_f32_e32 v143, v143
	v_pk_add_f32 v[202:203], v[202:203], 1.0 op_sel_hi:[1,0] neg_lo:[1,0] neg_hi:[1,0]
	v_mul_f32_e32 v152, 0x3f317217, v143
	v_fma_f32 v152, v143, s96, -v152
	v_fmac_f32_e32 v152, 0x3377d1cf, v143
	v_fmac_f32_e32 v152, 0x3f317217, v143
	v_cmp_lt_f32_e64 s[14:15], |v143|, s1
	s_nop 1
	v_cndmask_b32_e64 v143, v143, v152, s[14:15]
	v_cndmask_b32_e32 v152, 0, v223, vcc
	v_cmp_gt_f32_e32 vcc, s47, v206
	v_sub_f32_e32 v143, v143, v152
	v_cndmask_b32_e64 v185, 0, 32, vcc
	v_ldexp_f32 v185, v206, v185
	v_log_f32_e32 v185, v185
	s_waitcnt lgkmcnt(0)
	v_add_f32_dpp v133, v133, v133 row_shr:1 row_mask:0xf bank_mask:0xf
	v_mul_f32_e32 v187, 0x3f317217, v185
	v_fma_f32 v187, v185, s96, -v187
	v_fmac_f32_e32 v187, 0x3377d1cf, v185
	v_fmac_f32_e32 v187, 0x3f317217, v185
	v_cmp_lt_f32_e64 s[14:15], |v185|, s1
	v_cndmask_b32_e64 v185, v185, v187, s[14:15]
	v_cndmask_b32_e32 v187, 0, v223, vcc
	v_cmp_gt_f32_e32 vcc, s47, v207
	v_sub_f32_e32 v185, v185, v187
	v_add_f32_dpp v143, v143, v143 row_shr:1 row_mask:0xf bank_mask:0xf
	v_cndmask_b32_e64 v187, 0, 32, vcc
	v_ldexp_f32 v187, v207, v187
	v_log_f32_e32 v187, v187
	v_pk_add_f32 v[206:207], v[206:207], 1.0 op_sel_hi:[1,0] neg_lo:[1,0] neg_hi:[1,0]
	v_mul_f32_e32 v189, 0x3f317217, v187
	v_fma_f32 v189, v187, s96, -v189
	v_fmac_f32_e32 v189, 0x3377d1cf, v187
	v_fmac_f32_e32 v189, 0x3f317217, v187
	v_cmp_lt_f32_e64 s[14:15], |v187|, s1
	v_add_f32_dpp v133, v133, v133 row_shr:2 row_mask:0xf bank_mask:0xf
	v_cndmask_b32_e64 v187, v187, v189, s[14:15]
	v_cndmask_b32_e32 v189, 0, v223, vcc
	v_sub_f32_e32 v187, v187, v189
	v_cmp_gt_f32_e32 vcc, s47, v204
	s_waitcnt lgkmcnt(1)
	v_add_f32_dpp v185, v185, v185 row_shr:1 row_mask:0xf bank_mask:0xf
	s_waitcnt lgkmcnt(1)
	v_add_f32_dpp v143, v143, v143 row_shr:2 row_mask:0xf bank_mask:0xf
	s_waitcnt lgkmcnt(1)
	v_add_f32_dpp v187, v187, v187 row_shr:1 row_mask:0xf bank_mask:0xf
	s_waitcnt lgkmcnt(1)
	v_add_f32_dpp v133, v133, v133 row_shr:4 row_mask:0xf bank_mask:0xf
	s_waitcnt lgkmcnt(1)
	v_add_f32_dpp v185, v185, v185 row_shr:2 row_mask:0xf bank_mask:0xf
	s_waitcnt lgkmcnt(1)
	v_add_f32_dpp v143, v143, v143 row_shr:4 row_mask:0xf bank_mask:0xf
	s_waitcnt lgkmcnt(1)
	v_add_f32_dpp v187, v187, v187 row_shr:2 row_mask:0xf bank_mask:0xf
	s_waitcnt lgkmcnt(1)
	v_add_f32_dpp v133, v133, v133 row_shr:8 row_mask:0xf bank_mask:0xf
	s_waitcnt lgkmcnt(1)
	v_add_f32_dpp v185, v185, v185 row_shr:4 row_mask:0xf bank_mask:0xf
	s_waitcnt lgkmcnt(1)
	v_add_f32_dpp v143, v143, v143 row_shr:8 row_mask:0xf bank_mask:0xf
	v_mov_b32_dpp v152, v133 row_newbcast:15 row_mask:0xf bank_mask:0xf
	v_add_f32_e32 v133, 0, v133
	v_mov_b32_dpp v183, v143 row_newbcast:15 row_mask:0xf bank_mask:0xf
	v_add_f32_e32 v143, 0, v143
	v_mul_f32_e32 v133, 0xbfb8aa3b, v133
	s_waitcnt lgkmcnt(2)
	v_exp_f32_e32 v208, v133
	v_mul_f32_e32 v133, 0xbfb8aa3b, v143
	v_add_f32_dpp v187, v187, v187 row_shr:4 row_mask:0xf bank_mask:0xf
	v_exp_f32_e32 v209, v133
	v_mul_f32_e32 v133, 0xbfb8aa3b, v58
	v_exp_f32_e32 v133, v133
	s_waitcnt lgkmcnt(2)
	v_add_f32_e32 v152, 0, v152
	v_add_f32_dpp v185, v185, v185 row_shr:8 row_mask:0xf bank_mask:0xf
	v_add_f32_e32 v133, 1.0, v133
	v_rcp_f32_e32 v210, v133
	v_mul_f32_e32 v133, 0xbfb8aa3b, v59
	v_exp_f32_e32 v133, v133
	v_pk_mul_f32 v[202:203], v[202:203], v[208:209]
	v_add_f32_dpp v187, v187, v187 row_shr:8 row_mask:0xf bank_mask:0xf
	v_add_f32_e32 v133, 1.0, v133
	v_rcp_f32_e32 v211, v133
	v_mov_b32_dpp v189, v185 row_newbcast:15 row_mask:0xf bank_mask:0xf
	v_mov_b32_dpp v191, v187 row_newbcast:15 row_mask:0xf bank_mask:0xf
	v_rcp_f32_e32 v208, v208
	v_rcp_f32_e32 v209, v209
	v_add_f32_e32 v183, 0, v183
	v_pk_mul_f32 v[210:211], v[58:59], v[210:211]
	v_add_f32_e32 v185, v185, v152
	v_pk_mul_f32 v[208:209], v[210:211], v[208:209]
	s_waitcnt lgkmcnt(1)
	v_add_f32_e32 v152, v152, v189
	v_add_f32_e32 v187, v187, v183
	v_add_f32_e32 v189, v183, v191
	v_mul_f32_e32 v183, 0xbfb8aa3b, v185
	v_cvt_pk_bf16_f32 v143, v208, v209
	v_exp_f32_e32 v208, v183
	v_mul_f32_e32 v183, 0xbfb8aa3b, v187
	v_cndmask_b32_e64 v187, 0, 32, vcc
	v_ldexp_f32 v187, v204, v187
	v_log_f32_e32 v187, v187
	v_exp_f32_e32 v209, v183
	v_mul_f32_e32 v183, 0xbfb8aa3b, v42
	v_exp_f32_e32 v183, v183
	v_mul_f32_e32 v191, 0x3f317217, v187
	v_fma_f32 v191, v187, s96, -v191
	v_fmac_f32_e32 v191, 0x3377d1cf, v187
	v_fmac_f32_e32 v191, 0x3f317217, v187
	v_cmp_lt_f32_e64 s[14:15], |v187|, s1
	v_add_f32_e32 v183, 1.0, v183
	v_rcp_f32_e32 v210, v183
	v_cndmask_b32_e64 v187, v187, v191, s[14:15]
	v_cndmask_b32_e32 v191, 0, v223, vcc
	v_cmp_gt_f32_e32 vcc, s47, v205
	v_sub_f32_e32 v187, v187, v191
	v_mul_f32_e32 v183, 0xbfb8aa3b, v43
	v_cndmask_b32_e64 v191, 0, 32, vcc
	v_ldexp_f32 v191, v205, v191
	v_log_f32_e32 v191, v191
	v_exp_f32_e32 v183, v183
	v_pk_mul_f32 v[206:207], v[206:207], v[208:209]
	v_rcp_f32_e32 v208, v208
	v_mul_f32_e32 v197, 0x3f317217, v191
	v_fma_f32 v197, v191, s96, -v197
	v_fmac_f32_e32 v197, 0x3377d1cf, v191
	v_fmac_f32_e32 v197, 0x3f317217, v191
	v_cmp_lt_f32_e64 s[14:15], |v191|, s1
	v_add_f32_e32 v183, 1.0, v183
	v_rcp_f32_e32 v211, v183
	v_cndmask_b32_e64 v191, v191, v197, s[14:15]
	v_cndmask_b32_e32 v197, 0, v223, vcc
	v_sub_f32_e32 v191, v191, v197
	v_rcp_f32_e32 v209, v209
	v_pk_mul_f32 v[210:211], v[42:43], v[210:211]
	v_cmp_gt_f32_e32 vcc, s47, v128
	v_cvt_pk_bf16_f32 v133, v202, v203
	v_add_f32_dpp v187, v187, v187 row_shr:1 row_mask:0xf bank_mask:0xf
	v_pk_mul_f32 v[208:209], v[210:211], v[208:209]
	v_cndmask_b32_e64 v130, 0, 32, vcc
	v_cvt_pk_bf16_f32 v185, v208, v209
	v_ldexp_f32 v130, v128, v130
	v_add_f32_dpp v191, v191, v191 row_shr:1 row_mask:0xf bank_mask:0xf
	v_log_f32_e32 v130, v130
	v_pk_add_f32 v[204:205], v[204:205], 1.0 op_sel_hi:[1,0] neg_lo:[1,0] neg_hi:[1,0]
	v_cvt_pk_bf16_f32 v183, v206, v207
	v_add_f32_dpp v187, v187, v187 row_shr:2 row_mask:0xf bank_mask:0xf
	v_mul_f32_e32 v131, 0x3f317217, v130
	v_fma_f32 v131, v130, s96, -v131
	v_fmac_f32_e32 v131, 0x3377d1cf, v130
	v_fmac_f32_e32 v131, 0x3f317217, v130
	v_add_f32_dpp v191, v191, v191 row_shr:2 row_mask:0xf bank_mask:0xf
	v_cmp_lt_f32_e64 s[14:15], |v130|, s1
	v_add_f32_dpp v187, v187, v187 row_shr:4 row_mask:0xf bank_mask:0xf
	v_cndmask_b32_e64 v130, v130, v131, s[14:15]
	v_cndmask_b32_e32 v131, 0, v223, vcc
	v_cmp_gt_f32_e32 vcc, s47, v129
	v_sub_f32_e32 v130, v130, v131
	v_add_f32_dpp v191, v191, v191 row_shr:4 row_mask:0xf bank_mask:0xf
	v_cndmask_b32_e64 v131, 0, 32, vcc
	v_ldexp_f32 v131, v129, v131
	v_log_f32_e32 v131, v131
	v_pk_add_f32 v[128:129], v[128:129], 1.0 op_sel_hi:[1,0] neg_lo:[1,0] neg_hi:[1,0]
	v_add_f32_dpp v187, v187, v187 row_shr:8 row_mask:0xf bank_mask:0xf
	v_cmp_lt_f32_e64 s[14:15], |v131|, s1
	v_add_f32_dpp v191, v191, v191 row_shr:8 row_mask:0xf bank_mask:0xf
	s_nop 1
	v_mov_b32_dpp v208, v191 row_newbcast:15 row_mask:0xf bank_mask:0xf
	v_mov_b32_dpp v197, v187 row_newbcast:15 row_mask:0xf bank_mask:0xf
	v_add_f32_e32 v187, v187, v152
	v_add_f32_e32 v191, v191, v189
	v_mul_f32_e32 v187, 0xbfb8aa3b, v187
	s_waitcnt lgkmcnt(1)
	v_add_f32_e32 v189, v189, v208
	v_exp_f32_e32 v208, v187
	v_mul_f32_e32 v187, 0xbfb8aa3b, v191
	v_exp_f32_e32 v209, v187
	v_mul_f32_e32 v187, 0xbfb8aa3b, v26
	v_exp_f32_e32 v187, v187
	v_add_f32_e32 v152, v152, v197
	v_pk_mul_f32 v[204:205], v[204:205], v[208:209]
	v_rcp_f32_e32 v208, v208
	v_add_f32_e32 v187, 1.0, v187
	v_rcp_f32_e32 v210, v187
	v_mul_f32_e32 v187, 0xbfb8aa3b, v27
	v_exp_f32_e32 v187, v187
	v_rcp_f32_e32 v209, v209
	v_cvt_pk_bf16_f32 v191, v204, v205
	v_add_f32_e32 v187, 1.0, v187
	v_rcp_f32_e32 v211, v187
	v_mul_f32_e32 v187, 0x3f317217, v131
	v_fma_f32 v187, v131, s96, -v187
	v_fmac_f32_e32 v187, 0x3377d1cf, v131
	v_fmac_f32_e32 v187, 0x3f317217, v131
	v_cndmask_b32_e64 v131, v131, v187, s[14:15]
	v_cndmask_b32_e32 v187, 0, v223, vcc
	v_sub_f32_e32 v131, v131, v187
	v_pk_mul_f32 v[210:211], v[26:27], v[210:211]
	v_add_f32_dpp v130, v130, v130 row_shr:1 row_mask:0xf bank_mask:0xf
	v_pk_mul_f32 v[208:209], v[210:211], v[208:209]
	v_add_f32_dpp v131, v131, v131 row_shr:1 row_mask:0xf bank_mask:0xf
	v_cvt_pk_bf16_f32 v197, v208, v209
	v_add_f32_dpp v130, v130, v130 row_shr:2 row_mask:0xf bank_mask:0xf
	v_add_f32_dpp v131, v131, v131 row_shr:2 row_mask:0xf bank_mask:0xf
	s_nop 1
	v_add_f32_dpp v130, v130, v130 row_shr:4 row_mask:0xf bank_mask:0xf
	v_add_f32_dpp v131, v131, v131 row_shr:4 row_mask:0xf bank_mask:0xf
	s_nop 1
	v_add_f32_dpp v130, v130, v130 row_shr:8 row_mask:0xf bank_mask:0xf
	v_add_f32_e32 v201, v130, v152
	v_add_f32_dpp v131, v131, v131 row_shr:8 row_mask:0xf bank_mask:0xf
	v_mov_b32_dpp v187, v130 row_newbcast:15 row_mask:0xf bank_mask:0xf
	s_nop 1
	v_mov_b32_dpp v200, v131 row_newbcast:15 row_mask:0xf bank_mask:0xf
	s_waitcnt lgkmcnt(1)
	v_add_f32_e32 v130, v152, v187
	v_mul_f32_e32 v130, 0x3fb8aa3b, v130
	v_add_f32_e32 v152, v131, v189
	v_add_f32_e32 v131, v189, v200
	v_exp_f32_e32 v130, v130
	v_mul_f32_e32 v131, 0x3fb8aa3b, v131
	v_exp_f32_e32 v131, v131
	v_mul_f32_e32 v187, v202, v130
	v_cvt_pk_bf16_f32 v187, v187, s0
	global_store_short v[198:199], v187, off
	v_mul_f32_e32 v187, v203, v131
	v_cvt_pk_bf16_f32 v187, v187, s0
	global_store_short v[198:199], v187, off offset:128
	global_store_dwordx2 v[134:135], v[142:143], off offset:8
	global_store_dwordx2 v[140:141], v[132:133], off offset:8
	v_mul_f32_e32 v132, v206, v130
	v_cvt_pk_bf16_f32 v132, v132, s0
	global_store_short v[198:199], v132, off offset:32
	v_mul_f32_e32 v132, v207, v131
	v_cvt_pk_bf16_f32 v132, v132, s0
	global_store_short v[198:199], v132, off offset:160
	global_store_dwordx2 v[174:175], v[184:185], off offset:8
	global_store_dwordx2 v[176:177], v[182:183], off offset:8
	v_mul_f32_e32 v132, v204, v130
	v_cvt_pk_bf16_f32 v132, v132, s0
	global_store_short v[198:199], v132, off offset:64
	v_mul_f32_e32 v132, v205, v131
	v_cvt_pk_bf16_f32 v132, v132, s0
	global_store_short v[198:199], v132, off offset:192
	global_store_dwordx2 v[178:179], v[196:197], off offset:8
	global_store_dwordx2 v[180:181], v[190:191], off offset:8
	v_mul_f32_e32 v132, 0xbfb8aa3b, v201
	v_mul_f32_e32 v133, 0xbfb8aa3b, v152
	v_exp_f32_e32 v132, v132
	v_exp_f32_e32 v133, v133
	v_mul_f32_e32 v135, 0xbfb8aa3b, v11
	v_exp_f32_e32 v135, v135
	v_pk_mul_f32 v[128:129], v[128:129], v[132:133]
	s_nop 0
	v_mul_f32_e32 v134, v130, v128
	v_cvt_pk_bf16_f32 v134, v134, s0
	global_store_short v[198:199], v134, off offset:96
	v_mul_f32_e32 v134, v131, v129
	v_cvt_pk_bf16_f32 v134, v134, s0
	global_store_short v[198:199], v134, off offset:224
	v_mul_f32_e32 v134, 0xbfb8aa3b, v10
	v_exp_f32_e32 v134, v134
	v_add_f32_e32 v135, 1.0, v135
	v_rcp_f32_e32 v135, v135
	v_rcp_f32_e32 v132, v132
	v_add_f32_e32 v134, 1.0, v134
	v_rcp_f32_e32 v134, v134
	v_rcp_f32_e32 v133, v133
	v_cvt_pk_bf16_f32 v187, v128, v129
	v_pk_mul_f32 v[134:135], v[10:11], v[134:135]
	s_nop 0
	v_pk_mul_f32 v[132:133], v[134:135], v[132:133]
	s_nop 0
	v_cvt_pk_bf16_f32 v189, v132, v133
	global_store_dwordx2 v[136:137], v[188:189], off offset:8
	global_store_dwordx2 v[138:139], v[186:187], off offset:8
	s_and_saveexec_b64 s[14:15], s[4:5]
	s_cbranch_execz .LBB0_1962
	s_add_u32 s28, s33, s90
	s_addc_u32 s29, s0, s91
	s_lshl_b64 s[86:87], s[86:87], 2
	s_add_u32 s86, s28, s86
	s_addc_u32 s87, s29, s87
	global_store_dwordx2 v237, v[130:131], s[86:87] offset:24

; #define PG8_STAGE(bufoff, gbase, voff) do { _Pragma("unroll") for (int _i = 0; _i < 2; ++_i) \
;         __builtin_amdgcn_global_load_lds((const unsigned*)((const char*)(gbase) + (voff)[_i]), (PG8_LAS unsigned*)(lds + (bufoff) + ldsw + _i * 8192), 16, 0, 0); } while (0)
; #define PG8_LDA(dst, b, h) do { _Pragma("unroll") for (int m = 0; m < 4; ++m) _Pragma("unroll") for (int k = 0; k < 2; ++k) dst[m][k] = *(const PG8_LAS bf16x8*)(lds + PG8_SA(b, h) + aoff + m * 2048 + k * 1024); } while (0)
; #define PG8_LDB(dst, b, h) do { _Pragma("unroll") for (int n = 0; n < 2; ++n) _Pragma("unroll") for (int k = 0; k < 2; ++k) dst[n][k] = *(const PG8_LAS bf16x8*)(lds + PG8_SB(b, h) + boff + n * 2048 + k * 1024); } while (0)
; #define PG8_MMA(ai, bj, At, Bt) do { __builtin_amdgcn_s_setprio(1); _Pragma("unroll") for (int m = 0; m < 4; ++m) _Pragma("unroll") for (int n = 0; n < 2; ++n) _Pragma("unroll") for (int k = 0; k < 2; ++k) \
;         acc[ai][bj][m][n] = __builtin_amdgcn_mfma_f32_16x16x32_bf16(Bt[n][k], At[m][k], acc[ai][bj][m][n], 0, 0, 0); __builtin_amdgcn_s_setprio(0); } while (0)
; #define PG8_WAIT_V(n) asm volatile("s_waitcnt vmcnt(" #n ")" ::: "memory")
; #define PG8_WAIT_L(n) asm volatile("s_waitcnt lgkmcnt(" #n ")" ::: "memory")
; #define PG8_BAR __builtin_amdgcn_s_barrier()
; #define PG8_SCHED __builtin_amdgcn_sched_barrier(0)
; template <class Epi, class Sched, bool ALIGN_EPI = false, bool SP2 = false>
; __device__ __forceinline__ void gemm_phase(PG8_LAS unsigned char* lds, const Gemm g, const Sched& S, const Epi& E) {
;     ...
;             PG8_LDB(B0, 0, 0); PG8_LDB(B1, 0, 1); PG8_SCHED; PG8_LDA(At, 0, 0); PG8_STAGE(PG8_SA(1, 1), a1 + hstep, voffA);
;             PG8_WAIT_V(8); PG8_WAIT_L(0); PG8_BAR; PG8_MMA(0, 0, At, B0); PG8_MMA(0, 1, At, B1); PG8_BAR; PG8_SCHED;
;             PG8_LDA(At, 0, 1); PG8_STAGE(PG8_SB(0, 0), b2, voffB); PG8_STAGE(PG8_SB(0, 1), b2 + hstep, voffB); PG8_STAGE(PG8_SA(0, 0), a2, voffA);
;             PG8_WAIT_V(8); PG8_WAIT_L(0); PG8_BAR; PG8_MMA(1, 0, At, B0); PG8_MMA(1, 1, At, B1); PG8_BAR; PG8_SCHED;
.LBB0_1989:
	ds_read_b128 v[152:155], v148
	ds_read_b128 v[156:159], v148 offset:1024
	ds_read_b128 v[160:163], v148 offset:2048
	ds_read_b128 v[164:167], v148 offset:3072
	ds_read_b128 v[168:171], v149
	ds_read_b128 v[172:175], v149 offset:1024
	ds_read_b128 v[176:179], v149 offset:2048
	ds_read_b128 v[180:183], v149 offset:3072
	s_add_i32 s88, s30, 2
	s_add_u32 s89, s28, 0x80
	s_addc_u32 s31, s29, 0
	s_cmp_eq_u32 s81, s30
	s_cselect_b32 s30, s6, s89
	s_cselect_b32 s31, s7, s31
	s_cselect_b32 s91, s27, s87
	s_cselect_b32 s90, s26, s25
	v_lshl_add_u64 v[220:221], s[28:29], 0, v[140:141]
	s_add_i32 m0, s47, 0xc000
	ds_read_b128 v[184:187], v150
	ds_read_b128 v[188:191], v150 offset:1024
	ds_read_b128 v[196:199], v150 offset:2048
	ds_read_b128 v[200:203], v150 offset:3072
	ds_read_b128 v[204:207], v150 offset:4096
	ds_read_b128 v[208:211], v150 offset:5120
	ds_read_b128 v[212:215], v150 offset:6144
	ds_read_b128 v[216:219], v150 offset:7168
	global_load_lds_dwordx4 v[220:221], off
	v_lshl_add_u64 v[220:221], s[28:29], 0, v[142:143]
	s_add_i32 m0, s47, 0xe000
	s_nop 0
	global_load_lds_dwordx4 v[220:221], off
	s_waitcnt vmcnt(8)
	s_waitcnt lgkmcnt(0)
	s_barrier
	s_setprio 1
	v_mfma_f32_16x16x32_bf16 v[120:123], v[152:155], v[184:187], v[120:123]
	v_mfma_f32_16x16x32_bf16 v[124:127], v[160:163], v[184:187], v[124:127]
	v_mfma_f32_16x16x32_bf16 v[108:111], v[152:155], v[196:199], v[108:111]
	v_mfma_f32_16x16x32_bf16 v[104:107], v[160:163], v[196:199], v[104:107]
	v_mfma_f32_16x16x32_bf16 v[92:95], v[152:155], v[204:207], v[92:95]
	v_mfma_f32_16x16x32_bf16 v[88:91], v[160:163], v[204:207], v[88:91]
	v_mfma_f32_16x16x32_bf16 v[76:79], v[152:155], v[212:215], v[76:79]
	v_mfma_f32_16x16x32_bf16 v[72:75], v[160:163], v[212:215], v[72:75]
	v_mfma_f32_16x16x32_bf16 v[120:123], v[156:159], v[188:191], v[120:123]
	v_mfma_f32_16x16x32_bf16 v[124:127], v[164:167], v[188:191], v[124:127]
	v_mfma_f32_16x16x32_bf16 v[108:111], v[156:159], v[200:203], v[108:111]
	v_mfma_f32_16x16x32_bf16 v[104:107], v[164:167], v[200:203], v[104:107]
	v_mfma_f32_16x16x32_bf16 v[92:95], v[156:159], v[208:211], v[92:95]
	v_mfma_f32_16x16x32_bf16 v[88:91], v[164:167], v[208:211], v[88:91]
	v_mfma_f32_16x16x32_bf16 v[76:79], v[156:159], v[216:219], v[76:79]
	v_mfma_f32_16x16x32_bf16 v[72:75], v[164:167], v[216:219], v[72:75]
	s_setprio 0
	s_setprio 1
	v_mfma_f32_16x16x32_bf16 v[116:119], v[168:171], v[184:187], v[116:119]
	v_mfma_f32_16x16x32_bf16 v[112:115], v[176:179], v[184:187], v[112:115]
	v_mfma_f32_16x16x32_bf16 v[100:103], v[168:171], v[196:199], v[100:103]
	v_mfma_f32_16x16x32_bf16 v[96:99], v[176:179], v[196:199], v[96:99]
	v_mfma_f32_16x16x32_bf16 v[84:87], v[168:171], v[204:207], v[84:87]
	v_mfma_f32_16x16x32_bf16 v[80:83], v[176:179], v[204:207], v[80:83]
	v_mfma_f32_16x16x32_bf16 v[68:71], v[168:171], v[212:215], v[68:71]
	v_mfma_f32_16x16x32_bf16 v[64:67], v[176:179], v[212:215], v[64:67]
	v_mfma_f32_16x16x32_bf16 v[116:119], v[172:175], v[188:191], v[116:119]
	v_mfma_f32_16x16x32_bf16 v[112:115], v[180:183], v[188:191], v[112:115]
	v_mfma_f32_16x16x32_bf16 v[100:103], v[172:175], v[200:203], v[100:103]
	v_mfma_f32_16x16x32_bf16 v[96:99], v[180:183], v[200:203], v[96:99]
	v_mfma_f32_16x16x32_bf16 v[84:87], v[172:175], v[208:211], v[84:87]
	v_mfma_f32_16x16x32_bf16 v[80:83], v[180:183], v[208:211], v[80:83]
	v_mfma_f32_16x16x32_bf16 v[68:71], v[172:175], v[216:219], v[68:71]
	v_mfma_f32_16x16x32_bf16 v[64:67], v[180:183], v[216:219], v[64:67]
	s_setprio 0
	s_barrier
	s_add_i32 s89, s82, s36
	v_lshl_add_u64 v[220:221], s[90:91], 0, v[130:131]
	s_mov_b32 m0, s89
	ds_read_b128 v[184:187], v150 offset:16384
	ds_read_b128 v[188:191], v150 offset:17408
	ds_read_b128 v[196:199], v150 offset:18432
	ds_read_b128 v[200:203], v150 offset:19456
	ds_read_b128 v[204:207], v150 offset:20480
	ds_read_b128 v[208:211], v150 offset:21504
	ds_read_b128 v[212:215], v150 offset:22528
	ds_read_b128 v[216:219], v150 offset:23552
	global_load_lds_dwordx4 v[220:221], off
	s_add_i32 m0, s89, 0x2000
	v_lshl_add_u64 v[222:223], s[90:91], 0, v[134:135]
	s_add_u32 s90, s90, s8
	s_addc_u32 s91, s91, s9
	s_add_i32 s89, s83, s36
	global_load_lds_dwordx4 v[222:223], off
	v_lshl_add_u64 v[224:225], s[90:91], 0, v[130:131]
	s_mov_b32 m0, s89
	v_lshl_add_u64 v[226:227], s[90:91], 0, v[134:135]
	global_load_lds_dwordx4 v[224:225], off
	s_add_i32 m0, s89, 0x2000
	v_lshl_add_u64 v[228:229], s[30:31], 0, v[128:129]
	global_load_lds_dwordx4 v[226:227], off
	s_mov_b32 m0, s47
	v_lshl_add_u64 v[230:231], s[30:31], 0, v[132:133]
	global_load_lds_dwordx4 v[228:229], off
	s_mov_b32 m0, s66
	s_nop 0
	global_load_lds_dwordx4 v[230:231], off
	s_waitcnt vmcnt(8)
	s_waitcnt lgkmcnt(0)
	s_barrier
; #define PG8_STAGE(bufoff, gbase, voff) do { _Pragma("unroll") for (int _i = 0; _i < 2; ++_i) \
;         __builtin_amdgcn_global_load_lds((const unsigned*)((const char*)(gbase) + (voff)[_i]), (PG8_LAS unsigned*)(lds + (bufoff) + ldsw + _i * 8192), 16, 0, 0); } while (0)
; #define PG8_LDA(dst, b, h) do { _Pragma("unroll") for (int m = 0; m < 4; ++m) _Pragma("unroll") for (int k = 0; k < 2; ++k) dst[m][k] = *(const PG8_LAS bf16x8*)(lds + PG8_SA(b, h) + aoff + m * 2048 + k * 1024); } while (0)
; #define PG8_LDB(dst, b, h) do { _Pragma("unroll") for (int n = 0; n < 2; ++n) _Pragma("unroll") for (int k = 0; k < 2; ++k) dst[n][k] = *(const PG8_LAS bf16x8*)(lds + PG8_SB(b, h) + boff + n * 2048 + k * 1024); } while (0)
; #define PG8_MMA(ai, bj, At, Bt) do { __builtin_amdgcn_s_setprio(1); _Pragma("unroll") for (int m = 0; m < 4; ++m) _Pragma("unroll") for (int n = 0; n < 2; ++n) _Pragma("unroll") for (int k = 0; k < 2; ++k) \
;         acc[ai][bj][m][n] = __builtin_amdgcn_mfma_f32_16x16x32_bf16(Bt[n][k], At[m][k], acc[ai][bj][m][n], 0, 0, 0); __builtin_amdgcn_s_setprio(0); } while (0)
; #define PG8_WAIT_V(n) asm volatile("s_waitcnt vmcnt(" #n ")" ::: "memory")
; #define PG8_WAIT_L(n) asm volatile("s_waitcnt lgkmcnt(" #n ")" ::: "memory")
; #define PG8_BAR __builtin_amdgcn_s_barrier()
; #define PG8_SCHED __builtin_amdgcn_sched_barrier(0)
; template <class Epi, class Sched, bool ALIGN_EPI = false, bool SP2 = false>
; __device__ __forceinline__ void gemm_phase(PG8_LAS unsigned char* lds, const Gemm g, const Sched& S, const Epi& E) {
;     ...
;             PG8_WAIT_V(8); PG8_WAIT_L(0); PG8_BAR; PG8_MMA(1, 0, At, B0); PG8_MMA(1, 1, At, B1); PG8_BAR; PG8_SCHED;
;             PG8_LDB(B0, 1, 0); PG8_LDB(B1, 1, 1); PG8_SCHED; PG8_LDA(At, 1, 0); PG8_STAGE(PG8_SA(0, 1), a2 + hstep, voffA);
;             PG8_WAIT_V(8); PG8_WAIT_L(0); PG8_BAR; PG8_MMA(0, 0, At, B0); PG8_MMA(0, 1, At, B1); PG8_BAR; PG8_SCHED;
	s_setprio 1
	v_mfma_f32_16x16x32_bf16 v[60:63], v[152:155], v[184:187], v[60:63]
	v_mfma_f32_16x16x32_bf16 v[56:59], v[160:163], v[184:187], v[56:59]
	v_mfma_f32_16x16x32_bf16 v[44:47], v[152:155], v[196:199], v[44:47]
	v_mfma_f32_16x16x32_bf16 v[40:43], v[160:163], v[196:199], v[40:43]
	v_mfma_f32_16x16x32_bf16 v[28:31], v[152:155], v[204:207], v[28:31]
	v_mfma_f32_16x16x32_bf16 v[24:27], v[160:163], v[204:207], v[24:27]
	v_mfma_f32_16x16x32_bf16 v[12:15], v[152:155], v[212:215], v[12:15]
	v_mfma_f32_16x16x32_bf16 v[8:11], v[160:163], v[212:215], v[8:11]
	v_mfma_f32_16x16x32_bf16 v[60:63], v[156:159], v[188:191], v[60:63]
	v_mfma_f32_16x16x32_bf16 v[56:59], v[164:167], v[188:191], v[56:59]
	v_mfma_f32_16x16x32_bf16 v[44:47], v[156:159], v[200:203], v[44:47]
	v_mfma_f32_16x16x32_bf16 v[40:43], v[164:167], v[200:203], v[40:43]
	v_mfma_f32_16x16x32_bf16 v[28:31], v[156:159], v[208:211], v[28:31]
	v_mfma_f32_16x16x32_bf16 v[24:27], v[164:167], v[208:211], v[24:27]
	v_mfma_f32_16x16x32_bf16 v[12:15], v[156:159], v[216:219], v[12:15]
	v_mfma_f32_16x16x32_bf16 v[8:11], v[164:167], v[216:219], v[8:11]
	s_setprio 0
	s_setprio 1
	v_mfma_f32_16x16x32_bf16 v[52:55], v[168:171], v[184:187], v[52:55]
	v_mfma_f32_16x16x32_bf16 v[48:51], v[176:179], v[184:187], v[48:51]
	v_mfma_f32_16x16x32_bf16 v[36:39], v[168:171], v[196:199], v[36:39]
	v_mfma_f32_16x16x32_bf16 v[32:35], v[176:179], v[196:199], v[32:35]
	v_mfma_f32_16x16x32_bf16 v[20:23], v[168:171], v[204:207], v[20:23]
	v_mfma_f32_16x16x32_bf16 v[16:19], v[176:179], v[204:207], v[16:19]
	v_mfma_f32_16x16x32_bf16 v[4:7], v[168:171], v[212:215], v[4:7]
	v_mfma_f32_16x16x32_bf16 v[0:3], v[176:179], v[212:215], v[0:3]
	v_mfma_f32_16x16x32_bf16 v[52:55], v[172:175], v[188:191], v[52:55]
	v_mfma_f32_16x16x32_bf16 v[48:51], v[180:183], v[188:191], v[48:51]
	v_mfma_f32_16x16x32_bf16 v[36:39], v[172:175], v[200:203], v[36:39]
	v_mfma_f32_16x16x32_bf16 v[32:35], v[180:183], v[200:203], v[32:35]
	v_mfma_f32_16x16x32_bf16 v[20:23], v[172:175], v[208:211], v[20:23]
	v_mfma_f32_16x16x32_bf16 v[16:19], v[180:183], v[208:211], v[16:19]
	v_mfma_f32_16x16x32_bf16 v[4:7], v[172:175], v[216:219], v[4:7]
	v_mfma_f32_16x16x32_bf16 v[0:3], v[180:183], v[216:219], v[0:3]
	s_setprio 0
	s_barrier
	s_add_i32 s89, 0, 0x18000
	v_add_u32_e32 v136, s89, v146
	s_add_i32 s90, 0, 0x1c000
	ds_read_b128 v[152:155], v136
	ds_read_b128 v[156:159], v136 offset:1024
	ds_read_b128 v[160:163], v136 offset:2048
	ds_read_b128 v[164:167], v136 offset:3072
	v_add_u32_e32 v136, s90, v146
	ds_read_b128 v[168:171], v136
	ds_read_b128 v[172:175], v136 offset:1024
	ds_read_b128 v[176:179], v136 offset:2048
	ds_read_b128 v[180:183], v136 offset:3072
	s_add_u32 s30, s30, s8
	s_addc_u32 s31, s31, s9
	s_mov_b32 m0, s67
	v_lshl_add_u64 v[232:233], s[30:31], 0, v[128:129]
	ds_read_b128 v[184:187], v150 offset:32768
	ds_read_b128 v[188:191], v150 offset:33792
	ds_read_b128 v[196:199], v150 offset:34816
	ds_read_b128 v[200:203], v150 offset:35840
	ds_read_b128 v[204:207], v150 offset:36864
	ds_read_b128 v[208:211], v150 offset:37888
	ds_read_b128 v[212:215], v150 offset:38912
	ds_read_b128 v[216:219], v150 offset:39936
	global_load_lds_dwordx4 v[232:233], off
	v_lshl_add_u64 v[232:233], s[30:31], 0, v[132:133]
	s_mov_b32 m0, s70
	s_nop 0
	global_load_lds_dwordx4 v[232:233], off
	s_waitcnt vmcnt(8)
	s_waitcnt lgkmcnt(0)
	s_barrier
	s_setprio 1
	v_mfma_f32_16x16x32_bf16 v[120:123], v[152:155], v[184:187], v[120:123]
	v_mfma_f32_16x16x32_bf16 v[124:127], v[160:163], v[184:187], v[124:127]
	v_mfma_f32_16x16x32_bf16 v[108:111], v[152:155], v[196:199], v[108:111]
	v_mfma_f32_16x16x32_bf16 v[104:107], v[160:163], v[196:199], v[104:107]
	v_mfma_f32_16x16x32_bf16 v[92:95], v[152:155], v[204:207], v[92:95]
	v_mfma_f32_16x16x32_bf16 v[88:91], v[160:163], v[204:207], v[88:91]
	v_mfma_f32_16x16x32_bf16 v[76:79], v[152:155], v[212:215], v[76:79]
	v_mfma_f32_16x16x32_bf16 v[72:75], v[160:163], v[212:215], v[72:75]
	v_mfma_f32_16x16x32_bf16 v[120:123], v[156:159], v[188:191], v[120:123]
	v_mfma_f32_16x16x32_bf16 v[124:127], v[164:167], v[188:191], v[124:127]
	v_mfma_f32_16x16x32_bf16 v[108:111], v[156:159], v[200:203], v[108:111]
	v_mfma_f32_16x16x32_bf16 v[104:107], v[164:167], v[200:203], v[104:107]
	v_mfma_f32_16x16x32_bf16 v[92:95], v[156:159], v[208:211], v[92:95]
	v_mfma_f32_16x16x32_bf16 v[88:91], v[164:167], v[208:211], v[88:91]
	v_mfma_f32_16x16x32_bf16 v[76:79], v[156:159], v[216:219], v[76:79]
	v_mfma_f32_16x16x32_bf16 v[72:75], v[164:167], v[216:219], v[72:75]
	s_setprio 0
	s_setprio 1
	v_mfma_f32_16x16x32_bf16 v[116:119], v[168:171], v[184:187], v[116:119]
	v_mfma_f32_16x16x32_bf16 v[112:115], v[176:179], v[184:187], v[112:115]
	v_mfma_f32_16x16x32_bf16 v[100:103], v[168:171], v[196:199], v[100:103]
	v_mfma_f32_16x16x32_bf16 v[96:99], v[176:179], v[196:199], v[96:99]
	v_mfma_f32_16x16x32_bf16 v[84:87], v[168:171], v[204:207], v[84:87]
	v_mfma_f32_16x16x32_bf16 v[80:83], v[176:179], v[204:207], v[80:83]
	v_mfma_f32_16x16x32_bf16 v[68:71], v[168:171], v[212:215], v[68:71]
	v_mfma_f32_16x16x32_bf16 v[64:67], v[176:179], v[212:215], v[64:67]
	v_mfma_f32_16x16x32_bf16 v[116:119], v[172:175], v[188:191], v[116:119]
	v_mfma_f32_16x16x32_bf16 v[112:115], v[180:183], v[188:191], v[112:115]
	v_mfma_f32_16x16x32_bf16 v[100:103], v[172:175], v[200:203], v[100:103]
	v_mfma_f32_16x16x32_bf16 v[96:99], v[180:183], v[200:203], v[96:99]
	v_mfma_f32_16x16x32_bf16 v[84:87], v[172:175], v[208:211], v[84:87]
	v_mfma_f32_16x16x32_bf16 v[80:83], v[180:183], v[208:211], v[80:83]
	v_mfma_f32_16x16x32_bf16 v[68:71], v[172:175], v[216:219], v[68:71]
	v_mfma_f32_16x16x32_bf16 v[64:67], v[180:183], v[216:219], v[64:67]
	s_setprio 0
	s_barrier
; #define PG8_STAGE(bufoff, gbase, voff) do { _Pragma("unroll") for (int _i = 0; _i < 2; ++_i) \
;         __builtin_amdgcn_global_load_lds((const unsigned*)((const char*)(gbase) + (voff)[_i]), (PG8_LAS unsigned*)(lds + (bufoff) + ldsw + _i * 8192), 16, 0, 0); } while (0)
; #define PG8_LDA(dst, b, h) do { _Pragma("unroll") for (int m = 0; m < 4; ++m) _Pragma("unroll") for (int k = 0; k < 2; ++k) dst[m][k] = *(const PG8_LAS bf16x8*)(lds + PG8_SA(b, h) + aoff + m * 2048 + k * 1024); } while (0)
; #define PG8_MMA(ai, bj, At, Bt) do { __builtin_amdgcn_s_setprio(1); _Pragma("unroll") for (int m = 0; m < 4; ++m) _Pragma("unroll") for (int n = 0; n < 2; ++n) _Pragma("unroll") for (int k = 0; k < 2; ++k) \
;         acc[ai][bj][m][n] = __builtin_amdgcn_mfma_f32_16x16x32_bf16(Bt[n][k], At[m][k], acc[ai][bj][m][n], 0, 0, 0); __builtin_amdgcn_s_setprio(0); } while (0)
; #define PG8_WAIT_V(n) asm volatile("s_waitcnt vmcnt(" #n ")" ::: "memory")
; #define PG8_WAIT_L(n) asm volatile("s_waitcnt lgkmcnt(" #n ")" ::: "memory")
; #define PG8_BAR __builtin_amdgcn_s_barrier()
; #define PG8_SCHED __builtin_amdgcn_sched_barrier(0)
; template <class Epi, class Sched, bool ALIGN_EPI = false, bool SP2 = false>
; __device__ __forceinline__ void gemm_phase(PG8_LAS unsigned char* lds, const Gemm g, const Sched& S, const Epi& E) {
;     ...
;         for (int t = 0; t < nt; t += 2) {
;             const bool last = (t == nt - 2);
;             const char* a1 = cA + (size_t)(t + 1) * kstep;
;             const char* a2 = last ? nA : cA + (size_t)(t + 2) * kstep; const char* b2 = last ? nB : cB + (size_t)(t + 2) * kstep;
;     ...
;             PG8_LDA(At, 1, 1); PG8_STAGE(PG8_SB(1, 0), b3, voffB); PG8_STAGE(PG8_SB(1, 1), b3 + hstep, voffB); PG8_STAGE(PG8_SA(1, 0), a3, voffA);
;             PG8_WAIT_V(8); PG8_WAIT_L(0); PG8_BAR; PG8_MMA(1, 0, At, B0); PG8_MMA(1, 1, At, B1); PG8_BAR; PG8_SCHED;
	s_add_i32 s30, s89, s36
	v_lshl_add_u64 v[220:221], v[220:221], 0, s[14:15]
	s_mov_b32 m0, s30
	ds_read_b128 v[184:187], v150 offset:49152
	ds_read_b128 v[188:191], v150 offset:50176
	ds_read_b128 v[196:199], v150 offset:51200
	ds_read_b128 v[200:203], v150 offset:52224
	ds_read_b128 v[204:207], v150 offset:53248
	ds_read_b128 v[208:211], v150 offset:54272
	ds_read_b128 v[212:215], v150 offset:55296
	ds_read_b128 v[216:219], v150 offset:56320
	global_load_lds_dwordx4 v[220:221], off
	v_lshl_add_u64 v[220:221], v[222:223], 0, s[14:15]
	s_add_i32 m0, s30, 0x2000
	s_add_i32 s30, s90, s36
	global_load_lds_dwordx4 v[220:221], off
	v_lshl_add_u64 v[220:221], v[224:225], 0, s[14:15]
	s_mov_b32 m0, s30
	s_nop 0
	global_load_lds_dwordx4 v[220:221], off
	v_lshl_add_u64 v[220:221], v[226:227], 0, s[14:15]
	s_add_i32 m0, s30, 0x2000
	s_nop 0
	global_load_lds_dwordx4 v[220:221], off
	v_lshl_add_u64 v[220:221], v[228:229], 0, s[14:15]
	s_mov_b32 m0, s78
	s_nop 0
	global_load_lds_dwordx4 v[220:221], off
	v_lshl_add_u64 v[220:221], v[230:231], 0, s[14:15]
	s_mov_b32 m0, s79
	s_nop 0
	global_load_lds_dwordx4 v[220:221], off
	s_waitcnt vmcnt(8)
	s_waitcnt lgkmcnt(0)
	s_barrier
	s_setprio 1
	v_mfma_f32_16x16x32_bf16 v[60:63], v[152:155], v[184:187], v[60:63]
	v_mfma_f32_16x16x32_bf16 v[56:59], v[160:163], v[184:187], v[56:59]
	v_mfma_f32_16x16x32_bf16 v[44:47], v[152:155], v[196:199], v[44:47]
	v_mfma_f32_16x16x32_bf16 v[40:43], v[160:163], v[196:199], v[40:43]
	v_mfma_f32_16x16x32_bf16 v[28:31], v[152:155], v[204:207], v[28:31]
	v_mfma_f32_16x16x32_bf16 v[24:27], v[160:163], v[204:207], v[24:27]
	v_mfma_f32_16x16x32_bf16 v[12:15], v[152:155], v[212:215], v[12:15]
	v_mfma_f32_16x16x32_bf16 v[8:11], v[160:163], v[212:215], v[8:11]
	v_mfma_f32_16x16x32_bf16 v[60:63], v[156:159], v[188:191], v[60:63]
	v_mfma_f32_16x16x32_bf16 v[56:59], v[164:167], v[188:191], v[56:59]
	v_mfma_f32_16x16x32_bf16 v[44:47], v[156:159], v[200:203], v[44:47]
	v_mfma_f32_16x16x32_bf16 v[40:43], v[164:167], v[200:203], v[40:43]
	v_mfma_f32_16x16x32_bf16 v[28:31], v[156:159], v[208:211], v[28:31]
	v_mfma_f32_16x16x32_bf16 v[24:27], v[164:167], v[208:211], v[24:27]
	v_mfma_f32_16x16x32_bf16 v[12:15], v[156:159], v[216:219], v[12:15]
	v_mfma_f32_16x16x32_bf16 v[8:11], v[164:167], v[216:219], v[8:11]
	s_setprio 0
	s_setprio 1
	v_mfma_f32_16x16x32_bf16 v[52:55], v[168:171], v[184:187], v[52:55]
	v_mfma_f32_16x16x32_bf16 v[48:51], v[176:179], v[184:187], v[48:51]
	v_mfma_f32_16x16x32_bf16 v[36:39], v[168:171], v[196:199], v[36:39]
	v_mfma_f32_16x16x32_bf16 v[32:35], v[176:179], v[196:199], v[32:35]
	v_mfma_f32_16x16x32_bf16 v[20:23], v[168:171], v[204:207], v[20:23]
	v_mfma_f32_16x16x32_bf16 v[16:19], v[176:179], v[204:207], v[16:19]
	v_mfma_f32_16x16x32_bf16 v[4:7], v[168:171], v[212:215], v[4:7]
	v_mfma_f32_16x16x32_bf16 v[0:3], v[176:179], v[212:215], v[0:3]
	v_mfma_f32_16x16x32_bf16 v[52:55], v[172:175], v[188:191], v[52:55]
	v_mfma_f32_16x16x32_bf16 v[48:51], v[180:183], v[188:191], v[48:51]
	v_mfma_f32_16x16x32_bf16 v[36:39], v[172:175], v[200:203], v[36:39]
	v_mfma_f32_16x16x32_bf16 v[32:35], v[180:183], v[200:203], v[32:35]
	v_mfma_f32_16x16x32_bf16 v[20:23], v[172:175], v[208:211], v[20:23]
	v_mfma_f32_16x16x32_bf16 v[16:19], v[180:183], v[208:211], v[16:19]
	v_mfma_f32_16x16x32_bf16 v[4:7], v[172:175], v[216:219], v[4:7]
	v_mfma_f32_16x16x32_bf16 v[0:3], v[180:183], v[216:219], v[0:3]
	s_setprio 0
	s_barrier
	s_add_u32 s28, s28, 0x100
	s_addc_u32 s29, s29, 0
	s_add_u32 s25, s25, 0x100
	s_addc_u32 s87, s87, 0
	s_cmp_ge_i32 s88, s80
	s_mov_b32 s30, s88
	s_cbranch_scc0 .LBB0_1989
